# rms phases: non-temporal (nt) hint on the x row loads
# speedup vs baseline: 1.0146x; 1.0066x over previous
.LBB0_8:
	s_mov_b32 s15, s2
	s_mov_b64 s[6:7], -1
	s_mov_b64 s[0:1], 0
	s_cmp_lt_i32 s2, 19
	s_mov_b64 s[4:5], 0
	s_cbranch_scc1 .LBB0_17
	s_cmp_eq_u32 s15, 19
	s_mov_b64 s[4:5], -1
	s_cbranch_scc0 .LBB0_16
	v_mov_b32_e32 v0, 0xe0
	v_mov_b32_e32 v2, 0xd8
	v_add_u32_e32 v0, s91, v0
	ds_read_b64 v[0:1], v0
	v_mov_b32_e32 v4, 0xe0
	v_add_u32_e32 v2, s91, v2
	ds_read_b64 v[2:3], v2
	s_waitcnt lgkmcnt(0)
	v_readfirstlane_b32 s9, v1
	v_add_u32_e32 v4, s91, v4
	ds_read_b64 v[4:5], v4
	v_readfirstlane_b32 s8, v0
	v_mbcnt_lo_u32_b32 v0, -1, 0
	v_mbcnt_hi_u32_b32 v0, -1, v0
	v_readlane_b32 s2, v253, 11
	v_add_u32_e32 v1, s57, v0
	v_ashrrev_i32_e32 v1, 6, v1
	v_add_u32_e32 v52, s2, v1
	s_waitcnt lgkmcnt(1)
	v_readfirstlane_b32 s11, v3
	v_readfirstlane_b32 s10, v2
	s_waitcnt lgkmcnt(0)
	v_readfirstlane_b32 s7, v5
	v_readfirstlane_b32 s6, v4
	v_cmp_gt_i32_e32 vcc, s3, v52
	s_and_saveexec_b64 s[4:5], vcc
	s_cbranch_execz .LBB0_15
	v_readfirstlane_b32 s100, v52
	s_nop 3
	v_lshlrev_b32_e32 v120, 4, v0
	v_lshlrev_b32_e32 v121, 3, v0
	v_lshlrev_b32_e32 v122, 2, v214
	v_lshlrev_b32_e32 v123, 2, v215
	v_lshlrev_b32_e32 v124, 2, v216
	v_lshlrev_b32_e32 v125, 2, v217
	v_lshlrev_b32_e32 v126, 2, v218
	v_lshlrev_b32_e32 v127, 2, v219
	s_lshr_b32 s2, s100, 6
	s_lshl_b32 s2, s2, 11
	s_and_b32 s101, s100, 63
	s_add_u32 s2, s2, s101
	s_lshl_b32 s101, s2, 12
	s_add_u32 s8, s8, s101
	s_addc_u32 s9, s9, 0
	s_add_u32 s6, s6, s101
	s_addc_u32 s7, s7, 0
	global_load_dwordx4 v[0:3], v120, s[10:11] offset:0
	global_load_dwordx4 v[4:7], v120, s[10:11] offset:1024
	global_load_dwordx4 v[8:11], v120, s[10:11] offset:2048
	global_load_dwordx4 v[12:15], v120, s[10:11] offset:3072
	s_movk_i32 s2, 3
	global_load_dwordx4 v[48:51], v120, s[8:9] offset:0 nt
	global_load_dwordx4 v[52:55], v120, s[8:9] offset:1024 nt
	global_load_dwordx4 v[56:59], v120, s[8:9] offset:2048 nt
	global_load_dwordx4 v[60:63], v120, s[8:9] offset:3072 nt
	s_add_u32 s8, s8, 0x40000
	s_addc_u32 s9, s9, 0
	global_load_dwordx4 v[64:67], v120, s[8:9] offset:0 nt
	global_load_dwordx4 v[68:71], v120, s[8:9] offset:1024 nt
	global_load_dwordx4 v[72:75], v120, s[8:9] offset:2048 nt
	global_load_dwordx4 v[76:79], v120, s[8:9] offset:3072 nt
	s_add_u32 s8, s8, 0x40000
	s_addc_u32 s9, s9, 0
	global_load_dwordx4 v[80:83], v120, s[8:9] offset:0 nt
	global_load_dwordx4 v[84:87], v120, s[8:9] offset:1024 nt
	global_load_dwordx4 v[88:91], v120, s[8:9] offset:2048 nt
	global_load_dwordx4 v[92:95], v120, s[8:9] offset:3072 nt
	s_add_u32 s8, s8, 0x40000
	s_addc_u32 s9, s9, 0
	global_load_dwordx4 v[96:99], v120, s[8:9] offset:0 nt
	global_load_dwordx4 v[100:103], v120, s[8:9] offset:1024 nt
	global_load_dwordx4 v[104:107], v120, s[8:9] offset:2048 nt
	global_load_dwordx4 v[108:111], v120, s[8:9] offset:3072 nt
	s_add_u32 s8, s8, 0x40000
	s_addc_u32 s9, s9, 0
	global_load_dwordx4 v[132:135], v120, s[8:9] offset:0 nt
	global_load_dwordx4 v[136:139], v120, s[8:9] offset:1024 nt
	global_load_dwordx4 v[140:143], v120, s[8:9] offset:2048 nt
	global_load_dwordx4 v[144:147], v120, s[8:9] offset:3072 nt
	s_add_u32 s8, s8, 0x40000
	s_addc_u32 s9, s9, 0
	global_load_dwordx4 v[166:169], v120, s[8:9] offset:0 nt
	global_load_dwordx4 v[170:173], v120, s[8:9] offset:1024 nt
	global_load_dwordx4 v[174:177], v120, s[8:9] offset:2048 nt
	global_load_dwordx4 v[178:181], v120, s[8:9] offset:3072 nt
	s_add_u32 s8, s8, 0x40000
	s_addc_u32 s9, s9, 0
	global_load_dwordx4 v[182:185], v120, s[8:9] offset:0 nt
	global_load_dwordx4 v[186:189], v120, s[8:9] offset:1024 nt
	global_load_dwordx4 v[190:193], v120, s[8:9] offset:2048 nt
	global_load_dwordx4 v[194:197], v120, s[8:9] offset:3072 nt
	s_add_u32 s8, s8, 0x40000
	s_addc_u32 s9, s9, 0
	global_load_dwordx4 v[228:231], v120, s[8:9] offset:0 nt
	global_load_dwordx4 v[232:235], v120, s[8:9] offset:1024 nt
	global_load_dwordx4 v[236:239], v120, s[8:9] offset:2048 nt
	global_load_dwordx4 v[240:243], v120, s[8:9] offset:3072 nt
	s_add_u32 s8, s8, 0x40000
	s_addc_u32 s9, s9, 0
	s_waitcnt vmcnt(28)
	v_mul_f32_e32 v112, v48, v48
	v_fmac_f32_e32 v112, v49, v49
	v_fmac_f32_e32 v112, v50, v50
	v_fmac_f32_e32 v112, v51, v51
	v_fmac_f32_e32 v112, v52, v52
	v_fmac_f32_e32 v112, v53, v53
	v_fmac_f32_e32 v112, v54, v54
	v_fmac_f32_e32 v112, v55, v55
	v_fmac_f32_e32 v112, v56, v56
	v_fmac_f32_e32 v112, v57, v57
	v_fmac_f32_e32 v112, v58, v58
	v_fmac_f32_e32 v112, v59, v59
	v_fmac_f32_e32 v112, v60, v60
	v_fmac_f32_e32 v112, v61, v61
	v_fmac_f32_e32 v112, v62, v62
	v_fmac_f32_e32 v112, v63, v63
	s_waitcnt vmcnt(24)
	v_mul_f32_e32 v113, v64, v64
	v_fmac_f32_e32 v113, v65, v65
	v_fmac_f32_e32 v113, v66, v66
	v_fmac_f32_e32 v113, v67, v67
	v_fmac_f32_e32 v113, v68, v68
	v_fmac_f32_e32 v113, v69, v69
	v_fmac_f32_e32 v113, v70, v70
	v_fmac_f32_e32 v113, v71, v71
	v_fmac_f32_e32 v113, v72, v72
	v_fmac_f32_e32 v113, v73, v73
	v_fmac_f32_e32 v113, v74, v74
	v_fmac_f32_e32 v113, v75, v75
	v_fmac_f32_e32 v113, v76, v76
	v_fmac_f32_e32 v113, v77, v77
	v_fmac_f32_e32 v113, v78, v78
	v_fmac_f32_e32 v113, v79, v79
	s_waitcnt vmcnt(20)
	v_mul_f32_e32 v114, v80, v80
	v_fmac_f32_e32 v114, v81, v81
	v_fmac_f32_e32 v114, v82, v82
	v_fmac_f32_e32 v114, v83, v83
	v_fmac_f32_e32 v114, v84, v84
	v_fmac_f32_e32 v114, v85, v85
	v_fmac_f32_e32 v114, v86, v86
	v_fmac_f32_e32 v114, v87, v87
	v_fmac_f32_e32 v114, v88, v88
	v_fmac_f32_e32 v114, v89, v89
	v_fmac_f32_e32 v114, v90, v90
	v_fmac_f32_e32 v114, v91, v91
	v_fmac_f32_e32 v114, v92, v92
	v_fmac_f32_e32 v114, v93, v93
	v_fmac_f32_e32 v114, v94, v94
	v_fmac_f32_e32 v114, v95, v95
	s_waitcnt vmcnt(16)
	v_mul_f32_e32 v115, v96, v96
	v_fmac_f32_e32 v115, v97, v97
	v_fmac_f32_e32 v115, v98, v98
	v_fmac_f32_e32 v115, v99, v99
	v_fmac_f32_e32 v115, v100, v100
	v_fmac_f32_e32 v115, v101, v101
	v_fmac_f32_e32 v115, v102, v102
	v_fmac_f32_e32 v115, v103, v103
	v_fmac_f32_e32 v115, v104, v104
	v_fmac_f32_e32 v115, v105, v105
	v_fmac_f32_e32 v115, v106, v106
	v_fmac_f32_e32 v115, v107, v107
	v_fmac_f32_e32 v115, v108, v108
	v_fmac_f32_e32 v115, v109, v109
	v_fmac_f32_e32 v115, v110, v110
	v_fmac_f32_e32 v115, v111, v111
	ds_bpermute_b32 v116, v122, v112
	ds_bpermute_b32 v117, v122, v113
	ds_bpermute_b32 v118, v122, v114
	ds_bpermute_b32 v119, v122, v115
	s_waitcnt lgkmcnt(0)
	v_add_f32_e32 v112, v112, v116
	v_add_f32_e32 v113, v113, v117
	v_add_f32_e32 v114, v114, v118
	v_add_f32_e32 v115, v115, v119
	ds_bpermute_b32 v116, v123, v112
	ds_bpermute_b32 v117, v123, v113
	ds_bpermute_b32 v118, v123, v114
	ds_bpermute_b32 v119, v123, v115
	s_waitcnt lgkmcnt(0)
	v_add_f32_e32 v112, v112, v116
	v_add_f32_e32 v113, v113, v117
	v_add_f32_e32 v114, v114, v118
	v_add_f32_e32 v115, v115, v119
	ds_bpermute_b32 v116, v124, v112
	ds_bpermute_b32 v117, v124, v113
	ds_bpermute_b32 v118, v124, v114
	ds_bpermute_b32 v119, v124, v115
	s_waitcnt lgkmcnt(0)
	v_add_f32_e32 v112, v112, v116
	v_add_f32_e32 v113, v113, v117
	v_add_f32_e32 v114, v114, v118
	v_add_f32_e32 v115, v115, v119
	ds_bpermute_b32 v116, v125, v112
	ds_bpermute_b32 v117, v125, v113
	ds_bpermute_b32 v118, v125, v114
	ds_bpermute_b32 v119, v125, v115
	s_waitcnt lgkmcnt(0)
	v_add_f32_e32 v112, v112, v116
	v_add_f32_e32 v113, v113, v117
	v_add_f32_e32 v114, v114, v118
	v_add_f32_e32 v115, v115, v119
	ds_bpermute_b32 v116, v126, v112
	ds_bpermute_b32 v117, v126, v113
	ds_bpermute_b32 v118, v126, v114
	ds_bpermute_b32 v119, v126, v115
	s_waitcnt lgkmcnt(0)
	v_add_f32_e32 v112, v112, v116
	v_add_f32_e32 v113, v113, v117
	v_add_f32_e32 v114, v114, v118
	v_add_f32_e32 v115, v115, v119
	ds_bpermute_b32 v116, v127, v112
	ds_bpermute_b32 v117, v127, v113
	ds_bpermute_b32 v118, v127, v114
	ds_bpermute_b32 v119, v127, v115
	s_waitcnt lgkmcnt(0)
	v_add_f32_e32 v112, v112, v116
	v_add_f32_e32 v113, v113, v117
	v_add_f32_e32 v114, v114, v118
	v_add_f32_e32 v115, v115, v119
	v_fmamk_f32 v112, v112, 0x3a800000, v208
	v_fmamk_f32 v113, v113, 0x3a800000, v208
	v_fmamk_f32 v114, v114, 0x3a800000, v208
	v_fmamk_f32 v115, v115, 0x3a800000, v208
	v_rsq_f32_e32 v112, v112
	v_rsq_f32_e32 v113, v113
	v_rsq_f32_e32 v114, v114
	v_rsq_f32_e32 v115, v115
	s_nop 1
	v_mul_f32_e32 v48, v48, v112
	v_mul_f32_e32 v49, v49, v112
	v_mul_f32_e32 v50, v50, v112
	v_mul_f32_e32 v51, v51, v112
	v_mul_f32_e32 v48, v0, v48
	v_mul_f32_e32 v49, v1, v49
	v_mul_f32_e32 v50, v2, v50
	v_mul_f32_e32 v51, v3, v51
	global_store_dwordx4 v120, v[48:51], s[6:7] offset:0
	v_mul_f32_e32 v52, v52, v112
	v_mul_f32_e32 v53, v53, v112
	v_mul_f32_e32 v54, v54, v112
	v_mul_f32_e32 v55, v55, v112
	v_mul_f32_e32 v52, v4, v52
	v_mul_f32_e32 v53, v5, v53
	v_mul_f32_e32 v54, v6, v54
	v_mul_f32_e32 v55, v7, v55
	global_store_dwordx4 v120, v[52:55], s[6:7] offset:1024
	v_mul_f32_e32 v56, v56, v112
	v_mul_f32_e32 v57, v57, v112
	v_mul_f32_e32 v58, v58, v112
	v_mul_f32_e32 v59, v59, v112
	v_mul_f32_e32 v56, v8, v56
	v_mul_f32_e32 v57, v9, v57
	v_mul_f32_e32 v58, v10, v58
	v_mul_f32_e32 v59, v11, v59
	global_store_dwordx4 v120, v[56:59], s[6:7] offset:2048
	v_mul_f32_e32 v60, v60, v112
	v_mul_f32_e32 v61, v61, v112
	v_mul_f32_e32 v62, v62, v112
	v_mul_f32_e32 v63, v63, v112
	v_mul_f32_e32 v60, v12, v60
	v_mul_f32_e32 v61, v13, v61
	v_mul_f32_e32 v62, v14, v62
	v_mul_f32_e32 v63, v15, v63
	global_store_dwordx4 v120, v[60:63], s[6:7] offset:3072
	s_add_u32 s6, s6, 0x40000
	s_addc_u32 s7, s7, 0
	v_mul_f32_e32 v64, v64, v113
	v_mul_f32_e32 v65, v65, v113
	v_mul_f32_e32 v66, v66, v113
	v_mul_f32_e32 v67, v67, v113
	v_mul_f32_e32 v64, v0, v64
	v_mul_f32_e32 v65, v1, v65
	v_mul_f32_e32 v66, v2, v66
	v_mul_f32_e32 v67, v3, v67
	global_store_dwordx4 v120, v[64:67], s[6:7] offset:0
	v_mul_f32_e32 v68, v68, v113
	v_mul_f32_e32 v69, v69, v113
	v_mul_f32_e32 v70, v70, v113
	v_mul_f32_e32 v71, v71, v113
	v_mul_f32_e32 v68, v4, v68
	v_mul_f32_e32 v69, v5, v69
	v_mul_f32_e32 v70, v6, v70
	v_mul_f32_e32 v71, v7, v71
	global_store_dwordx4 v120, v[68:71], s[6:7] offset:1024
	v_mul_f32_e32 v72, v72, v113
	v_mul_f32_e32 v73, v73, v113
	v_mul_f32_e32 v74, v74, v113
	v_mul_f32_e32 v75, v75, v113
	v_mul_f32_e32 v72, v8, v72
	v_mul_f32_e32 v73, v9, v73
	v_mul_f32_e32 v74, v10, v74
	v_mul_f32_e32 v75, v11, v75
	global_store_dwordx4 v120, v[72:75], s[6:7] offset:2048
	v_mul_f32_e32 v76, v76, v113
	v_mul_f32_e32 v77, v77, v113
	v_mul_f32_e32 v78, v78, v113
	v_mul_f32_e32 v79, v79, v113
	v_mul_f32_e32 v76, v12, v76
	v_mul_f32_e32 v77, v13, v77
	v_mul_f32_e32 v78, v14, v78
	v_mul_f32_e32 v79, v15, v79
	global_store_dwordx4 v120, v[76:79], s[6:7] offset:3072
	s_add_u32 s6, s6, 0x40000
	s_addc_u32 s7, s7, 0
	v_mul_f32_e32 v80, v80, v114
	v_mul_f32_e32 v81, v81, v114
	v_mul_f32_e32 v82, v82, v114
	v_mul_f32_e32 v83, v83, v114
	v_mul_f32_e32 v80, v0, v80
	v_mul_f32_e32 v81, v1, v81
	v_mul_f32_e32 v82, v2, v82
	v_mul_f32_e32 v83, v3, v83
	global_store_dwordx4 v120, v[80:83], s[6:7] offset:0
	v_mul_f32_e32 v84, v84, v114
	v_mul_f32_e32 v85, v85, v114
	v_mul_f32_e32 v86, v86, v114
	v_mul_f32_e32 v87, v87, v114
	v_mul_f32_e32 v84, v4, v84
	v_mul_f32_e32 v85, v5, v85
	v_mul_f32_e32 v86, v6, v86
	v_mul_f32_e32 v87, v7, v87
	global_store_dwordx4 v120, v[84:87], s[6:7] offset:1024
	v_mul_f32_e32 v88, v88, v114
	v_mul_f32_e32 v89, v89, v114
	v_mul_f32_e32 v90, v90, v114
	v_mul_f32_e32 v91, v91, v114
	v_mul_f32_e32 v88, v8, v88
	v_mul_f32_e32 v89, v9, v89
	v_mul_f32_e32 v90, v10, v90
	v_mul_f32_e32 v91, v11, v91
	global_store_dwordx4 v120, v[88:91], s[6:7] offset:2048
	v_mul_f32_e32 v92, v92, v114
	v_mul_f32_e32 v93, v93, v114
	v_mul_f32_e32 v94, v94, v114
	v_mul_f32_e32 v95, v95, v114
	v_mul_f32_e32 v92, v12, v92
	v_mul_f32_e32 v93, v13, v93
	v_mul_f32_e32 v94, v14, v94
	v_mul_f32_e32 v95, v15, v95
	global_store_dwordx4 v120, v[92:95], s[6:7] offset:3072
	s_add_u32 s6, s6, 0x40000
	s_addc_u32 s7, s7, 0
	v_mul_f32_e32 v96, v96, v115
	v_mul_f32_e32 v97, v97, v115
	v_mul_f32_e32 v98, v98, v115
	v_mul_f32_e32 v99, v99, v115
	v_mul_f32_e32 v96, v0, v96
	v_mul_f32_e32 v97, v1, v97
	v_mul_f32_e32 v98, v2, v98
	v_mul_f32_e32 v99, v3, v99
	global_store_dwordx4 v120, v[96:99], s[6:7] offset:0
	v_mul_f32_e32 v100, v100, v115
	v_mul_f32_e32 v101, v101, v115
	v_mul_f32_e32 v102, v102, v115
	v_mul_f32_e32 v103, v103, v115
	v_mul_f32_e32 v100, v4, v100
	v_mul_f32_e32 v101, v5, v101
	v_mul_f32_e32 v102, v6, v102
	v_mul_f32_e32 v103, v7, v103
	global_store_dwordx4 v120, v[100:103], s[6:7] offset:1024
	v_mul_f32_e32 v104, v104, v115
	v_mul_f32_e32 v105, v105, v115
	v_mul_f32_e32 v106, v106, v115
	v_mul_f32_e32 v107, v107, v115
	v_mul_f32_e32 v104, v8, v104
	v_mul_f32_e32 v105, v9, v105
	v_mul_f32_e32 v106, v10, v106
	v_mul_f32_e32 v107, v11, v107
	global_store_dwordx4 v120, v[104:107], s[6:7] offset:2048
	v_mul_f32_e32 v108, v108, v115
	v_mul_f32_e32 v109, v109, v115
	v_mul_f32_e32 v110, v110, v115
	v_mul_f32_e32 v111, v111, v115
	v_mul_f32_e32 v108, v12, v108
	v_mul_f32_e32 v109, v13, v109
	v_mul_f32_e32 v110, v14, v110
	v_mul_f32_e32 v111, v15, v111
	global_store_dwordx4 v120, v[108:111], s[6:7] offset:3072
	s_add_u32 s6, s6, 0x40000
	s_addc_u32 s7, s7, 0
.Lrms_final_loop:
	global_load_dwordx4 v[48:51], v120, s[8:9] offset:0 nt
	global_load_dwordx4 v[52:55], v120, s[8:9] offset:1024 nt
	global_load_dwordx4 v[56:59], v120, s[8:9] offset:2048 nt
	global_load_dwordx4 v[60:63], v120, s[8:9] offset:3072 nt
	s_add_u32 s8, s8, 0x40000
	s_addc_u32 s9, s9, 0
	global_load_dwordx4 v[64:67], v120, s[8:9] offset:0 nt
	global_load_dwordx4 v[68:71], v120, s[8:9] offset:1024 nt
	global_load_dwordx4 v[72:75], v120, s[8:9] offset:2048 nt
	global_load_dwordx4 v[76:79], v120, s[8:9] offset:3072 nt
	s_add_u32 s8, s8, 0x40000
	s_addc_u32 s9, s9, 0
	global_load_dwordx4 v[80:83], v120, s[8:9] offset:0 nt
	global_load_dwordx4 v[84:87], v120, s[8:9] offset:1024 nt
	global_load_dwordx4 v[88:91], v120, s[8:9] offset:2048 nt
	global_load_dwordx4 v[92:95], v120, s[8:9] offset:3072 nt
	s_add_u32 s8, s8, 0x40000
	s_addc_u32 s9, s9, 0
	global_load_dwordx4 v[96:99], v120, s[8:9] offset:0 nt
	global_load_dwordx4 v[100:103], v120, s[8:9] offset:1024 nt
	global_load_dwordx4 v[104:107], v120, s[8:9] offset:2048 nt
	global_load_dwordx4 v[108:111], v120, s[8:9] offset:3072 nt
	s_add_u32 s8, s8, 0x40000
	s_addc_u32 s9, s9, 0
	s_waitcnt vmcnt(44)
	v_mul_f32_e32 v112, v132, v132
	v_fmac_f32_e32 v112, v133, v133
	v_fmac_f32_e32 v112, v134, v134
	v_fmac_f32_e32 v112, v135, v135
	v_fmac_f32_e32 v112, v136, v136
	v_fmac_f32_e32 v112, v137, v137
	v_fmac_f32_e32 v112, v138, v138
	v_fmac_f32_e32 v112, v139, v139
	v_fmac_f32_e32 v112, v140, v140
	v_fmac_f32_e32 v112, v141, v141
	v_fmac_f32_e32 v112, v142, v142
	v_fmac_f32_e32 v112, v143, v143
	v_fmac_f32_e32 v112, v144, v144
	v_fmac_f32_e32 v112, v145, v145
	v_fmac_f32_e32 v112, v146, v146
	v_fmac_f32_e32 v112, v147, v147
	s_waitcnt vmcnt(40)
	v_mul_f32_e32 v113, v166, v166
	v_fmac_f32_e32 v113, v167, v167
	v_fmac_f32_e32 v113, v168, v168
	v_fmac_f32_e32 v113, v169, v169
	v_fmac_f32_e32 v113, v170, v170
	v_fmac_f32_e32 v113, v171, v171
	v_fmac_f32_e32 v113, v172, v172
	v_fmac_f32_e32 v113, v173, v173
	v_fmac_f32_e32 v113, v174, v174
	v_fmac_f32_e32 v113, v175, v175
	v_fmac_f32_e32 v113, v176, v176
	v_fmac_f32_e32 v113, v177, v177
	v_fmac_f32_e32 v113, v178, v178
	v_fmac_f32_e32 v113, v179, v179
	v_fmac_f32_e32 v113, v180, v180
	v_fmac_f32_e32 v113, v181, v181
	s_waitcnt vmcnt(36)
	v_mul_f32_e32 v114, v182, v182
	v_fmac_f32_e32 v114, v183, v183
	v_fmac_f32_e32 v114, v184, v184
	v_fmac_f32_e32 v114, v185, v185
	v_fmac_f32_e32 v114, v186, v186
	v_fmac_f32_e32 v114, v187, v187
	v_fmac_f32_e32 v114, v188, v188
	v_fmac_f32_e32 v114, v189, v189
	v_fmac_f32_e32 v114, v190, v190
	v_fmac_f32_e32 v114, v191, v191
	v_fmac_f32_e32 v114, v192, v192
	v_fmac_f32_e32 v114, v193, v193
	v_fmac_f32_e32 v114, v194, v194
	v_fmac_f32_e32 v114, v195, v195
	v_fmac_f32_e32 v114, v196, v196
	v_fmac_f32_e32 v114, v197, v197
	s_waitcnt vmcnt(32)
	v_mul_f32_e32 v115, v228, v228
	v_fmac_f32_e32 v115, v229, v229
	v_fmac_f32_e32 v115, v230, v230
	v_fmac_f32_e32 v115, v231, v231
	v_fmac_f32_e32 v115, v232, v232
	v_fmac_f32_e32 v115, v233, v233
	v_fmac_f32_e32 v115, v234, v234
	v_fmac_f32_e32 v115, v235, v235
	v_fmac_f32_e32 v115, v236, v236
	v_fmac_f32_e32 v115, v237, v237
	v_fmac_f32_e32 v115, v238, v238
	v_fmac_f32_e32 v115, v239, v239
	v_fmac_f32_e32 v115, v240, v240
	v_fmac_f32_e32 v115, v241, v241
	v_fmac_f32_e32 v115, v242, v242
	v_fmac_f32_e32 v115, v243, v243
	ds_bpermute_b32 v116, v122, v112
	ds_bpermute_b32 v117, v122, v113
	ds_bpermute_b32 v118, v122, v114
	ds_bpermute_b32 v119, v122, v115
	s_waitcnt lgkmcnt(0)
	v_add_f32_e32 v112, v112, v116
	v_add_f32_e32 v113, v113, v117
	v_add_f32_e32 v114, v114, v118
	v_add_f32_e32 v115, v115, v119
	ds_bpermute_b32 v116, v123, v112
	ds_bpermute_b32 v117, v123, v113
	ds_bpermute_b32 v118, v123, v114
	ds_bpermute_b32 v119, v123, v115
	s_waitcnt lgkmcnt(0)
	v_add_f32_e32 v112, v112, v116
	v_add_f32_e32 v113, v113, v117
	v_add_f32_e32 v114, v114, v118
	v_add_f32_e32 v115, v115, v119
	ds_bpermute_b32 v116, v124, v112
	ds_bpermute_b32 v117, v124, v113
	ds_bpermute_b32 v118, v124, v114
	ds_bpermute_b32 v119, v124, v115
	s_waitcnt lgkmcnt(0)
	v_add_f32_e32 v112, v112, v116
	v_add_f32_e32 v113, v113, v117
	v_add_f32_e32 v114, v114, v118
	v_add_f32_e32 v115, v115, v119
	ds_bpermute_b32 v116, v125, v112
	ds_bpermute_b32 v117, v125, v113
	ds_bpermute_b32 v118, v125, v114
	ds_bpermute_b32 v119, v125, v115
	s_waitcnt lgkmcnt(0)
	v_add_f32_e32 v112, v112, v116
	v_add_f32_e32 v113, v113, v117
	v_add_f32_e32 v114, v114, v118
	v_add_f32_e32 v115, v115, v119
	ds_bpermute_b32 v116, v126, v112
	ds_bpermute_b32 v117, v126, v113
	ds_bpermute_b32 v118, v126, v114
	ds_bpermute_b32 v119, v126, v115
	s_waitcnt lgkmcnt(0)
	v_add_f32_e32 v112, v112, v116
	v_add_f32_e32 v113, v113, v117
	v_add_f32_e32 v114, v114, v118
	v_add_f32_e32 v115, v115, v119
	ds_bpermute_b32 v116, v127, v112
	ds_bpermute_b32 v117, v127, v113
	ds_bpermute_b32 v118, v127, v114
	ds_bpermute_b32 v119, v127, v115
	s_waitcnt lgkmcnt(0)
	v_add_f32_e32 v112, v112, v116
	v_add_f32_e32 v113, v113, v117
	v_add_f32_e32 v114, v114, v118
	v_add_f32_e32 v115, v115, v119
	v_fmamk_f32 v112, v112, 0x3a800000, v208
	v_fmamk_f32 v113, v113, 0x3a800000, v208
	v_fmamk_f32 v114, v114, 0x3a800000, v208
	v_fmamk_f32 v115, v115, 0x3a800000, v208
	v_rsq_f32_e32 v112, v112
	v_rsq_f32_e32 v113, v113
	v_rsq_f32_e32 v114, v114
	v_rsq_f32_e32 v115, v115
	s_nop 1
	v_mul_f32_e32 v132, v132, v112
	v_mul_f32_e32 v133, v133, v112
	v_mul_f32_e32 v134, v134, v112
	v_mul_f32_e32 v135, v135, v112
	v_mul_f32_e32 v132, v0, v132
	v_mul_f32_e32 v133, v1, v133
	v_mul_f32_e32 v134, v2, v134
	v_mul_f32_e32 v135, v3, v135
	global_store_dwordx4 v120, v[132:135], s[6:7] offset:0
	v_mul_f32_e32 v136, v136, v112
	v_mul_f32_e32 v137, v137, v112
	v_mul_f32_e32 v138, v138, v112
	v_mul_f32_e32 v139, v139, v112
	v_mul_f32_e32 v136, v4, v136
	v_mul_f32_e32 v137, v5, v137
	v_mul_f32_e32 v138, v6, v138
	v_mul_f32_e32 v139, v7, v139
	global_store_dwordx4 v120, v[136:139], s[6:7] offset:1024
	v_mul_f32_e32 v140, v140, v112
	v_mul_f32_e32 v141, v141, v112
	v_mul_f32_e32 v142, v142, v112
	v_mul_f32_e32 v143, v143, v112
	v_mul_f32_e32 v140, v8, v140
	v_mul_f32_e32 v141, v9, v141
	v_mul_f32_e32 v142, v10, v142
	v_mul_f32_e32 v143, v11, v143
	global_store_dwordx4 v120, v[140:143], s[6:7] offset:2048
	v_mul_f32_e32 v144, v144, v112
	v_mul_f32_e32 v145, v145, v112
	v_mul_f32_e32 v146, v146, v112
	v_mul_f32_e32 v147, v147, v112
	v_mul_f32_e32 v144, v12, v144
	v_mul_f32_e32 v145, v13, v145
	v_mul_f32_e32 v146, v14, v146
	v_mul_f32_e32 v147, v15, v147
	global_store_dwordx4 v120, v[144:147], s[6:7] offset:3072
	s_add_u32 s6, s6, 0x40000
	s_addc_u32 s7, s7, 0
	v_mul_f32_e32 v166, v166, v113
	v_mul_f32_e32 v167, v167, v113
	v_mul_f32_e32 v168, v168, v113
	v_mul_f32_e32 v169, v169, v113
	v_mul_f32_e32 v166, v0, v166
	v_mul_f32_e32 v167, v1, v167
	v_mul_f32_e32 v168, v2, v168
	v_mul_f32_e32 v169, v3, v169
	global_store_dwordx4 v120, v[166:169], s[6:7] offset:0
	v_mul_f32_e32 v170, v170, v113
	v_mul_f32_e32 v171, v171, v113
	v_mul_f32_e32 v172, v172, v113
	v_mul_f32_e32 v173, v173, v113
	v_mul_f32_e32 v170, v4, v170
	v_mul_f32_e32 v171, v5, v171
	v_mul_f32_e32 v172, v6, v172
	v_mul_f32_e32 v173, v7, v173
	global_store_dwordx4 v120, v[170:173], s[6:7] offset:1024
	v_mul_f32_e32 v174, v174, v113
	v_mul_f32_e32 v175, v175, v113
	v_mul_f32_e32 v176, v176, v113
	v_mul_f32_e32 v177, v177, v113
	v_mul_f32_e32 v174, v8, v174
	v_mul_f32_e32 v175, v9, v175
	v_mul_f32_e32 v176, v10, v176
	v_mul_f32_e32 v177, v11, v177
	global_store_dwordx4 v120, v[174:177], s[6:7] offset:2048
	v_mul_f32_e32 v178, v178, v113
	v_mul_f32_e32 v179, v179, v113
	v_mul_f32_e32 v180, v180, v113
	v_mul_f32_e32 v181, v181, v113
	v_mul_f32_e32 v178, v12, v178
	v_mul_f32_e32 v179, v13, v179
	v_mul_f32_e32 v180, v14, v180
	v_mul_f32_e32 v181, v15, v181
	global_store_dwordx4 v120, v[178:181], s[6:7] offset:3072
	s_add_u32 s6, s6, 0x40000
	s_addc_u32 s7, s7, 0
	v_mul_f32_e32 v182, v182, v114
	v_mul_f32_e32 v183, v183, v114
	v_mul_f32_e32 v184, v184, v114
	v_mul_f32_e32 v185, v185, v114
	v_mul_f32_e32 v182, v0, v182
	v_mul_f32_e32 v183, v1, v183
	v_mul_f32_e32 v184, v2, v184
	v_mul_f32_e32 v185, v3, v185
	global_store_dwordx4 v120, v[182:185], s[6:7] offset:0
	v_mul_f32_e32 v186, v186, v114
	v_mul_f32_e32 v187, v187, v114
	v_mul_f32_e32 v188, v188, v114
	v_mul_f32_e32 v189, v189, v114
	v_mul_f32_e32 v186, v4, v186
	v_mul_f32_e32 v187, v5, v187
	v_mul_f32_e32 v188, v6, v188
	v_mul_f32_e32 v189, v7, v189
	global_store_dwordx4 v120, v[186:189], s[6:7] offset:1024
	v_mul_f32_e32 v190, v190, v114
	v_mul_f32_e32 v191, v191, v114
	v_mul_f32_e32 v192, v192, v114
	v_mul_f32_e32 v193, v193, v114
	v_mul_f32_e32 v190, v8, v190
	v_mul_f32_e32 v191, v9, v191
	v_mul_f32_e32 v192, v10, v192
	v_mul_f32_e32 v193, v11, v193
	global_store_dwordx4 v120, v[190:193], s[6:7] offset:2048
	v_mul_f32_e32 v194, v194, v114
	v_mul_f32_e32 v195, v195, v114
	v_mul_f32_e32 v196, v196, v114
	v_mul_f32_e32 v197, v197, v114
	v_mul_f32_e32 v194, v12, v194
	v_mul_f32_e32 v195, v13, v195
	v_mul_f32_e32 v196, v14, v196
	v_mul_f32_e32 v197, v15, v197
	global_store_dwordx4 v120, v[194:197], s[6:7] offset:3072
	s_add_u32 s6, s6, 0x40000
	s_addc_u32 s7, s7, 0
	v_mul_f32_e32 v228, v228, v115
	v_mul_f32_e32 v229, v229, v115
	v_mul_f32_e32 v230, v230, v115
	v_mul_f32_e32 v231, v231, v115
	v_mul_f32_e32 v228, v0, v228
	v_mul_f32_e32 v229, v1, v229
	v_mul_f32_e32 v230, v2, v230
	v_mul_f32_e32 v231, v3, v231
	global_store_dwordx4 v120, v[228:231], s[6:7] offset:0
	v_mul_f32_e32 v232, v232, v115
	v_mul_f32_e32 v233, v233, v115
	v_mul_f32_e32 v234, v234, v115
	v_mul_f32_e32 v235, v235, v115
	v_mul_f32_e32 v232, v4, v232
	v_mul_f32_e32 v233, v5, v233
	v_mul_f32_e32 v234, v6, v234
	v_mul_f32_e32 v235, v7, v235
	global_store_dwordx4 v120, v[232:235], s[6:7] offset:1024
	v_mul_f32_e32 v236, v236, v115
	v_mul_f32_e32 v237, v237, v115
	v_mul_f32_e32 v238, v238, v115
	v_mul_f32_e32 v239, v239, v115
	v_mul_f32_e32 v236, v8, v236
	v_mul_f32_e32 v237, v9, v237
	v_mul_f32_e32 v238, v10, v238
	v_mul_f32_e32 v239, v11, v239
	global_store_dwordx4 v120, v[236:239], s[6:7] offset:2048
	v_mul_f32_e32 v240, v240, v115
	v_mul_f32_e32 v241, v241, v115
	v_mul_f32_e32 v242, v242, v115
	v_mul_f32_e32 v243, v243, v115
	v_mul_f32_e32 v240, v12, v240
	v_mul_f32_e32 v241, v13, v241
	v_mul_f32_e32 v242, v14, v242
	v_mul_f32_e32 v243, v15, v243
	global_store_dwordx4 v120, v[240:243], s[6:7] offset:3072
	s_add_u32 s6, s6, 0x40000
	s_addc_u32 s7, s7, 0
	global_load_dwordx4 v[132:135], v120, s[8:9] offset:0 nt
	global_load_dwordx4 v[136:139], v120, s[8:9] offset:1024 nt
	global_load_dwordx4 v[140:143], v120, s[8:9] offset:2048 nt
	global_load_dwordx4 v[144:147], v120, s[8:9] offset:3072 nt
	s_add_u32 s8, s8, 0x40000
	s_addc_u32 s9, s9, 0
	global_load_dwordx4 v[166:169], v120, s[8:9] offset:0 nt
	global_load_dwordx4 v[170:173], v120, s[8:9] offset:1024 nt
	global_load_dwordx4 v[174:177], v120, s[8:9] offset:2048 nt
	global_load_dwordx4 v[178:181], v120, s[8:9] offset:3072 nt
	s_add_u32 s8, s8, 0x40000
	s_addc_u32 s9, s9, 0
	global_load_dwordx4 v[182:185], v120, s[8:9] offset:0 nt
	global_load_dwordx4 v[186:189], v120, s[8:9] offset:1024 nt
	global_load_dwordx4 v[190:193], v120, s[8:9] offset:2048 nt
	global_load_dwordx4 v[194:197], v120, s[8:9] offset:3072 nt
	s_add_u32 s8, s8, 0x40000
	s_addc_u32 s9, s9, 0
	global_load_dwordx4 v[228:231], v120, s[8:9] offset:0 nt
	global_load_dwordx4 v[232:235], v120, s[8:9] offset:1024 nt
	global_load_dwordx4 v[236:239], v120, s[8:9] offset:2048 nt
	global_load_dwordx4 v[240:243], v120, s[8:9] offset:3072 nt
	s_add_u32 s8, s8, 0x40000
	s_addc_u32 s9, s9, 0
	s_waitcnt vmcnt(44)
	v_mul_f32_e32 v112, v48, v48
	v_fmac_f32_e32 v112, v49, v49
	v_fmac_f32_e32 v112, v50, v50
	v_fmac_f32_e32 v112, v51, v51
	v_fmac_f32_e32 v112, v52, v52
	v_fmac_f32_e32 v112, v53, v53
	v_fmac_f32_e32 v112, v54, v54
	v_fmac_f32_e32 v112, v55, v55
	v_fmac_f32_e32 v112, v56, v56
	v_fmac_f32_e32 v112, v57, v57
	v_fmac_f32_e32 v112, v58, v58
	v_fmac_f32_e32 v112, v59, v59
	v_fmac_f32_e32 v112, v60, v60
	v_fmac_f32_e32 v112, v61, v61
	v_fmac_f32_e32 v112, v62, v62
	v_fmac_f32_e32 v112, v63, v63
	s_waitcnt vmcnt(40)
	v_mul_f32_e32 v113, v64, v64
	v_fmac_f32_e32 v113, v65, v65
	v_fmac_f32_e32 v113, v66, v66
	v_fmac_f32_e32 v113, v67, v67
	v_fmac_f32_e32 v113, v68, v68
	v_fmac_f32_e32 v113, v69, v69
	v_fmac_f32_e32 v113, v70, v70
	v_fmac_f32_e32 v113, v71, v71
	v_fmac_f32_e32 v113, v72, v72
	v_fmac_f32_e32 v113, v73, v73
	v_fmac_f32_e32 v113, v74, v74
	v_fmac_f32_e32 v113, v75, v75
	v_fmac_f32_e32 v113, v76, v76
	v_fmac_f32_e32 v113, v77, v77
	v_fmac_f32_e32 v113, v78, v78
	v_fmac_f32_e32 v113, v79, v79
	s_waitcnt vmcnt(36)
	v_mul_f32_e32 v114, v80, v80
	v_fmac_f32_e32 v114, v81, v81
	v_fmac_f32_e32 v114, v82, v82
	v_fmac_f32_e32 v114, v83, v83
	v_fmac_f32_e32 v114, v84, v84
	v_fmac_f32_e32 v114, v85, v85
	v_fmac_f32_e32 v114, v86, v86
	v_fmac_f32_e32 v114, v87, v87
	v_fmac_f32_e32 v114, v88, v88
	v_fmac_f32_e32 v114, v89, v89
	v_fmac_f32_e32 v114, v90, v90
	v_fmac_f32_e32 v114, v91, v91
	v_fmac_f32_e32 v114, v92, v92
	v_fmac_f32_e32 v114, v93, v93
	v_fmac_f32_e32 v114, v94, v94
	v_fmac_f32_e32 v114, v95, v95
	s_waitcnt vmcnt(32)
	v_mul_f32_e32 v115, v96, v96
	v_fmac_f32_e32 v115, v97, v97
	v_fmac_f32_e32 v115, v98, v98
	v_fmac_f32_e32 v115, v99, v99
	v_fmac_f32_e32 v115, v100, v100
	v_fmac_f32_e32 v115, v101, v101
	v_fmac_f32_e32 v115, v102, v102
	v_fmac_f32_e32 v115, v103, v103
	v_fmac_f32_e32 v115, v104, v104
	v_fmac_f32_e32 v115, v105, v105
	v_fmac_f32_e32 v115, v106, v106
	v_fmac_f32_e32 v115, v107, v107
	v_fmac_f32_e32 v115, v108, v108
	v_fmac_f32_e32 v115, v109, v109
	v_fmac_f32_e32 v115, v110, v110
	v_fmac_f32_e32 v115, v111, v111
	ds_bpermute_b32 v116, v122, v112
	ds_bpermute_b32 v117, v122, v113
	ds_bpermute_b32 v118, v122, v114
	ds_bpermute_b32 v119, v122, v115
	s_waitcnt lgkmcnt(0)
	v_add_f32_e32 v112, v112, v116
	v_add_f32_e32 v113, v113, v117
	v_add_f32_e32 v114, v114, v118
	v_add_f32_e32 v115, v115, v119
	ds_bpermute_b32 v116, v123, v112
	ds_bpermute_b32 v117, v123, v113
	ds_bpermute_b32 v118, v123, v114
	ds_bpermute_b32 v119, v123, v115
	s_waitcnt lgkmcnt(0)
	v_add_f32_e32 v112, v112, v116
	v_add_f32_e32 v113, v113, v117
	v_add_f32_e32 v114, v114, v118
	v_add_f32_e32 v115, v115, v119
	ds_bpermute_b32 v116, v124, v112
	ds_bpermute_b32 v117, v124, v113
	ds_bpermute_b32 v118, v124, v114
	ds_bpermute_b32 v119, v124, v115
	s_waitcnt lgkmcnt(0)
	v_add_f32_e32 v112, v112, v116
	v_add_f32_e32 v113, v113, v117
	v_add_f32_e32 v114, v114, v118
	v_add_f32_e32 v115, v115, v119
	ds_bpermute_b32 v116, v125, v112
	ds_bpermute_b32 v117, v125, v113
	ds_bpermute_b32 v118, v125, v114
	ds_bpermute_b32 v119, v125, v115
	s_waitcnt lgkmcnt(0)
	v_add_f32_e32 v112, v112, v116
	v_add_f32_e32 v113, v113, v117
	v_add_f32_e32 v114, v114, v118
	v_add_f32_e32 v115, v115, v119
	ds_bpermute_b32 v116, v126, v112
	ds_bpermute_b32 v117, v126, v113
	ds_bpermute_b32 v118, v126, v114
	ds_bpermute_b32 v119, v126, v115
	s_waitcnt lgkmcnt(0)
	v_add_f32_e32 v112, v112, v116
	v_add_f32_e32 v113, v113, v117
	v_add_f32_e32 v114, v114, v118
	v_add_f32_e32 v115, v115, v119
	ds_bpermute_b32 v116, v127, v112
	ds_bpermute_b32 v117, v127, v113
	ds_bpermute_b32 v118, v127, v114
	ds_bpermute_b32 v119, v127, v115
	s_waitcnt lgkmcnt(0)
	v_add_f32_e32 v112, v112, v116
	v_add_f32_e32 v113, v113, v117
	v_add_f32_e32 v114, v114, v118
	v_add_f32_e32 v115, v115, v119
	v_fmamk_f32 v112, v112, 0x3a800000, v208
	v_fmamk_f32 v113, v113, 0x3a800000, v208
	v_fmamk_f32 v114, v114, 0x3a800000, v208
	v_fmamk_f32 v115, v115, 0x3a800000, v208
	v_rsq_f32_e32 v112, v112
	v_rsq_f32_e32 v113, v113
	v_rsq_f32_e32 v114, v114
	v_rsq_f32_e32 v115, v115
	s_nop 1
	v_mul_f32_e32 v48, v48, v112
	v_mul_f32_e32 v49, v49, v112
	v_mul_f32_e32 v50, v50, v112
	v_mul_f32_e32 v51, v51, v112
	v_mul_f32_e32 v48, v0, v48
	v_mul_f32_e32 v49, v1, v49
	v_mul_f32_e32 v50, v2, v50
	v_mul_f32_e32 v51, v3, v51
	global_store_dwordx4 v120, v[48:51], s[6:7] offset:0
	v_mul_f32_e32 v52, v52, v112
	v_mul_f32_e32 v53, v53, v112
	v_mul_f32_e32 v54, v54, v112
	v_mul_f32_e32 v55, v55, v112
	v_mul_f32_e32 v52, v4, v52
	v_mul_f32_e32 v53, v5, v53
	v_mul_f32_e32 v54, v6, v54
	v_mul_f32_e32 v55, v7, v55
	global_store_dwordx4 v120, v[52:55], s[6:7] offset:1024
	v_mul_f32_e32 v56, v56, v112
	v_mul_f32_e32 v57, v57, v112
	v_mul_f32_e32 v58, v58, v112
	v_mul_f32_e32 v59, v59, v112
	v_mul_f32_e32 v56, v8, v56
	v_mul_f32_e32 v57, v9, v57
	v_mul_f32_e32 v58, v10, v58
	v_mul_f32_e32 v59, v11, v59
	global_store_dwordx4 v120, v[56:59], s[6:7] offset:2048
	v_mul_f32_e32 v60, v60, v112
	v_mul_f32_e32 v61, v61, v112
	v_mul_f32_e32 v62, v62, v112
	v_mul_f32_e32 v63, v63, v112
	v_mul_f32_e32 v60, v12, v60
	v_mul_f32_e32 v61, v13, v61
	v_mul_f32_e32 v62, v14, v62
	v_mul_f32_e32 v63, v15, v63
	global_store_dwordx4 v120, v[60:63], s[6:7] offset:3072
	s_add_u32 s6, s6, 0x40000
	s_addc_u32 s7, s7, 0
	v_mul_f32_e32 v64, v64, v113
	v_mul_f32_e32 v65, v65, v113
	v_mul_f32_e32 v66, v66, v113
	v_mul_f32_e32 v67, v67, v113
	v_mul_f32_e32 v64, v0, v64
	v_mul_f32_e32 v65, v1, v65
	v_mul_f32_e32 v66, v2, v66
	v_mul_f32_e32 v67, v3, v67
	global_store_dwordx4 v120, v[64:67], s[6:7] offset:0
	v_mul_f32_e32 v68, v68, v113
	v_mul_f32_e32 v69, v69, v113
	v_mul_f32_e32 v70, v70, v113
	v_mul_f32_e32 v71, v71, v113
	v_mul_f32_e32 v68, v4, v68
	v_mul_f32_e32 v69, v5, v69
	v_mul_f32_e32 v70, v6, v70
	v_mul_f32_e32 v71, v7, v71
	global_store_dwordx4 v120, v[68:71], s[6:7] offset:1024
	v_mul_f32_e32 v72, v72, v113
	v_mul_f32_e32 v73, v73, v113
	v_mul_f32_e32 v74, v74, v113
	v_mul_f32_e32 v75, v75, v113
	v_mul_f32_e32 v72, v8, v72
	v_mul_f32_e32 v73, v9, v73
	v_mul_f32_e32 v74, v10, v74
	v_mul_f32_e32 v75, v11, v75
	global_store_dwordx4 v120, v[72:75], s[6:7] offset:2048
	v_mul_f32_e32 v76, v76, v113
	v_mul_f32_e32 v77, v77, v113
	v_mul_f32_e32 v78, v78, v113
	v_mul_f32_e32 v79, v79, v113
	v_mul_f32_e32 v76, v12, v76
	v_mul_f32_e32 v77, v13, v77
	v_mul_f32_e32 v78, v14, v78
	v_mul_f32_e32 v79, v15, v79
	global_store_dwordx4 v120, v[76:79], s[6:7] offset:3072
	s_add_u32 s6, s6, 0x40000
	s_addc_u32 s7, s7, 0
	v_mul_f32_e32 v80, v80, v114
	v_mul_f32_e32 v81, v81, v114
	v_mul_f32_e32 v82, v82, v114
	v_mul_f32_e32 v83, v83, v114
	v_mul_f32_e32 v80, v0, v80
	v_mul_f32_e32 v81, v1, v81
	v_mul_f32_e32 v82, v2, v82
	v_mul_f32_e32 v83, v3, v83
	global_store_dwordx4 v120, v[80:83], s[6:7] offset:0
	v_mul_f32_e32 v84, v84, v114
	v_mul_f32_e32 v85, v85, v114
	v_mul_f32_e32 v86, v86, v114
	v_mul_f32_e32 v87, v87, v114
	v_mul_f32_e32 v84, v4, v84
	v_mul_f32_e32 v85, v5, v85
	v_mul_f32_e32 v86, v6, v86
	v_mul_f32_e32 v87, v7, v87
	global_store_dwordx4 v120, v[84:87], s[6:7] offset:1024
	v_mul_f32_e32 v88, v88, v114
	v_mul_f32_e32 v89, v89, v114
	v_mul_f32_e32 v90, v90, v114
	v_mul_f32_e32 v91, v91, v114
	v_mul_f32_e32 v88, v8, v88
	v_mul_f32_e32 v89, v9, v89
	v_mul_f32_e32 v90, v10, v90
	v_mul_f32_e32 v91, v11, v91
	global_store_dwordx4 v120, v[88:91], s[6:7] offset:2048
	v_mul_f32_e32 v92, v92, v114
	v_mul_f32_e32 v93, v93, v114
	v_mul_f32_e32 v94, v94, v114
	v_mul_f32_e32 v95, v95, v114
	v_mul_f32_e32 v92, v12, v92
	v_mul_f32_e32 v93, v13, v93
	v_mul_f32_e32 v94, v14, v94
	v_mul_f32_e32 v95, v15, v95
	global_store_dwordx4 v120, v[92:95], s[6:7] offset:3072
	s_add_u32 s6, s6, 0x40000
	s_addc_u32 s7, s7, 0
	v_mul_f32_e32 v96, v96, v115
	v_mul_f32_e32 v97, v97, v115
	v_mul_f32_e32 v98, v98, v115
	v_mul_f32_e32 v99, v99, v115
	v_mul_f32_e32 v96, v0, v96
	v_mul_f32_e32 v97, v1, v97
	v_mul_f32_e32 v98, v2, v98
	v_mul_f32_e32 v99, v3, v99
	global_store_dwordx4 v120, v[96:99], s[6:7] offset:0
	v_mul_f32_e32 v100, v100, v115
	v_mul_f32_e32 v101, v101, v115
	v_mul_f32_e32 v102, v102, v115
	v_mul_f32_e32 v103, v103, v115
	v_mul_f32_e32 v100, v4, v100
	v_mul_f32_e32 v101, v5, v101
	v_mul_f32_e32 v102, v6, v102
	v_mul_f32_e32 v103, v7, v103
	global_store_dwordx4 v120, v[100:103], s[6:7] offset:1024
	v_mul_f32_e32 v104, v104, v115
	v_mul_f32_e32 v105, v105, v115
	v_mul_f32_e32 v106, v106, v115
	v_mul_f32_e32 v107, v107, v115
	v_mul_f32_e32 v104, v8, v104
	v_mul_f32_e32 v105, v9, v105
	v_mul_f32_e32 v106, v10, v106
	v_mul_f32_e32 v107, v11, v107
	global_store_dwordx4 v120, v[104:107], s[6:7] offset:2048
	v_mul_f32_e32 v108, v108, v115
	v_mul_f32_e32 v109, v109, v115
	v_mul_f32_e32 v110, v110, v115
	v_mul_f32_e32 v111, v111, v115
	v_mul_f32_e32 v108, v12, v108
	v_mul_f32_e32 v109, v13, v109
	v_mul_f32_e32 v110, v14, v110
	v_mul_f32_e32 v111, v15, v111
	global_store_dwordx4 v120, v[108:111], s[6:7] offset:3072
	s_add_u32 s6, s6, 0x40000
	s_addc_u32 s7, s7, 0
	s_sub_u32 s2, s2, 1
	s_cmp_lg_u32 s2, 0
	s_cbranch_scc1 .Lrms_final_loop
	s_waitcnt vmcnt(28)
	v_mul_f32_e32 v112, v132, v132
	v_fmac_f32_e32 v112, v133, v133
	v_fmac_f32_e32 v112, v134, v134
	v_fmac_f32_e32 v112, v135, v135
	v_fmac_f32_e32 v112, v136, v136
	v_fmac_f32_e32 v112, v137, v137
	v_fmac_f32_e32 v112, v138, v138
	v_fmac_f32_e32 v112, v139, v139
	v_fmac_f32_e32 v112, v140, v140
	v_fmac_f32_e32 v112, v141, v141
	v_fmac_f32_e32 v112, v142, v142
	v_fmac_f32_e32 v112, v143, v143
	v_fmac_f32_e32 v112, v144, v144
	v_fmac_f32_e32 v112, v145, v145
	v_fmac_f32_e32 v112, v146, v146
	v_fmac_f32_e32 v112, v147, v147
	s_waitcnt vmcnt(24)
	v_mul_f32_e32 v113, v166, v166
	v_fmac_f32_e32 v113, v167, v167
	v_fmac_f32_e32 v113, v168, v168
	v_fmac_f32_e32 v113, v169, v169
	v_fmac_f32_e32 v113, v170, v170
	v_fmac_f32_e32 v113, v171, v171
	v_fmac_f32_e32 v113, v172, v172
	v_fmac_f32_e32 v113, v173, v173
	v_fmac_f32_e32 v113, v174, v174
	v_fmac_f32_e32 v113, v175, v175
	v_fmac_f32_e32 v113, v176, v176
	v_fmac_f32_e32 v113, v177, v177
	v_fmac_f32_e32 v113, v178, v178
	v_fmac_f32_e32 v113, v179, v179
	v_fmac_f32_e32 v113, v180, v180
	v_fmac_f32_e32 v113, v181, v181
	s_waitcnt vmcnt(20)
	v_mul_f32_e32 v114, v182, v182
	v_fmac_f32_e32 v114, v183, v183
	v_fmac_f32_e32 v114, v184, v184
	v_fmac_f32_e32 v114, v185, v185
	v_fmac_f32_e32 v114, v186, v186
	v_fmac_f32_e32 v114, v187, v187
	v_fmac_f32_e32 v114, v188, v188
	v_fmac_f32_e32 v114, v189, v189
	v_fmac_f32_e32 v114, v190, v190
	v_fmac_f32_e32 v114, v191, v191
	v_fmac_f32_e32 v114, v192, v192
	v_fmac_f32_e32 v114, v193, v193
	v_fmac_f32_e32 v114, v194, v194
	v_fmac_f32_e32 v114, v195, v195
	v_fmac_f32_e32 v114, v196, v196
	v_fmac_f32_e32 v114, v197, v197
	s_waitcnt vmcnt(16)
	v_mul_f32_e32 v115, v228, v228
	v_fmac_f32_e32 v115, v229, v229
	v_fmac_f32_e32 v115, v230, v230
	v_fmac_f32_e32 v115, v231, v231
	v_fmac_f32_e32 v115, v232, v232
	v_fmac_f32_e32 v115, v233, v233
	v_fmac_f32_e32 v115, v234, v234
	v_fmac_f32_e32 v115, v235, v235
	v_fmac_f32_e32 v115, v236, v236
	v_fmac_f32_e32 v115, v237, v237
	v_fmac_f32_e32 v115, v238, v238
	v_fmac_f32_e32 v115, v239, v239
	v_fmac_f32_e32 v115, v240, v240
	v_fmac_f32_e32 v115, v241, v241
	v_fmac_f32_e32 v115, v242, v242
	v_fmac_f32_e32 v115, v243, v243
	ds_bpermute_b32 v116, v122, v112
	ds_bpermute_b32 v117, v122, v113
	ds_bpermute_b32 v118, v122, v114
	ds_bpermute_b32 v119, v122, v115
	s_waitcnt lgkmcnt(0)
	v_add_f32_e32 v112, v112, v116
	v_add_f32_e32 v113, v113, v117
	v_add_f32_e32 v114, v114, v118
	v_add_f32_e32 v115, v115, v119
	ds_bpermute_b32 v116, v123, v112
	ds_bpermute_b32 v117, v123, v113
	ds_bpermute_b32 v118, v123, v114
	ds_bpermute_b32 v119, v123, v115
	s_waitcnt lgkmcnt(0)
	v_add_f32_e32 v112, v112, v116
	v_add_f32_e32 v113, v113, v117
	v_add_f32_e32 v114, v114, v118
	v_add_f32_e32 v115, v115, v119
	ds_bpermute_b32 v116, v124, v112
	ds_bpermute_b32 v117, v124, v113
	ds_bpermute_b32 v118, v124, v114
	ds_bpermute_b32 v119, v124, v115
	s_waitcnt lgkmcnt(0)
	v_add_f32_e32 v112, v112, v116
	v_add_f32_e32 v113, v113, v117
	v_add_f32_e32 v114, v114, v118
	v_add_f32_e32 v115, v115, v119
	ds_bpermute_b32 v116, v125, v112
	ds_bpermute_b32 v117, v125, v113
	ds_bpermute_b32 v118, v125, v114
	ds_bpermute_b32 v119, v125, v115
	s_waitcnt lgkmcnt(0)
	v_add_f32_e32 v112, v112, v116
	v_add_f32_e32 v113, v113, v117
	v_add_f32_e32 v114, v114, v118
	v_add_f32_e32 v115, v115, v119
	ds_bpermute_b32 v116, v126, v112
	ds_bpermute_b32 v117, v126, v113
	ds_bpermute_b32 v118, v126, v114
	ds_bpermute_b32 v119, v126, v115
	s_waitcnt lgkmcnt(0)
	v_add_f32_e32 v112, v112, v116
	v_add_f32_e32 v113, v113, v117
	v_add_f32_e32 v114, v114, v118
	v_add_f32_e32 v115, v115, v119
	ds_bpermute_b32 v116, v127, v112
	ds_bpermute_b32 v117, v127, v113
	ds_bpermute_b32 v118, v127, v114
	ds_bpermute_b32 v119, v127, v115
	s_waitcnt lgkmcnt(0)
	v_add_f32_e32 v112, v112, v116
	v_add_f32_e32 v113, v113, v117
	v_add_f32_e32 v114, v114, v118
	v_add_f32_e32 v115, v115, v119
	v_fmamk_f32 v112, v112, 0x3a800000, v208
	v_fmamk_f32 v113, v113, 0x3a800000, v208
	v_fmamk_f32 v114, v114, 0x3a800000, v208
	v_fmamk_f32 v115, v115, 0x3a800000, v208
	v_rsq_f32_e32 v112, v112
	v_rsq_f32_e32 v113, v113
	v_rsq_f32_e32 v114, v114
	v_rsq_f32_e32 v115, v115
	s_nop 1
	v_mul_f32_e32 v132, v132, v112
	v_mul_f32_e32 v133, v133, v112
	v_mul_f32_e32 v134, v134, v112
	v_mul_f32_e32 v135, v135, v112
	v_mul_f32_e32 v132, v0, v132
	v_mul_f32_e32 v133, v1, v133
	v_mul_f32_e32 v134, v2, v134
	v_mul_f32_e32 v135, v3, v135
	global_store_dwordx4 v120, v[132:135], s[6:7] offset:0
	v_mul_f32_e32 v136, v136, v112
	v_mul_f32_e32 v137, v137, v112
	v_mul_f32_e32 v138, v138, v112
	v_mul_f32_e32 v139, v139, v112
	v_mul_f32_e32 v136, v4, v136
	v_mul_f32_e32 v137, v5, v137
	v_mul_f32_e32 v138, v6, v138
	v_mul_f32_e32 v139, v7, v139
	global_store_dwordx4 v120, v[136:139], s[6:7] offset:1024
	v_mul_f32_e32 v140, v140, v112
	v_mul_f32_e32 v141, v141, v112
	v_mul_f32_e32 v142, v142, v112
	v_mul_f32_e32 v143, v143, v112
	v_mul_f32_e32 v140, v8, v140
	v_mul_f32_e32 v141, v9, v141
	v_mul_f32_e32 v142, v10, v142
	v_mul_f32_e32 v143, v11, v143
	global_store_dwordx4 v120, v[140:143], s[6:7] offset:2048
	v_mul_f32_e32 v144, v144, v112
	v_mul_f32_e32 v145, v145, v112
	v_mul_f32_e32 v146, v146, v112
	v_mul_f32_e32 v147, v147, v112
	v_mul_f32_e32 v144, v12, v144
	v_mul_f32_e32 v145, v13, v145
	v_mul_f32_e32 v146, v14, v146
	v_mul_f32_e32 v147, v15, v147
	global_store_dwordx4 v120, v[144:147], s[6:7] offset:3072
	s_add_u32 s6, s6, 0x40000
	s_addc_u32 s7, s7, 0
	v_mul_f32_e32 v166, v166, v113
	v_mul_f32_e32 v167, v167, v113
	v_mul_f32_e32 v168, v168, v113
	v_mul_f32_e32 v169, v169, v113
	v_mul_f32_e32 v166, v0, v166
	v_mul_f32_e32 v167, v1, v167
	v_mul_f32_e32 v168, v2, v168
	v_mul_f32_e32 v169, v3, v169
	global_store_dwordx4 v120, v[166:169], s[6:7] offset:0
	v_mul_f32_e32 v170, v170, v113
	v_mul_f32_e32 v171, v171, v113
	v_mul_f32_e32 v172, v172, v113
	v_mul_f32_e32 v173, v173, v113
	v_mul_f32_e32 v170, v4, v170
	v_mul_f32_e32 v171, v5, v171
	v_mul_f32_e32 v172, v6, v172
	v_mul_f32_e32 v173, v7, v173
	global_store_dwordx4 v120, v[170:173], s[6:7] offset:1024
	v_mul_f32_e32 v174, v174, v113
	v_mul_f32_e32 v175, v175, v113
	v_mul_f32_e32 v176, v176, v113
	v_mul_f32_e32 v177, v177, v113
	v_mul_f32_e32 v174, v8, v174
	v_mul_f32_e32 v175, v9, v175
	v_mul_f32_e32 v176, v10, v176
	v_mul_f32_e32 v177, v11, v177
	global_store_dwordx4 v120, v[174:177], s[6:7] offset:2048
	v_mul_f32_e32 v178, v178, v113
	v_mul_f32_e32 v179, v179, v113
	v_mul_f32_e32 v180, v180, v113
	v_mul_f32_e32 v181, v181, v113
	v_mul_f32_e32 v178, v12, v178
	v_mul_f32_e32 v179, v13, v179
	v_mul_f32_e32 v180, v14, v180
	v_mul_f32_e32 v181, v15, v181
	global_store_dwordx4 v120, v[178:181], s[6:7] offset:3072
	s_add_u32 s6, s6, 0x40000
	s_addc_u32 s7, s7, 0
	v_mul_f32_e32 v182, v182, v114
	v_mul_f32_e32 v183, v183, v114
	v_mul_f32_e32 v184, v184, v114
	v_mul_f32_e32 v185, v185, v114
	v_mul_f32_e32 v182, v0, v182
	v_mul_f32_e32 v183, v1, v183
	v_mul_f32_e32 v184, v2, v184
	v_mul_f32_e32 v185, v3, v185
	global_store_dwordx4 v120, v[182:185], s[6:7] offset:0
	v_mul_f32_e32 v186, v186, v114
	v_mul_f32_e32 v187, v187, v114
	v_mul_f32_e32 v188, v188, v114
	v_mul_f32_e32 v189, v189, v114
	v_mul_f32_e32 v186, v4, v186
	v_mul_f32_e32 v187, v5, v187
	v_mul_f32_e32 v188, v6, v188
	v_mul_f32_e32 v189, v7, v189
	global_store_dwordx4 v120, v[186:189], s[6:7] offset:1024
	v_mul_f32_e32 v190, v190, v114
	v_mul_f32_e32 v191, v191, v114
	v_mul_f32_e32 v192, v192, v114
	v_mul_f32_e32 v193, v193, v114
	v_mul_f32_e32 v190, v8, v190
	v_mul_f32_e32 v191, v9, v191
	v_mul_f32_e32 v192, v10, v192
	v_mul_f32_e32 v193, v11, v193
	global_store_dwordx4 v120, v[190:193], s[6:7] offset:2048
	v_mul_f32_e32 v194, v194, v114
	v_mul_f32_e32 v195, v195, v114
	v_mul_f32_e32 v196, v196, v114
	v_mul_f32_e32 v197, v197, v114
	v_mul_f32_e32 v194, v12, v194
	v_mul_f32_e32 v195, v13, v195
	v_mul_f32_e32 v196, v14, v196
	v_mul_f32_e32 v197, v15, v197
	global_store_dwordx4 v120, v[194:197], s[6:7] offset:3072
	s_add_u32 s6, s6, 0x40000
	s_addc_u32 s7, s7, 0
	v_mul_f32_e32 v228, v228, v115
	v_mul_f32_e32 v229, v229, v115
	v_mul_f32_e32 v230, v230, v115
	v_mul_f32_e32 v231, v231, v115
	v_mul_f32_e32 v228, v0, v228
	v_mul_f32_e32 v229, v1, v229
	v_mul_f32_e32 v230, v2, v230
	v_mul_f32_e32 v231, v3, v231
	global_store_dwordx4 v120, v[228:231], s[6:7] offset:0
	v_mul_f32_e32 v232, v232, v115
	v_mul_f32_e32 v233, v233, v115
	v_mul_f32_e32 v234, v234, v115
	v_mul_f32_e32 v235, v235, v115
	v_mul_f32_e32 v232, v4, v232
	v_mul_f32_e32 v233, v5, v233
	v_mul_f32_e32 v234, v6, v234
	v_mul_f32_e32 v235, v7, v235
	global_store_dwordx4 v120, v[232:235], s[6:7] offset:1024
	v_mul_f32_e32 v236, v236, v115
	v_mul_f32_e32 v237, v237, v115
	v_mul_f32_e32 v238, v238, v115
	v_mul_f32_e32 v239, v239, v115
	v_mul_f32_e32 v236, v8, v236
	v_mul_f32_e32 v237, v9, v237
	v_mul_f32_e32 v238, v10, v238
	v_mul_f32_e32 v239, v11, v239
	global_store_dwordx4 v120, v[236:239], s[6:7] offset:2048
	v_mul_f32_e32 v240, v240, v115
	v_mul_f32_e32 v241, v241, v115
	v_mul_f32_e32 v242, v242, v115
	v_mul_f32_e32 v243, v243, v115
	v_mul_f32_e32 v240, v12, v240
	v_mul_f32_e32 v241, v13, v241
	v_mul_f32_e32 v242, v14, v242
	v_mul_f32_e32 v243, v15, v243
	global_store_dwordx4 v120, v[240:243], s[6:7] offset:3072
	s_add_u32 s6, s6, 0x40000
	s_addc_u32 s7, s7, 0

.LBB0_83:
	v_writelane_b32 v252, s4, 35
	s_and_b64 vcc, exec, s[8:9]
	s_nop 0
	v_writelane_b32 v252, s5, 36
	s_cbranch_vccz .LBB0_90
	v_mov_b32_e32 v0, 0xe0
	v_readlane_b32 s4, v253, 11
	v_add_u32_e32 v0, s91, v0
	ds_read_b64 v[0:1], v0
	s_waitcnt lgkmcnt(0)
	v_readfirstlane_b32 s6, v0
	v_mov_b32_e32 v0, 24
	v_readfirstlane_b32 s7, v1
	v_add_u32_e32 v0, s91, v0
	ds_read_b64 v[0:1], v0
	s_waitcnt lgkmcnt(0)
	v_readfirstlane_b32 s10, v0
	v_mov_b32_e32 v0, 0xe8
	v_readfirstlane_b32 s2, v1
	v_add_u32_e32 v0, s91, v0
	ds_read_b64 v[0:1], v0
	s_waitcnt lgkmcnt(0)
	v_readfirstlane_b32 s9, v1
	v_readfirstlane_b32 s8, v0
	v_mbcnt_lo_u32_b32 v0, -1, 0
	v_mbcnt_hi_u32_b32 v0, -1, v0
	s_nop 0
	v_add_u32_e32 v1, s57, v0
	v_ashrrev_i32_e32 v1, 6, v1
	v_add_u32_e32 v56, s4, v1
	v_cmp_gt_i32_e32 vcc, s3, v56
	s_and_saveexec_b64 s[4:5], vcc
	v_readlane_b32 s14, v252, 23
	s_cbranch_execz .LBB0_89
	v_readfirstlane_b32 s100, v56
	v_readlane_b32 s11, v252, 31
	s_nop 3
	s_lshl_b32 s12, s11, 12
	s_mov_b32 s11, s2
	s_add_u32 s10, s10, s12
	s_addc_u32 s11, s11, 0
	s_add_u32 s8, s8, 0x5200000
	s_addc_u32 s9, s9, 0
	s_nop 3
	v_lshlrev_b32_e32 v120, 4, v0
	v_lshlrev_b32_e32 v121, 3, v0
	v_lshlrev_b32_e32 v122, 2, v214
	v_lshlrev_b32_e32 v123, 2, v215
	v_lshlrev_b32_e32 v124, 2, v216
	v_lshlrev_b32_e32 v125, 2, v217
	v_lshlrev_b32_e32 v126, 2, v218
	v_lshlrev_b32_e32 v127, 2, v219
	s_lshr_b32 s2, s100, 6
	s_lshl_b32 s2, s2, 11
	s_and_b32 s101, s100, 63
	s_add_u32 s2, s2, s101
	s_lshl_b32 s101, s2, 12
	s_add_u32 s6, s6, s101
	s_addc_u32 s7, s7, 0
	s_lshl_b32 s101, s2, 11
	s_add_u32 s8, s8, s101
	s_addc_u32 s9, s9, 0
	global_load_dwordx4 v[0:3], v120, s[10:11] offset:0
	global_load_dwordx4 v[4:7], v120, s[10:11] offset:1024
	global_load_dwordx4 v[8:11], v120, s[10:11] offset:2048
	global_load_dwordx4 v[12:15], v120, s[10:11] offset:3072
	v_readlane_b32 s10, v252, 32
	v_readlane_b32 s11, v252, 33
	s_lshr_b32 s2, s100, 6
	s_mul_i32 s2, s2, 0x6000
	s_nop 3
	s_add_u32 s10, s10, s2
	s_addc_u32 s11, s11, 0
	s_add_u32 s10, s10, 0x4000
	s_addc_u32 s11, s11, 0
	global_load_dwordx4 v[16:19], v120, s[10:11] offset:0
	global_load_dwordx4 v[20:23], v120, s[10:11] offset:1024
	global_load_dwordx4 v[24:27], v120, s[10:11] offset:2048
	global_load_dwordx4 v[28:31], v120, s[10:11] offset:3072
	s_sub_u32 s10, s10, 0x1000
	s_subb_u32 s11, s11, 0
	global_load_dwordx4 v[32:35], v120, s[10:11] offset:0
	global_load_dwordx4 v[36:39], v120, s[10:11] offset:1024
	global_load_dwordx4 v[40:43], v120, s[10:11] offset:2048
	global_load_dwordx4 v[44:47], v120, s[10:11] offset:3072
	s_waitcnt vmcnt(0)
	v_add_f32_e32 v16, 1.0, v16
	v_add_f32_e32 v17, 1.0, v17
	v_add_f32_e32 v18, 1.0, v18
	v_add_f32_e32 v19, 1.0, v19
	v_add_f32_e32 v20, 1.0, v20
	v_add_f32_e32 v21, 1.0, v21
	v_add_f32_e32 v22, 1.0, v22
	v_add_f32_e32 v23, 1.0, v23
	v_add_f32_e32 v24, 1.0, v24
	v_add_f32_e32 v25, 1.0, v25
	v_add_f32_e32 v26, 1.0, v26
	v_add_f32_e32 v27, 1.0, v27
	v_add_f32_e32 v28, 1.0, v28
	v_add_f32_e32 v29, 1.0, v29
	v_add_f32_e32 v30, 1.0, v30
	v_add_f32_e32 v31, 1.0, v31
	s_movk_i32 s2, 3
	global_load_dwordx4 v[48:51], v120, s[6:7] offset:0 nt
	global_load_dwordx4 v[52:55], v120, s[6:7] offset:1024 nt
	global_load_dwordx4 v[56:59], v120, s[6:7] offset:2048 nt
	global_load_dwordx4 v[60:63], v120, s[6:7] offset:3072 nt
	s_add_u32 s6, s6, 0x40000
	s_addc_u32 s7, s7, 0
	global_load_dwordx4 v[64:67], v120, s[6:7] offset:0 nt
	global_load_dwordx4 v[68:71], v120, s[6:7] offset:1024 nt
	global_load_dwordx4 v[72:75], v120, s[6:7] offset:2048 nt
	global_load_dwordx4 v[76:79], v120, s[6:7] offset:3072 nt
	s_add_u32 s6, s6, 0x40000
	s_addc_u32 s7, s7, 0
	global_load_dwordx4 v[80:83], v120, s[6:7] offset:0 nt
	global_load_dwordx4 v[84:87], v120, s[6:7] offset:1024 nt
	global_load_dwordx4 v[88:91], v120, s[6:7] offset:2048 nt
	global_load_dwordx4 v[92:95], v120, s[6:7] offset:3072 nt
	s_add_u32 s6, s6, 0x40000
	s_addc_u32 s7, s7, 0
	global_load_dwordx4 v[96:99], v120, s[6:7] offset:0 nt
	global_load_dwordx4 v[100:103], v120, s[6:7] offset:1024 nt
	global_load_dwordx4 v[104:107], v120, s[6:7] offset:2048 nt
	global_load_dwordx4 v[108:111], v120, s[6:7] offset:3072 nt
	s_add_u32 s6, s6, 0x40000
	s_addc_u32 s7, s7, 0
	global_load_dwordx4 v[132:135], v120, s[6:7] offset:0 nt
	global_load_dwordx4 v[136:139], v120, s[6:7] offset:1024 nt
	global_load_dwordx4 v[140:143], v120, s[6:7] offset:2048 nt
	global_load_dwordx4 v[144:147], v120, s[6:7] offset:3072 nt
	s_add_u32 s6, s6, 0x40000
	s_addc_u32 s7, s7, 0
	global_load_dwordx4 v[166:169], v120, s[6:7] offset:0 nt
	global_load_dwordx4 v[170:173], v120, s[6:7] offset:1024 nt
	global_load_dwordx4 v[174:177], v120, s[6:7] offset:2048 nt
	global_load_dwordx4 v[178:181], v120, s[6:7] offset:3072 nt
	s_add_u32 s6, s6, 0x40000
	s_addc_u32 s7, s7, 0
	global_load_dwordx4 v[182:185], v120, s[6:7] offset:0 nt
	global_load_dwordx4 v[186:189], v120, s[6:7] offset:1024 nt
	global_load_dwordx4 v[190:193], v120, s[6:7] offset:2048 nt
	global_load_dwordx4 v[194:197], v120, s[6:7] offset:3072 nt
	s_add_u32 s6, s6, 0x40000
	s_addc_u32 s7, s7, 0
	global_load_dwordx4 v[228:231], v120, s[6:7] offset:0 nt
	global_load_dwordx4 v[232:235], v120, s[6:7] offset:1024 nt
	global_load_dwordx4 v[236:239], v120, s[6:7] offset:2048 nt
	global_load_dwordx4 v[240:243], v120, s[6:7] offset:3072 nt
	s_add_u32 s6, s6, 0x40000
	s_addc_u32 s7, s7, 0
	s_waitcnt vmcnt(28)
	v_mul_f32_e32 v112, v48, v48
	v_fmac_f32_e32 v112, v49, v49
	v_fmac_f32_e32 v112, v50, v50
	v_fmac_f32_e32 v112, v51, v51
	v_fmac_f32_e32 v112, v52, v52
	v_fmac_f32_e32 v112, v53, v53
	v_fmac_f32_e32 v112, v54, v54
	v_fmac_f32_e32 v112, v55, v55
	v_fmac_f32_e32 v112, v56, v56
	v_fmac_f32_e32 v112, v57, v57
	v_fmac_f32_e32 v112, v58, v58
	v_fmac_f32_e32 v112, v59, v59
	v_fmac_f32_e32 v112, v60, v60
	v_fmac_f32_e32 v112, v61, v61
	v_fmac_f32_e32 v112, v62, v62
	v_fmac_f32_e32 v112, v63, v63
	s_waitcnt vmcnt(24)
	v_mul_f32_e32 v113, v64, v64
	v_fmac_f32_e32 v113, v65, v65
	v_fmac_f32_e32 v113, v66, v66
	v_fmac_f32_e32 v113, v67, v67
	v_fmac_f32_e32 v113, v68, v68
	v_fmac_f32_e32 v113, v69, v69
	v_fmac_f32_e32 v113, v70, v70
	v_fmac_f32_e32 v113, v71, v71
	v_fmac_f32_e32 v113, v72, v72
	v_fmac_f32_e32 v113, v73, v73
	v_fmac_f32_e32 v113, v74, v74
	v_fmac_f32_e32 v113, v75, v75
	v_fmac_f32_e32 v113, v76, v76
	v_fmac_f32_e32 v113, v77, v77
	v_fmac_f32_e32 v113, v78, v78
	v_fmac_f32_e32 v113, v79, v79
	s_waitcnt vmcnt(20)
	v_mul_f32_e32 v114, v80, v80
	v_fmac_f32_e32 v114, v81, v81
	v_fmac_f32_e32 v114, v82, v82
	v_fmac_f32_e32 v114, v83, v83
	v_fmac_f32_e32 v114, v84, v84
	v_fmac_f32_e32 v114, v85, v85
	v_fmac_f32_e32 v114, v86, v86
	v_fmac_f32_e32 v114, v87, v87
	v_fmac_f32_e32 v114, v88, v88
	v_fmac_f32_e32 v114, v89, v89
	v_fmac_f32_e32 v114, v90, v90
	v_fmac_f32_e32 v114, v91, v91
	v_fmac_f32_e32 v114, v92, v92
	v_fmac_f32_e32 v114, v93, v93
	v_fmac_f32_e32 v114, v94, v94
	v_fmac_f32_e32 v114, v95, v95
	s_waitcnt vmcnt(16)
	v_mul_f32_e32 v115, v96, v96
	v_fmac_f32_e32 v115, v97, v97
	v_fmac_f32_e32 v115, v98, v98
	v_fmac_f32_e32 v115, v99, v99
	v_fmac_f32_e32 v115, v100, v100
	v_fmac_f32_e32 v115, v101, v101
	v_fmac_f32_e32 v115, v102, v102
	v_fmac_f32_e32 v115, v103, v103
	v_fmac_f32_e32 v115, v104, v104
	v_fmac_f32_e32 v115, v105, v105
	v_fmac_f32_e32 v115, v106, v106
	v_fmac_f32_e32 v115, v107, v107
	v_fmac_f32_e32 v115, v108, v108
	v_fmac_f32_e32 v115, v109, v109
	v_fmac_f32_e32 v115, v110, v110
	v_fmac_f32_e32 v115, v111, v111
	ds_bpermute_b32 v116, v122, v112
	ds_bpermute_b32 v117, v122, v113
	ds_bpermute_b32 v118, v122, v114
	ds_bpermute_b32 v119, v122, v115
	s_waitcnt lgkmcnt(0)
	v_add_f32_e32 v112, v112, v116
	v_add_f32_e32 v113, v113, v117
	v_add_f32_e32 v114, v114, v118
	v_add_f32_e32 v115, v115, v119
	ds_bpermute_b32 v116, v123, v112
	ds_bpermute_b32 v117, v123, v113
	ds_bpermute_b32 v118, v123, v114
	ds_bpermute_b32 v119, v123, v115
	s_waitcnt lgkmcnt(0)
	v_add_f32_e32 v112, v112, v116
	v_add_f32_e32 v113, v113, v117
	v_add_f32_e32 v114, v114, v118
	v_add_f32_e32 v115, v115, v119
	ds_bpermute_b32 v116, v124, v112
	ds_bpermute_b32 v117, v124, v113
	ds_bpermute_b32 v118, v124, v114
	ds_bpermute_b32 v119, v124, v115
	s_waitcnt lgkmcnt(0)
	v_add_f32_e32 v112, v112, v116
	v_add_f32_e32 v113, v113, v117
	v_add_f32_e32 v114, v114, v118
	v_add_f32_e32 v115, v115, v119
	ds_bpermute_b32 v116, v125, v112
	ds_bpermute_b32 v117, v125, v113
	ds_bpermute_b32 v118, v125, v114
	ds_bpermute_b32 v119, v125, v115
	s_waitcnt lgkmcnt(0)
	v_add_f32_e32 v112, v112, v116
	v_add_f32_e32 v113, v113, v117
	v_add_f32_e32 v114, v114, v118
	v_add_f32_e32 v115, v115, v119
	ds_bpermute_b32 v116, v126, v112
	ds_bpermute_b32 v117, v126, v113
	ds_bpermute_b32 v118, v126, v114
	ds_bpermute_b32 v119, v126, v115
	s_waitcnt lgkmcnt(0)
	v_add_f32_e32 v112, v112, v116
	v_add_f32_e32 v113, v113, v117
	v_add_f32_e32 v114, v114, v118
	v_add_f32_e32 v115, v115, v119
	ds_bpermute_b32 v116, v127, v112
	ds_bpermute_b32 v117, v127, v113
	ds_bpermute_b32 v118, v127, v114
	ds_bpermute_b32 v119, v127, v115
	s_waitcnt lgkmcnt(0)
	v_add_f32_e32 v112, v112, v116
	v_add_f32_e32 v113, v113, v117
	v_add_f32_e32 v114, v114, v118
	v_add_f32_e32 v115, v115, v119
	v_fmamk_f32 v112, v112, 0x3a800000, v208
	v_fmamk_f32 v113, v113, 0x3a800000, v208
	v_fmamk_f32 v114, v114, 0x3a800000, v208
	v_fmamk_f32 v115, v115, 0x3a800000, v208
	v_rsq_f32_e32 v112, v112
	v_rsq_f32_e32 v113, v113
	v_rsq_f32_e32 v114, v114
	v_rsq_f32_e32 v115, v115
	s_nop 1
	v_mul_f32_e32 v48, v48, v112
	v_mul_f32_e32 v49, v49, v112
	v_mul_f32_e32 v50, v50, v112
	v_mul_f32_e32 v51, v51, v112
	v_mul_f32_e32 v48, v0, v48
	v_mul_f32_e32 v49, v1, v49
	v_mul_f32_e32 v50, v2, v50
	v_mul_f32_e32 v51, v3, v51
	v_fma_f32 v48, v48, v16, v32
	v_fma_f32 v49, v49, v17, v33
	v_fma_f32 v50, v50, v18, v34
	v_fma_f32 v51, v51, v19, v35
	v_cvt_pk_bf16_f32 v128, v48, v49
	v_cvt_pk_bf16_f32 v129, v50, v51
	global_store_dwordx2 v121, v[128:129], s[8:9] offset:0
	v_mul_f32_e32 v52, v52, v112
	v_mul_f32_e32 v53, v53, v112
	v_mul_f32_e32 v54, v54, v112
	v_mul_f32_e32 v55, v55, v112
	v_mul_f32_e32 v52, v4, v52
	v_mul_f32_e32 v53, v5, v53
	v_mul_f32_e32 v54, v6, v54
	v_mul_f32_e32 v55, v7, v55
	v_fma_f32 v52, v52, v20, v36
	v_fma_f32 v53, v53, v21, v37
	v_fma_f32 v54, v54, v22, v38
	v_fma_f32 v55, v55, v23, v39
	v_cvt_pk_bf16_f32 v130, v52, v53
	v_cvt_pk_bf16_f32 v131, v54, v55
	global_store_dwordx2 v121, v[130:131], s[8:9] offset:512
	v_mul_f32_e32 v56, v56, v112
	v_mul_f32_e32 v57, v57, v112
	v_mul_f32_e32 v58, v58, v112
	v_mul_f32_e32 v59, v59, v112
	v_mul_f32_e32 v56, v8, v56
	v_mul_f32_e32 v57, v9, v57
	v_mul_f32_e32 v58, v10, v58
	v_mul_f32_e32 v59, v11, v59
	v_fma_f32 v56, v56, v24, v40
	v_fma_f32 v57, v57, v25, v41
	v_fma_f32 v58, v58, v26, v42
	v_fma_f32 v59, v59, v27, v43
	v_cvt_pk_bf16_f32 v128, v56, v57
	v_cvt_pk_bf16_f32 v129, v58, v59
	global_store_dwordx2 v121, v[128:129], s[8:9] offset:1024
	v_mul_f32_e32 v60, v60, v112
	v_mul_f32_e32 v61, v61, v112
	v_mul_f32_e32 v62, v62, v112
	v_mul_f32_e32 v63, v63, v112
	v_mul_f32_e32 v60, v12, v60
	v_mul_f32_e32 v61, v13, v61
	v_mul_f32_e32 v62, v14, v62
	v_mul_f32_e32 v63, v15, v63
	v_fma_f32 v60, v60, v28, v44
	v_fma_f32 v61, v61, v29, v45
	v_fma_f32 v62, v62, v30, v46
	v_fma_f32 v63, v63, v31, v47
	v_cvt_pk_bf16_f32 v130, v60, v61
	v_cvt_pk_bf16_f32 v131, v62, v63
	global_store_dwordx2 v121, v[130:131], s[8:9] offset:1536
	s_add_u32 s8, s8, 0x20000
	s_addc_u32 s9, s9, 0
	v_mul_f32_e32 v64, v64, v113
	v_mul_f32_e32 v65, v65, v113
	v_mul_f32_e32 v66, v66, v113
	v_mul_f32_e32 v67, v67, v113
	v_mul_f32_e32 v64, v0, v64
	v_mul_f32_e32 v65, v1, v65
	v_mul_f32_e32 v66, v2, v66
	v_mul_f32_e32 v67, v3, v67
	v_fma_f32 v64, v64, v16, v32
	v_fma_f32 v65, v65, v17, v33
	v_fma_f32 v66, v66, v18, v34
	v_fma_f32 v67, v67, v19, v35
	v_cvt_pk_bf16_f32 v128, v64, v65
	v_cvt_pk_bf16_f32 v129, v66, v67
	global_store_dwordx2 v121, v[128:129], s[8:9] offset:0
	v_mul_f32_e32 v68, v68, v113
	v_mul_f32_e32 v69, v69, v113
	v_mul_f32_e32 v70, v70, v113
	v_mul_f32_e32 v71, v71, v113
	v_mul_f32_e32 v68, v4, v68
	v_mul_f32_e32 v69, v5, v69
	v_mul_f32_e32 v70, v6, v70
	v_mul_f32_e32 v71, v7, v71
	v_fma_f32 v68, v68, v20, v36
	v_fma_f32 v69, v69, v21, v37
	v_fma_f32 v70, v70, v22, v38
	v_fma_f32 v71, v71, v23, v39
	v_cvt_pk_bf16_f32 v130, v68, v69
	v_cvt_pk_bf16_f32 v131, v70, v71
	global_store_dwordx2 v121, v[130:131], s[8:9] offset:512
	v_mul_f32_e32 v72, v72, v113
	v_mul_f32_e32 v73, v73, v113
	v_mul_f32_e32 v74, v74, v113
	v_mul_f32_e32 v75, v75, v113
	v_mul_f32_e32 v72, v8, v72
	v_mul_f32_e32 v73, v9, v73
	v_mul_f32_e32 v74, v10, v74
	v_mul_f32_e32 v75, v11, v75
	v_fma_f32 v72, v72, v24, v40
	v_fma_f32 v73, v73, v25, v41
	v_fma_f32 v74, v74, v26, v42
	v_fma_f32 v75, v75, v27, v43
	v_cvt_pk_bf16_f32 v128, v72, v73
	v_cvt_pk_bf16_f32 v129, v74, v75
	global_store_dwordx2 v121, v[128:129], s[8:9] offset:1024
	v_mul_f32_e32 v76, v76, v113
	v_mul_f32_e32 v77, v77, v113
	v_mul_f32_e32 v78, v78, v113
	v_mul_f32_e32 v79, v79, v113
	v_mul_f32_e32 v76, v12, v76
	v_mul_f32_e32 v77, v13, v77
	v_mul_f32_e32 v78, v14, v78
	v_mul_f32_e32 v79, v15, v79
	v_fma_f32 v76, v76, v28, v44
	v_fma_f32 v77, v77, v29, v45
	v_fma_f32 v78, v78, v30, v46
	v_fma_f32 v79, v79, v31, v47
	v_cvt_pk_bf16_f32 v130, v76, v77
	v_cvt_pk_bf16_f32 v131, v78, v79
	global_store_dwordx2 v121, v[130:131], s[8:9] offset:1536
	s_add_u32 s8, s8, 0x20000
	s_addc_u32 s9, s9, 0
	v_mul_f32_e32 v80, v80, v114
	v_mul_f32_e32 v81, v81, v114
	v_mul_f32_e32 v82, v82, v114
	v_mul_f32_e32 v83, v83, v114
	v_mul_f32_e32 v80, v0, v80
	v_mul_f32_e32 v81, v1, v81
	v_mul_f32_e32 v82, v2, v82
	v_mul_f32_e32 v83, v3, v83
	v_fma_f32 v80, v80, v16, v32
	v_fma_f32 v81, v81, v17, v33
	v_fma_f32 v82, v82, v18, v34
	v_fma_f32 v83, v83, v19, v35
	v_cvt_pk_bf16_f32 v128, v80, v81
	v_cvt_pk_bf16_f32 v129, v82, v83
	global_store_dwordx2 v121, v[128:129], s[8:9] offset:0
	v_mul_f32_e32 v84, v84, v114
	v_mul_f32_e32 v85, v85, v114
	v_mul_f32_e32 v86, v86, v114
	v_mul_f32_e32 v87, v87, v114
	v_mul_f32_e32 v84, v4, v84
	v_mul_f32_e32 v85, v5, v85
	v_mul_f32_e32 v86, v6, v86
	v_mul_f32_e32 v87, v7, v87
	v_fma_f32 v84, v84, v20, v36
	v_fma_f32 v85, v85, v21, v37
	v_fma_f32 v86, v86, v22, v38
	v_fma_f32 v87, v87, v23, v39
	v_cvt_pk_bf16_f32 v130, v84, v85
	v_cvt_pk_bf16_f32 v131, v86, v87
	global_store_dwordx2 v121, v[130:131], s[8:9] offset:512
	v_mul_f32_e32 v88, v88, v114
	v_mul_f32_e32 v89, v89, v114
	v_mul_f32_e32 v90, v90, v114
	v_mul_f32_e32 v91, v91, v114
	v_mul_f32_e32 v88, v8, v88
	v_mul_f32_e32 v89, v9, v89
	v_mul_f32_e32 v90, v10, v90
	v_mul_f32_e32 v91, v11, v91
	v_fma_f32 v88, v88, v24, v40
	v_fma_f32 v89, v89, v25, v41
	v_fma_f32 v90, v90, v26, v42
	v_fma_f32 v91, v91, v27, v43
	v_cvt_pk_bf16_f32 v128, v88, v89
	v_cvt_pk_bf16_f32 v129, v90, v91
	global_store_dwordx2 v121, v[128:129], s[8:9] offset:1024
	v_mul_f32_e32 v92, v92, v114
	v_mul_f32_e32 v93, v93, v114
	v_mul_f32_e32 v94, v94, v114
	v_mul_f32_e32 v95, v95, v114
	v_mul_f32_e32 v92, v12, v92
	v_mul_f32_e32 v93, v13, v93
	v_mul_f32_e32 v94, v14, v94
	v_mul_f32_e32 v95, v15, v95
	v_fma_f32 v92, v92, v28, v44
	v_fma_f32 v93, v93, v29, v45
	v_fma_f32 v94, v94, v30, v46
	v_fma_f32 v95, v95, v31, v47
	v_cvt_pk_bf16_f32 v130, v92, v93
	v_cvt_pk_bf16_f32 v131, v94, v95
	global_store_dwordx2 v121, v[130:131], s[8:9] offset:1536
	s_add_u32 s8, s8, 0x20000
	s_addc_u32 s9, s9, 0
	v_mul_f32_e32 v96, v96, v115
	v_mul_f32_e32 v97, v97, v115
	v_mul_f32_e32 v98, v98, v115
	v_mul_f32_e32 v99, v99, v115
	v_mul_f32_e32 v96, v0, v96
	v_mul_f32_e32 v97, v1, v97
	v_mul_f32_e32 v98, v2, v98
	v_mul_f32_e32 v99, v3, v99
	v_fma_f32 v96, v96, v16, v32
	v_fma_f32 v97, v97, v17, v33
	v_fma_f32 v98, v98, v18, v34
	v_fma_f32 v99, v99, v19, v35
	v_cvt_pk_bf16_f32 v128, v96, v97
	v_cvt_pk_bf16_f32 v129, v98, v99
	global_store_dwordx2 v121, v[128:129], s[8:9] offset:0
	v_mul_f32_e32 v100, v100, v115
	v_mul_f32_e32 v101, v101, v115
	v_mul_f32_e32 v102, v102, v115
	v_mul_f32_e32 v103, v103, v115
	v_mul_f32_e32 v100, v4, v100
	v_mul_f32_e32 v101, v5, v101
	v_mul_f32_e32 v102, v6, v102
	v_mul_f32_e32 v103, v7, v103
	v_fma_f32 v100, v100, v20, v36
	v_fma_f32 v101, v101, v21, v37
	v_fma_f32 v102, v102, v22, v38
	v_fma_f32 v103, v103, v23, v39
	v_cvt_pk_bf16_f32 v130, v100, v101
	v_cvt_pk_bf16_f32 v131, v102, v103
	global_store_dwordx2 v121, v[130:131], s[8:9] offset:512
	v_mul_f32_e32 v104, v104, v115
	v_mul_f32_e32 v105, v105, v115
	v_mul_f32_e32 v106, v106, v115
	v_mul_f32_e32 v107, v107, v115
	v_mul_f32_e32 v104, v8, v104
	v_mul_f32_e32 v105, v9, v105
	v_mul_f32_e32 v106, v10, v106
	v_mul_f32_e32 v107, v11, v107
	v_fma_f32 v104, v104, v24, v40
	v_fma_f32 v105, v105, v25, v41
	v_fma_f32 v106, v106, v26, v42
	v_fma_f32 v107, v107, v27, v43
	v_cvt_pk_bf16_f32 v128, v104, v105
	v_cvt_pk_bf16_f32 v129, v106, v107
	global_store_dwordx2 v121, v[128:129], s[8:9] offset:1024
	v_mul_f32_e32 v108, v108, v115
	v_mul_f32_e32 v109, v109, v115
	v_mul_f32_e32 v110, v110, v115
	v_mul_f32_e32 v111, v111, v115
	v_mul_f32_e32 v108, v12, v108
	v_mul_f32_e32 v109, v13, v109
	v_mul_f32_e32 v110, v14, v110
	v_mul_f32_e32 v111, v15, v111
	v_fma_f32 v108, v108, v28, v44
	v_fma_f32 v109, v109, v29, v45
	v_fma_f32 v110, v110, v30, v46
	v_fma_f32 v111, v111, v31, v47
	v_cvt_pk_bf16_f32 v130, v108, v109
	v_cvt_pk_bf16_f32 v131, v110, v111
	global_store_dwordx2 v121, v[130:131], s[8:9] offset:1536
	s_add_u32 s8, s8, 0x20000
	s_addc_u32 s9, s9, 0
.Lrms_sub6_loop:
	global_load_dwordx4 v[48:51], v120, s[6:7] offset:0 nt
	global_load_dwordx4 v[52:55], v120, s[6:7] offset:1024 nt
	global_load_dwordx4 v[56:59], v120, s[6:7] offset:2048 nt
	global_load_dwordx4 v[60:63], v120, s[6:7] offset:3072 nt
	s_add_u32 s6, s6, 0x40000
	s_addc_u32 s7, s7, 0
	global_load_dwordx4 v[64:67], v120, s[6:7] offset:0 nt
	global_load_dwordx4 v[68:71], v120, s[6:7] offset:1024 nt
	global_load_dwordx4 v[72:75], v120, s[6:7] offset:2048 nt
	global_load_dwordx4 v[76:79], v120, s[6:7] offset:3072 nt
	s_add_u32 s6, s6, 0x40000
	s_addc_u32 s7, s7, 0
	global_load_dwordx4 v[80:83], v120, s[6:7] offset:0 nt
	global_load_dwordx4 v[84:87], v120, s[6:7] offset:1024 nt
	global_load_dwordx4 v[88:91], v120, s[6:7] offset:2048 nt
	global_load_dwordx4 v[92:95], v120, s[6:7] offset:3072 nt
	s_add_u32 s6, s6, 0x40000
	s_addc_u32 s7, s7, 0
	global_load_dwordx4 v[96:99], v120, s[6:7] offset:0 nt
	global_load_dwordx4 v[100:103], v120, s[6:7] offset:1024 nt
	global_load_dwordx4 v[104:107], v120, s[6:7] offset:2048 nt
	global_load_dwordx4 v[108:111], v120, s[6:7] offset:3072 nt
	s_add_u32 s6, s6, 0x40000
	s_addc_u32 s7, s7, 0
	s_waitcnt vmcnt(44)
	v_mul_f32_e32 v112, v132, v132
	v_fmac_f32_e32 v112, v133, v133
	v_fmac_f32_e32 v112, v134, v134
	v_fmac_f32_e32 v112, v135, v135
	v_fmac_f32_e32 v112, v136, v136
	v_fmac_f32_e32 v112, v137, v137
	v_fmac_f32_e32 v112, v138, v138
	v_fmac_f32_e32 v112, v139, v139
	v_fmac_f32_e32 v112, v140, v140
	v_fmac_f32_e32 v112, v141, v141
	v_fmac_f32_e32 v112, v142, v142
	v_fmac_f32_e32 v112, v143, v143
	v_fmac_f32_e32 v112, v144, v144
	v_fmac_f32_e32 v112, v145, v145
	v_fmac_f32_e32 v112, v146, v146
	v_fmac_f32_e32 v112, v147, v147
	s_waitcnt vmcnt(40)
	v_mul_f32_e32 v113, v166, v166
	v_fmac_f32_e32 v113, v167, v167
	v_fmac_f32_e32 v113, v168, v168
	v_fmac_f32_e32 v113, v169, v169
	v_fmac_f32_e32 v113, v170, v170
	v_fmac_f32_e32 v113, v171, v171
	v_fmac_f32_e32 v113, v172, v172
	v_fmac_f32_e32 v113, v173, v173
	v_fmac_f32_e32 v113, v174, v174
	v_fmac_f32_e32 v113, v175, v175
	v_fmac_f32_e32 v113, v176, v176
	v_fmac_f32_e32 v113, v177, v177
	v_fmac_f32_e32 v113, v178, v178
	v_fmac_f32_e32 v113, v179, v179
	v_fmac_f32_e32 v113, v180, v180
	v_fmac_f32_e32 v113, v181, v181
	s_waitcnt vmcnt(36)
	v_mul_f32_e32 v114, v182, v182
	v_fmac_f32_e32 v114, v183, v183
	v_fmac_f32_e32 v114, v184, v184
	v_fmac_f32_e32 v114, v185, v185
	v_fmac_f32_e32 v114, v186, v186
	v_fmac_f32_e32 v114, v187, v187
	v_fmac_f32_e32 v114, v188, v188
	v_fmac_f32_e32 v114, v189, v189
	v_fmac_f32_e32 v114, v190, v190
	v_fmac_f32_e32 v114, v191, v191
	v_fmac_f32_e32 v114, v192, v192
	v_fmac_f32_e32 v114, v193, v193
	v_fmac_f32_e32 v114, v194, v194
	v_fmac_f32_e32 v114, v195, v195
	v_fmac_f32_e32 v114, v196, v196
	v_fmac_f32_e32 v114, v197, v197
	s_waitcnt vmcnt(32)
	v_mul_f32_e32 v115, v228, v228
	v_fmac_f32_e32 v115, v229, v229
	v_fmac_f32_e32 v115, v230, v230
	v_fmac_f32_e32 v115, v231, v231
	v_fmac_f32_e32 v115, v232, v232
	v_fmac_f32_e32 v115, v233, v233
	v_fmac_f32_e32 v115, v234, v234
	v_fmac_f32_e32 v115, v235, v235
	v_fmac_f32_e32 v115, v236, v236
	v_fmac_f32_e32 v115, v237, v237
	v_fmac_f32_e32 v115, v238, v238
	v_fmac_f32_e32 v115, v239, v239
	v_fmac_f32_e32 v115, v240, v240
	v_fmac_f32_e32 v115, v241, v241
	v_fmac_f32_e32 v115, v242, v242
	v_fmac_f32_e32 v115, v243, v243
	ds_bpermute_b32 v116, v122, v112
	ds_bpermute_b32 v117, v122, v113
	ds_bpermute_b32 v118, v122, v114
	ds_bpermute_b32 v119, v122, v115
	s_waitcnt lgkmcnt(0)
	v_add_f32_e32 v112, v112, v116
	v_add_f32_e32 v113, v113, v117
	v_add_f32_e32 v114, v114, v118
	v_add_f32_e32 v115, v115, v119
	ds_bpermute_b32 v116, v123, v112
	ds_bpermute_b32 v117, v123, v113
	ds_bpermute_b32 v118, v123, v114
	ds_bpermute_b32 v119, v123, v115
	s_waitcnt lgkmcnt(0)
	v_add_f32_e32 v112, v112, v116
	v_add_f32_e32 v113, v113, v117
	v_add_f32_e32 v114, v114, v118
	v_add_f32_e32 v115, v115, v119
	ds_bpermute_b32 v116, v124, v112
	ds_bpermute_b32 v117, v124, v113
	ds_bpermute_b32 v118, v124, v114
	ds_bpermute_b32 v119, v124, v115
	s_waitcnt lgkmcnt(0)
	v_add_f32_e32 v112, v112, v116
	v_add_f32_e32 v113, v113, v117
	v_add_f32_e32 v114, v114, v118
	v_add_f32_e32 v115, v115, v119
	ds_bpermute_b32 v116, v125, v112
	ds_bpermute_b32 v117, v125, v113
	ds_bpermute_b32 v118, v125, v114
	ds_bpermute_b32 v119, v125, v115
	s_waitcnt lgkmcnt(0)
	v_add_f32_e32 v112, v112, v116
	v_add_f32_e32 v113, v113, v117
	v_add_f32_e32 v114, v114, v118
	v_add_f32_e32 v115, v115, v119
	ds_bpermute_b32 v116, v126, v112
	ds_bpermute_b32 v117, v126, v113
	ds_bpermute_b32 v118, v126, v114
	ds_bpermute_b32 v119, v126, v115
	s_waitcnt lgkmcnt(0)
	v_add_f32_e32 v112, v112, v116
	v_add_f32_e32 v113, v113, v117
	v_add_f32_e32 v114, v114, v118
	v_add_f32_e32 v115, v115, v119
	ds_bpermute_b32 v116, v127, v112
	ds_bpermute_b32 v117, v127, v113
	ds_bpermute_b32 v118, v127, v114
	ds_bpermute_b32 v119, v127, v115
	s_waitcnt lgkmcnt(0)
	v_add_f32_e32 v112, v112, v116
	v_add_f32_e32 v113, v113, v117
	v_add_f32_e32 v114, v114, v118
	v_add_f32_e32 v115, v115, v119
	v_fmamk_f32 v112, v112, 0x3a800000, v208
	v_fmamk_f32 v113, v113, 0x3a800000, v208
	v_fmamk_f32 v114, v114, 0x3a800000, v208
	v_fmamk_f32 v115, v115, 0x3a800000, v208
	v_rsq_f32_e32 v112, v112
	v_rsq_f32_e32 v113, v113
	v_rsq_f32_e32 v114, v114
	v_rsq_f32_e32 v115, v115
	s_nop 1
	v_mul_f32_e32 v132, v132, v112
	v_mul_f32_e32 v133, v133, v112
	v_mul_f32_e32 v134, v134, v112
	v_mul_f32_e32 v135, v135, v112
	v_mul_f32_e32 v132, v0, v132
	v_mul_f32_e32 v133, v1, v133
	v_mul_f32_e32 v134, v2, v134
	v_mul_f32_e32 v135, v3, v135
	v_fma_f32 v132, v132, v16, v32
	v_fma_f32 v133, v133, v17, v33
	v_fma_f32 v134, v134, v18, v34
	v_fma_f32 v135, v135, v19, v35
	v_cvt_pk_bf16_f32 v128, v132, v133
	v_cvt_pk_bf16_f32 v129, v134, v135
	global_store_dwordx2 v121, v[128:129], s[8:9] offset:0
	v_mul_f32_e32 v136, v136, v112
	v_mul_f32_e32 v137, v137, v112
	v_mul_f32_e32 v138, v138, v112
	v_mul_f32_e32 v139, v139, v112
	v_mul_f32_e32 v136, v4, v136
	v_mul_f32_e32 v137, v5, v137
	v_mul_f32_e32 v138, v6, v138
	v_mul_f32_e32 v139, v7, v139
	v_fma_f32 v136, v136, v20, v36
	v_fma_f32 v137, v137, v21, v37
	v_fma_f32 v138, v138, v22, v38
	v_fma_f32 v139, v139, v23, v39
	v_cvt_pk_bf16_f32 v130, v136, v137
	v_cvt_pk_bf16_f32 v131, v138, v139
	global_store_dwordx2 v121, v[130:131], s[8:9] offset:512
	v_mul_f32_e32 v140, v140, v112
	v_mul_f32_e32 v141, v141, v112
	v_mul_f32_e32 v142, v142, v112
	v_mul_f32_e32 v143, v143, v112
	v_mul_f32_e32 v140, v8, v140
	v_mul_f32_e32 v141, v9, v141
	v_mul_f32_e32 v142, v10, v142
	v_mul_f32_e32 v143, v11, v143
	v_fma_f32 v140, v140, v24, v40
	v_fma_f32 v141, v141, v25, v41
	v_fma_f32 v142, v142, v26, v42
	v_fma_f32 v143, v143, v27, v43
	v_cvt_pk_bf16_f32 v128, v140, v141
	v_cvt_pk_bf16_f32 v129, v142, v143
	global_store_dwordx2 v121, v[128:129], s[8:9] offset:1024
	v_mul_f32_e32 v144, v144, v112
	v_mul_f32_e32 v145, v145, v112
	v_mul_f32_e32 v146, v146, v112
	v_mul_f32_e32 v147, v147, v112
	v_mul_f32_e32 v144, v12, v144
	v_mul_f32_e32 v145, v13, v145
	v_mul_f32_e32 v146, v14, v146
	v_mul_f32_e32 v147, v15, v147
	v_fma_f32 v144, v144, v28, v44
	v_fma_f32 v145, v145, v29, v45
	v_fma_f32 v146, v146, v30, v46
	v_fma_f32 v147, v147, v31, v47
	v_cvt_pk_bf16_f32 v130, v144, v145
	v_cvt_pk_bf16_f32 v131, v146, v147
	global_store_dwordx2 v121, v[130:131], s[8:9] offset:1536
	s_add_u32 s8, s8, 0x20000
	s_addc_u32 s9, s9, 0
	v_mul_f32_e32 v166, v166, v113
	v_mul_f32_e32 v167, v167, v113
	v_mul_f32_e32 v168, v168, v113
	v_mul_f32_e32 v169, v169, v113
	v_mul_f32_e32 v166, v0, v166
	v_mul_f32_e32 v167, v1, v167
	v_mul_f32_e32 v168, v2, v168
	v_mul_f32_e32 v169, v3, v169
	v_fma_f32 v166, v166, v16, v32
	v_fma_f32 v167, v167, v17, v33
	v_fma_f32 v168, v168, v18, v34
	v_fma_f32 v169, v169, v19, v35
	v_cvt_pk_bf16_f32 v128, v166, v167
	v_cvt_pk_bf16_f32 v129, v168, v169
	global_store_dwordx2 v121, v[128:129], s[8:9] offset:0
	v_mul_f32_e32 v170, v170, v113
	v_mul_f32_e32 v171, v171, v113
	v_mul_f32_e32 v172, v172, v113
	v_mul_f32_e32 v173, v173, v113
	v_mul_f32_e32 v170, v4, v170
	v_mul_f32_e32 v171, v5, v171
	v_mul_f32_e32 v172, v6, v172
	v_mul_f32_e32 v173, v7, v173
	v_fma_f32 v170, v170, v20, v36
	v_fma_f32 v171, v171, v21, v37
	v_fma_f32 v172, v172, v22, v38
	v_fma_f32 v173, v173, v23, v39
	v_cvt_pk_bf16_f32 v130, v170, v171
	v_cvt_pk_bf16_f32 v131, v172, v173
	global_store_dwordx2 v121, v[130:131], s[8:9] offset:512
	v_mul_f32_e32 v174, v174, v113
	v_mul_f32_e32 v175, v175, v113
	v_mul_f32_e32 v176, v176, v113
	v_mul_f32_e32 v177, v177, v113
	v_mul_f32_e32 v174, v8, v174
	v_mul_f32_e32 v175, v9, v175
	v_mul_f32_e32 v176, v10, v176
	v_mul_f32_e32 v177, v11, v177
	v_fma_f32 v174, v174, v24, v40
	v_fma_f32 v175, v175, v25, v41
	v_fma_f32 v176, v176, v26, v42
	v_fma_f32 v177, v177, v27, v43
	v_cvt_pk_bf16_f32 v128, v174, v175
	v_cvt_pk_bf16_f32 v129, v176, v177
	global_store_dwordx2 v121, v[128:129], s[8:9] offset:1024
	v_mul_f32_e32 v178, v178, v113
	v_mul_f32_e32 v179, v179, v113
	v_mul_f32_e32 v180, v180, v113
	v_mul_f32_e32 v181, v181, v113
	v_mul_f32_e32 v178, v12, v178
	v_mul_f32_e32 v179, v13, v179
	v_mul_f32_e32 v180, v14, v180
	v_mul_f32_e32 v181, v15, v181
	v_fma_f32 v178, v178, v28, v44
	v_fma_f32 v179, v179, v29, v45
	v_fma_f32 v180, v180, v30, v46
	v_fma_f32 v181, v181, v31, v47
	v_cvt_pk_bf16_f32 v130, v178, v179
	v_cvt_pk_bf16_f32 v131, v180, v181
	global_store_dwordx2 v121, v[130:131], s[8:9] offset:1536
	s_add_u32 s8, s8, 0x20000
	s_addc_u32 s9, s9, 0
	v_mul_f32_e32 v182, v182, v114
	v_mul_f32_e32 v183, v183, v114
	v_mul_f32_e32 v184, v184, v114
	v_mul_f32_e32 v185, v185, v114
	v_mul_f32_e32 v182, v0, v182
	v_mul_f32_e32 v183, v1, v183
	v_mul_f32_e32 v184, v2, v184
	v_mul_f32_e32 v185, v3, v185
	v_fma_f32 v182, v182, v16, v32
	v_fma_f32 v183, v183, v17, v33
	v_fma_f32 v184, v184, v18, v34
	v_fma_f32 v185, v185, v19, v35
	v_cvt_pk_bf16_f32 v128, v182, v183
	v_cvt_pk_bf16_f32 v129, v184, v185
	global_store_dwordx2 v121, v[128:129], s[8:9] offset:0
	v_mul_f32_e32 v186, v186, v114
	v_mul_f32_e32 v187, v187, v114
	v_mul_f32_e32 v188, v188, v114
	v_mul_f32_e32 v189, v189, v114
	v_mul_f32_e32 v186, v4, v186
	v_mul_f32_e32 v187, v5, v187
	v_mul_f32_e32 v188, v6, v188
	v_mul_f32_e32 v189, v7, v189
	v_fma_f32 v186, v186, v20, v36
	v_fma_f32 v187, v187, v21, v37
	v_fma_f32 v188, v188, v22, v38
	v_fma_f32 v189, v189, v23, v39
	v_cvt_pk_bf16_f32 v130, v186, v187
	v_cvt_pk_bf16_f32 v131, v188, v189
	global_store_dwordx2 v121, v[130:131], s[8:9] offset:512
	v_mul_f32_e32 v190, v190, v114
	v_mul_f32_e32 v191, v191, v114
	v_mul_f32_e32 v192, v192, v114
	v_mul_f32_e32 v193, v193, v114
	v_mul_f32_e32 v190, v8, v190
	v_mul_f32_e32 v191, v9, v191
	v_mul_f32_e32 v192, v10, v192
	v_mul_f32_e32 v193, v11, v193
	v_fma_f32 v190, v190, v24, v40
	v_fma_f32 v191, v191, v25, v41
	v_fma_f32 v192, v192, v26, v42
	v_fma_f32 v193, v193, v27, v43
	v_cvt_pk_bf16_f32 v128, v190, v191
	v_cvt_pk_bf16_f32 v129, v192, v193
	global_store_dwordx2 v121, v[128:129], s[8:9] offset:1024
	v_mul_f32_e32 v194, v194, v114
	v_mul_f32_e32 v195, v195, v114
	v_mul_f32_e32 v196, v196, v114
	v_mul_f32_e32 v197, v197, v114
	v_mul_f32_e32 v194, v12, v194
	v_mul_f32_e32 v195, v13, v195
	v_mul_f32_e32 v196, v14, v196
	v_mul_f32_e32 v197, v15, v197
	v_fma_f32 v194, v194, v28, v44
	v_fma_f32 v195, v195, v29, v45
	v_fma_f32 v196, v196, v30, v46
	v_fma_f32 v197, v197, v31, v47
	v_cvt_pk_bf16_f32 v130, v194, v195
	v_cvt_pk_bf16_f32 v131, v196, v197
	global_store_dwordx2 v121, v[130:131], s[8:9] offset:1536
	s_add_u32 s8, s8, 0x20000
	s_addc_u32 s9, s9, 0
	v_mul_f32_e32 v228, v228, v115
	v_mul_f32_e32 v229, v229, v115
	v_mul_f32_e32 v230, v230, v115
	v_mul_f32_e32 v231, v231, v115
	v_mul_f32_e32 v228, v0, v228
	v_mul_f32_e32 v229, v1, v229
	v_mul_f32_e32 v230, v2, v230
	v_mul_f32_e32 v231, v3, v231
	v_fma_f32 v228, v228, v16, v32
	v_fma_f32 v229, v229, v17, v33
	v_fma_f32 v230, v230, v18, v34
	v_fma_f32 v231, v231, v19, v35
	v_cvt_pk_bf16_f32 v128, v228, v229
	v_cvt_pk_bf16_f32 v129, v230, v231
	global_store_dwordx2 v121, v[128:129], s[8:9] offset:0
	v_mul_f32_e32 v232, v232, v115
	v_mul_f32_e32 v233, v233, v115
	v_mul_f32_e32 v234, v234, v115
	v_mul_f32_e32 v235, v235, v115
	v_mul_f32_e32 v232, v4, v232
	v_mul_f32_e32 v233, v5, v233
	v_mul_f32_e32 v234, v6, v234
	v_mul_f32_e32 v235, v7, v235
	v_fma_f32 v232, v232, v20, v36
	v_fma_f32 v233, v233, v21, v37
	v_fma_f32 v234, v234, v22, v38
	v_fma_f32 v235, v235, v23, v39
	v_cvt_pk_bf16_f32 v130, v232, v233
	v_cvt_pk_bf16_f32 v131, v234, v235
	global_store_dwordx2 v121, v[130:131], s[8:9] offset:512
	v_mul_f32_e32 v236, v236, v115
	v_mul_f32_e32 v237, v237, v115
	v_mul_f32_e32 v238, v238, v115
	v_mul_f32_e32 v239, v239, v115
	v_mul_f32_e32 v236, v8, v236
	v_mul_f32_e32 v237, v9, v237
	v_mul_f32_e32 v238, v10, v238
	v_mul_f32_e32 v239, v11, v239
	v_fma_f32 v236, v236, v24, v40
	v_fma_f32 v237, v237, v25, v41
	v_fma_f32 v238, v238, v26, v42
	v_fma_f32 v239, v239, v27, v43
	v_cvt_pk_bf16_f32 v128, v236, v237
	v_cvt_pk_bf16_f32 v129, v238, v239
	global_store_dwordx2 v121, v[128:129], s[8:9] offset:1024
	v_mul_f32_e32 v240, v240, v115
	v_mul_f32_e32 v241, v241, v115
	v_mul_f32_e32 v242, v242, v115
	v_mul_f32_e32 v243, v243, v115
	v_mul_f32_e32 v240, v12, v240
	v_mul_f32_e32 v241, v13, v241
	v_mul_f32_e32 v242, v14, v242
	v_mul_f32_e32 v243, v15, v243
	v_fma_f32 v240, v240, v28, v44
	v_fma_f32 v241, v241, v29, v45
	v_fma_f32 v242, v242, v30, v46
	v_fma_f32 v243, v243, v31, v47
	v_cvt_pk_bf16_f32 v130, v240, v241
	v_cvt_pk_bf16_f32 v131, v242, v243
	global_store_dwordx2 v121, v[130:131], s[8:9] offset:1536
	s_add_u32 s8, s8, 0x20000
	s_addc_u32 s9, s9, 0
	global_load_dwordx4 v[132:135], v120, s[6:7] offset:0 nt
	global_load_dwordx4 v[136:139], v120, s[6:7] offset:1024 nt
	global_load_dwordx4 v[140:143], v120, s[6:7] offset:2048 nt
	global_load_dwordx4 v[144:147], v120, s[6:7] offset:3072 nt
	s_add_u32 s6, s6, 0x40000
	s_addc_u32 s7, s7, 0
	global_load_dwordx4 v[166:169], v120, s[6:7] offset:0 nt
	global_load_dwordx4 v[170:173], v120, s[6:7] offset:1024 nt
	global_load_dwordx4 v[174:177], v120, s[6:7] offset:2048 nt
	global_load_dwordx4 v[178:181], v120, s[6:7] offset:3072 nt
	s_add_u32 s6, s6, 0x40000
	s_addc_u32 s7, s7, 0
	global_load_dwordx4 v[182:185], v120, s[6:7] offset:0 nt
	global_load_dwordx4 v[186:189], v120, s[6:7] offset:1024 nt
	global_load_dwordx4 v[190:193], v120, s[6:7] offset:2048 nt
	global_load_dwordx4 v[194:197], v120, s[6:7] offset:3072 nt
	s_add_u32 s6, s6, 0x40000
	s_addc_u32 s7, s7, 0
	global_load_dwordx4 v[228:231], v120, s[6:7] offset:0 nt
	global_load_dwordx4 v[232:235], v120, s[6:7] offset:1024 nt
	global_load_dwordx4 v[236:239], v120, s[6:7] offset:2048 nt
	global_load_dwordx4 v[240:243], v120, s[6:7] offset:3072 nt
	s_add_u32 s6, s6, 0x40000
	s_addc_u32 s7, s7, 0
	s_waitcnt vmcnt(44)
	v_mul_f32_e32 v112, v48, v48
	v_fmac_f32_e32 v112, v49, v49
	v_fmac_f32_e32 v112, v50, v50
	v_fmac_f32_e32 v112, v51, v51
	v_fmac_f32_e32 v112, v52, v52
	v_fmac_f32_e32 v112, v53, v53
	v_fmac_f32_e32 v112, v54, v54
	v_fmac_f32_e32 v112, v55, v55
	v_fmac_f32_e32 v112, v56, v56
	v_fmac_f32_e32 v112, v57, v57
	v_fmac_f32_e32 v112, v58, v58
	v_fmac_f32_e32 v112, v59, v59
	v_fmac_f32_e32 v112, v60, v60
	v_fmac_f32_e32 v112, v61, v61
	v_fmac_f32_e32 v112, v62, v62
	v_fmac_f32_e32 v112, v63, v63
	s_waitcnt vmcnt(40)
	v_mul_f32_e32 v113, v64, v64
	v_fmac_f32_e32 v113, v65, v65
	v_fmac_f32_e32 v113, v66, v66
	v_fmac_f32_e32 v113, v67, v67
	v_fmac_f32_e32 v113, v68, v68
	v_fmac_f32_e32 v113, v69, v69
	v_fmac_f32_e32 v113, v70, v70
	v_fmac_f32_e32 v113, v71, v71
	v_fmac_f32_e32 v113, v72, v72
	v_fmac_f32_e32 v113, v73, v73
	v_fmac_f32_e32 v113, v74, v74
	v_fmac_f32_e32 v113, v75, v75
	v_fmac_f32_e32 v113, v76, v76
	v_fmac_f32_e32 v113, v77, v77
	v_fmac_f32_e32 v113, v78, v78
	v_fmac_f32_e32 v113, v79, v79
	s_waitcnt vmcnt(36)
	v_mul_f32_e32 v114, v80, v80
	v_fmac_f32_e32 v114, v81, v81
	v_fmac_f32_e32 v114, v82, v82
	v_fmac_f32_e32 v114, v83, v83
	v_fmac_f32_e32 v114, v84, v84
	v_fmac_f32_e32 v114, v85, v85
	v_fmac_f32_e32 v114, v86, v86
	v_fmac_f32_e32 v114, v87, v87
	v_fmac_f32_e32 v114, v88, v88
	v_fmac_f32_e32 v114, v89, v89
	v_fmac_f32_e32 v114, v90, v90
	v_fmac_f32_e32 v114, v91, v91
	v_fmac_f32_e32 v114, v92, v92
	v_fmac_f32_e32 v114, v93, v93
	v_fmac_f32_e32 v114, v94, v94
	v_fmac_f32_e32 v114, v95, v95
	s_waitcnt vmcnt(32)
	v_mul_f32_e32 v115, v96, v96
	v_fmac_f32_e32 v115, v97, v97
	v_fmac_f32_e32 v115, v98, v98
	v_fmac_f32_e32 v115, v99, v99
	v_fmac_f32_e32 v115, v100, v100
	v_fmac_f32_e32 v115, v101, v101
	v_fmac_f32_e32 v115, v102, v102
	v_fmac_f32_e32 v115, v103, v103
	v_fmac_f32_e32 v115, v104, v104
	v_fmac_f32_e32 v115, v105, v105
	v_fmac_f32_e32 v115, v106, v106
	v_fmac_f32_e32 v115, v107, v107
	v_fmac_f32_e32 v115, v108, v108
	v_fmac_f32_e32 v115, v109, v109
	v_fmac_f32_e32 v115, v110, v110
	v_fmac_f32_e32 v115, v111, v111
	ds_bpermute_b32 v116, v122, v112
	ds_bpermute_b32 v117, v122, v113
	ds_bpermute_b32 v118, v122, v114
	ds_bpermute_b32 v119, v122, v115
	s_waitcnt lgkmcnt(0)
	v_add_f32_e32 v112, v112, v116
	v_add_f32_e32 v113, v113, v117
	v_add_f32_e32 v114, v114, v118
	v_add_f32_e32 v115, v115, v119
	ds_bpermute_b32 v116, v123, v112
	ds_bpermute_b32 v117, v123, v113
	ds_bpermute_b32 v118, v123, v114
	ds_bpermute_b32 v119, v123, v115
	s_waitcnt lgkmcnt(0)
	v_add_f32_e32 v112, v112, v116
	v_add_f32_e32 v113, v113, v117
	v_add_f32_e32 v114, v114, v118
	v_add_f32_e32 v115, v115, v119
	ds_bpermute_b32 v116, v124, v112
	ds_bpermute_b32 v117, v124, v113
	ds_bpermute_b32 v118, v124, v114
	ds_bpermute_b32 v119, v124, v115
	s_waitcnt lgkmcnt(0)
	v_add_f32_e32 v112, v112, v116
	v_add_f32_e32 v113, v113, v117
	v_add_f32_e32 v114, v114, v118
	v_add_f32_e32 v115, v115, v119
	ds_bpermute_b32 v116, v125, v112
	ds_bpermute_b32 v117, v125, v113
	ds_bpermute_b32 v118, v125, v114
	ds_bpermute_b32 v119, v125, v115
	s_waitcnt lgkmcnt(0)
	v_add_f32_e32 v112, v112, v116
	v_add_f32_e32 v113, v113, v117
	v_add_f32_e32 v114, v114, v118
	v_add_f32_e32 v115, v115, v119
	ds_bpermute_b32 v116, v126, v112
	ds_bpermute_b32 v117, v126, v113
	ds_bpermute_b32 v118, v126, v114
	ds_bpermute_b32 v119, v126, v115
	s_waitcnt lgkmcnt(0)
	v_add_f32_e32 v112, v112, v116
	v_add_f32_e32 v113, v113, v117
	v_add_f32_e32 v114, v114, v118
	v_add_f32_e32 v115, v115, v119
	ds_bpermute_b32 v116, v127, v112
	ds_bpermute_b32 v117, v127, v113
	ds_bpermute_b32 v118, v127, v114
	ds_bpermute_b32 v119, v127, v115
	s_waitcnt lgkmcnt(0)
	v_add_f32_e32 v112, v112, v116
	v_add_f32_e32 v113, v113, v117
	v_add_f32_e32 v114, v114, v118
	v_add_f32_e32 v115, v115, v119
	v_fmamk_f32 v112, v112, 0x3a800000, v208
	v_fmamk_f32 v113, v113, 0x3a800000, v208
	v_fmamk_f32 v114, v114, 0x3a800000, v208
	v_fmamk_f32 v115, v115, 0x3a800000, v208
	v_rsq_f32_e32 v112, v112
	v_rsq_f32_e32 v113, v113
	v_rsq_f32_e32 v114, v114
	v_rsq_f32_e32 v115, v115
	s_nop 1
	v_mul_f32_e32 v48, v48, v112
	v_mul_f32_e32 v49, v49, v112
	v_mul_f32_e32 v50, v50, v112
	v_mul_f32_e32 v51, v51, v112
	v_mul_f32_e32 v48, v0, v48
	v_mul_f32_e32 v49, v1, v49
	v_mul_f32_e32 v50, v2, v50
	v_mul_f32_e32 v51, v3, v51
	v_fma_f32 v48, v48, v16, v32
	v_fma_f32 v49, v49, v17, v33
	v_fma_f32 v50, v50, v18, v34
	v_fma_f32 v51, v51, v19, v35
	v_cvt_pk_bf16_f32 v128, v48, v49
	v_cvt_pk_bf16_f32 v129, v50, v51
	global_store_dwordx2 v121, v[128:129], s[8:9] offset:0
	v_mul_f32_e32 v52, v52, v112
	v_mul_f32_e32 v53, v53, v112
	v_mul_f32_e32 v54, v54, v112
	v_mul_f32_e32 v55, v55, v112
	v_mul_f32_e32 v52, v4, v52
	v_mul_f32_e32 v53, v5, v53
	v_mul_f32_e32 v54, v6, v54
	v_mul_f32_e32 v55, v7, v55
	v_fma_f32 v52, v52, v20, v36
	v_fma_f32 v53, v53, v21, v37
	v_fma_f32 v54, v54, v22, v38
	v_fma_f32 v55, v55, v23, v39
	v_cvt_pk_bf16_f32 v130, v52, v53
	v_cvt_pk_bf16_f32 v131, v54, v55
	global_store_dwordx2 v121, v[130:131], s[8:9] offset:512
	v_mul_f32_e32 v56, v56, v112
	v_mul_f32_e32 v57, v57, v112
	v_mul_f32_e32 v58, v58, v112
	v_mul_f32_e32 v59, v59, v112
	v_mul_f32_e32 v56, v8, v56
	v_mul_f32_e32 v57, v9, v57
	v_mul_f32_e32 v58, v10, v58
	v_mul_f32_e32 v59, v11, v59
	v_fma_f32 v56, v56, v24, v40
	v_fma_f32 v57, v57, v25, v41
	v_fma_f32 v58, v58, v26, v42
	v_fma_f32 v59, v59, v27, v43
	v_cvt_pk_bf16_f32 v128, v56, v57
	v_cvt_pk_bf16_f32 v129, v58, v59
	global_store_dwordx2 v121, v[128:129], s[8:9] offset:1024
	v_mul_f32_e32 v60, v60, v112
	v_mul_f32_e32 v61, v61, v112
	v_mul_f32_e32 v62, v62, v112
	v_mul_f32_e32 v63, v63, v112
	v_mul_f32_e32 v60, v12, v60
	v_mul_f32_e32 v61, v13, v61
	v_mul_f32_e32 v62, v14, v62
	v_mul_f32_e32 v63, v15, v63
	v_fma_f32 v60, v60, v28, v44
	v_fma_f32 v61, v61, v29, v45
	v_fma_f32 v62, v62, v30, v46
	v_fma_f32 v63, v63, v31, v47
	v_cvt_pk_bf16_f32 v130, v60, v61
	v_cvt_pk_bf16_f32 v131, v62, v63
	global_store_dwordx2 v121, v[130:131], s[8:9] offset:1536
	s_add_u32 s8, s8, 0x20000
	s_addc_u32 s9, s9, 0
	v_mul_f32_e32 v64, v64, v113
	v_mul_f32_e32 v65, v65, v113
	v_mul_f32_e32 v66, v66, v113
	v_mul_f32_e32 v67, v67, v113
	v_mul_f32_e32 v64, v0, v64
	v_mul_f32_e32 v65, v1, v65
	v_mul_f32_e32 v66, v2, v66
	v_mul_f32_e32 v67, v3, v67
	v_fma_f32 v64, v64, v16, v32
	v_fma_f32 v65, v65, v17, v33
	v_fma_f32 v66, v66, v18, v34
	v_fma_f32 v67, v67, v19, v35
	v_cvt_pk_bf16_f32 v128, v64, v65
	v_cvt_pk_bf16_f32 v129, v66, v67
	global_store_dwordx2 v121, v[128:129], s[8:9] offset:0
	v_mul_f32_e32 v68, v68, v113
	v_mul_f32_e32 v69, v69, v113
	v_mul_f32_e32 v70, v70, v113
	v_mul_f32_e32 v71, v71, v113
	v_mul_f32_e32 v68, v4, v68
	v_mul_f32_e32 v69, v5, v69
	v_mul_f32_e32 v70, v6, v70
	v_mul_f32_e32 v71, v7, v71
	v_fma_f32 v68, v68, v20, v36
	v_fma_f32 v69, v69, v21, v37
	v_fma_f32 v70, v70, v22, v38
	v_fma_f32 v71, v71, v23, v39
	v_cvt_pk_bf16_f32 v130, v68, v69
	v_cvt_pk_bf16_f32 v131, v70, v71
	global_store_dwordx2 v121, v[130:131], s[8:9] offset:512
	v_mul_f32_e32 v72, v72, v113
	v_mul_f32_e32 v73, v73, v113
	v_mul_f32_e32 v74, v74, v113
	v_mul_f32_e32 v75, v75, v113
	v_mul_f32_e32 v72, v8, v72
	v_mul_f32_e32 v73, v9, v73
	v_mul_f32_e32 v74, v10, v74
	v_mul_f32_e32 v75, v11, v75
	v_fma_f32 v72, v72, v24, v40
	v_fma_f32 v73, v73, v25, v41
	v_fma_f32 v74, v74, v26, v42
	v_fma_f32 v75, v75, v27, v43
	v_cvt_pk_bf16_f32 v128, v72, v73
	v_cvt_pk_bf16_f32 v129, v74, v75
	global_store_dwordx2 v121, v[128:129], s[8:9] offset:1024
	v_mul_f32_e32 v76, v76, v113
	v_mul_f32_e32 v77, v77, v113
	v_mul_f32_e32 v78, v78, v113
	v_mul_f32_e32 v79, v79, v113
	v_mul_f32_e32 v76, v12, v76
	v_mul_f32_e32 v77, v13, v77
	v_mul_f32_e32 v78, v14, v78
	v_mul_f32_e32 v79, v15, v79
	v_fma_f32 v76, v76, v28, v44
	v_fma_f32 v77, v77, v29, v45
	v_fma_f32 v78, v78, v30, v46
	v_fma_f32 v79, v79, v31, v47
	v_cvt_pk_bf16_f32 v130, v76, v77
	v_cvt_pk_bf16_f32 v131, v78, v79
	global_store_dwordx2 v121, v[130:131], s[8:9] offset:1536
	s_add_u32 s8, s8, 0x20000
	s_addc_u32 s9, s9, 0
	v_mul_f32_e32 v80, v80, v114
	v_mul_f32_e32 v81, v81, v114
	v_mul_f32_e32 v82, v82, v114
	v_mul_f32_e32 v83, v83, v114
	v_mul_f32_e32 v80, v0, v80
	v_mul_f32_e32 v81, v1, v81
	v_mul_f32_e32 v82, v2, v82
	v_mul_f32_e32 v83, v3, v83
	v_fma_f32 v80, v80, v16, v32
	v_fma_f32 v81, v81, v17, v33
	v_fma_f32 v82, v82, v18, v34
	v_fma_f32 v83, v83, v19, v35
	v_cvt_pk_bf16_f32 v128, v80, v81
	v_cvt_pk_bf16_f32 v129, v82, v83
	global_store_dwordx2 v121, v[128:129], s[8:9] offset:0
	v_mul_f32_e32 v84, v84, v114
	v_mul_f32_e32 v85, v85, v114
	v_mul_f32_e32 v86, v86, v114
	v_mul_f32_e32 v87, v87, v114
	v_mul_f32_e32 v84, v4, v84
	v_mul_f32_e32 v85, v5, v85
	v_mul_f32_e32 v86, v6, v86
	v_mul_f32_e32 v87, v7, v87
	v_fma_f32 v84, v84, v20, v36
	v_fma_f32 v85, v85, v21, v37
	v_fma_f32 v86, v86, v22, v38
	v_fma_f32 v87, v87, v23, v39
	v_cvt_pk_bf16_f32 v130, v84, v85
	v_cvt_pk_bf16_f32 v131, v86, v87
	global_store_dwordx2 v121, v[130:131], s[8:9] offset:512
	v_mul_f32_e32 v88, v88, v114
	v_mul_f32_e32 v89, v89, v114
	v_mul_f32_e32 v90, v90, v114
	v_mul_f32_e32 v91, v91, v114
	v_mul_f32_e32 v88, v8, v88
	v_mul_f32_e32 v89, v9, v89
	v_mul_f32_e32 v90, v10, v90
	v_mul_f32_e32 v91, v11, v91
	v_fma_f32 v88, v88, v24, v40
	v_fma_f32 v89, v89, v25, v41
	v_fma_f32 v90, v90, v26, v42
	v_fma_f32 v91, v91, v27, v43
	v_cvt_pk_bf16_f32 v128, v88, v89
	v_cvt_pk_bf16_f32 v129, v90, v91
	global_store_dwordx2 v121, v[128:129], s[8:9] offset:1024
	v_mul_f32_e32 v92, v92, v114
	v_mul_f32_e32 v93, v93, v114
	v_mul_f32_e32 v94, v94, v114
	v_mul_f32_e32 v95, v95, v114
	v_mul_f32_e32 v92, v12, v92
	v_mul_f32_e32 v93, v13, v93
	v_mul_f32_e32 v94, v14, v94
	v_mul_f32_e32 v95, v15, v95
	v_fma_f32 v92, v92, v28, v44
	v_fma_f32 v93, v93, v29, v45
	v_fma_f32 v94, v94, v30, v46
	v_fma_f32 v95, v95, v31, v47
	v_cvt_pk_bf16_f32 v130, v92, v93
	v_cvt_pk_bf16_f32 v131, v94, v95
	global_store_dwordx2 v121, v[130:131], s[8:9] offset:1536
	s_add_u32 s8, s8, 0x20000
	s_addc_u32 s9, s9, 0
	v_mul_f32_e32 v96, v96, v115
	v_mul_f32_e32 v97, v97, v115
	v_mul_f32_e32 v98, v98, v115
	v_mul_f32_e32 v99, v99, v115
	v_mul_f32_e32 v96, v0, v96
	v_mul_f32_e32 v97, v1, v97
	v_mul_f32_e32 v98, v2, v98
	v_mul_f32_e32 v99, v3, v99
	v_fma_f32 v96, v96, v16, v32
	v_fma_f32 v97, v97, v17, v33
	v_fma_f32 v98, v98, v18, v34
	v_fma_f32 v99, v99, v19, v35
	v_cvt_pk_bf16_f32 v128, v96, v97
	v_cvt_pk_bf16_f32 v129, v98, v99
	global_store_dwordx2 v121, v[128:129], s[8:9] offset:0
	v_mul_f32_e32 v100, v100, v115
	v_mul_f32_e32 v101, v101, v115
	v_mul_f32_e32 v102, v102, v115
	v_mul_f32_e32 v103, v103, v115
	v_mul_f32_e32 v100, v4, v100
	v_mul_f32_e32 v101, v5, v101
	v_mul_f32_e32 v102, v6, v102
	v_mul_f32_e32 v103, v7, v103
	v_fma_f32 v100, v100, v20, v36
	v_fma_f32 v101, v101, v21, v37
	v_fma_f32 v102, v102, v22, v38
	v_fma_f32 v103, v103, v23, v39
	v_cvt_pk_bf16_f32 v130, v100, v101
	v_cvt_pk_bf16_f32 v131, v102, v103
	global_store_dwordx2 v121, v[130:131], s[8:9] offset:512
	v_mul_f32_e32 v104, v104, v115
	v_mul_f32_e32 v105, v105, v115
	v_mul_f32_e32 v106, v106, v115
	v_mul_f32_e32 v107, v107, v115
	v_mul_f32_e32 v104, v8, v104
	v_mul_f32_e32 v105, v9, v105
	v_mul_f32_e32 v106, v10, v106
	v_mul_f32_e32 v107, v11, v107
	v_fma_f32 v104, v104, v24, v40
	v_fma_f32 v105, v105, v25, v41
	v_fma_f32 v106, v106, v26, v42
	v_fma_f32 v107, v107, v27, v43
	v_cvt_pk_bf16_f32 v128, v104, v105
	v_cvt_pk_bf16_f32 v129, v106, v107
	global_store_dwordx2 v121, v[128:129], s[8:9] offset:1024
	v_mul_f32_e32 v108, v108, v115
	v_mul_f32_e32 v109, v109, v115
	v_mul_f32_e32 v110, v110, v115
	v_mul_f32_e32 v111, v111, v115
	v_mul_f32_e32 v108, v12, v108
	v_mul_f32_e32 v109, v13, v109
	v_mul_f32_e32 v110, v14, v110
	v_mul_f32_e32 v111, v15, v111
	v_fma_f32 v108, v108, v28, v44
	v_fma_f32 v109, v109, v29, v45
	v_fma_f32 v110, v110, v30, v46
	v_fma_f32 v111, v111, v31, v47
	v_cvt_pk_bf16_f32 v130, v108, v109
	v_cvt_pk_bf16_f32 v131, v110, v111
	global_store_dwordx2 v121, v[130:131], s[8:9] offset:1536
	s_add_u32 s8, s8, 0x20000
	s_addc_u32 s9, s9, 0
	s_sub_u32 s2, s2, 1
	s_cmp_lg_u32 s2, 0
	s_cbranch_scc1 .Lrms_sub6_loop
	s_waitcnt vmcnt(28)
	v_mul_f32_e32 v112, v132, v132
	v_fmac_f32_e32 v112, v133, v133
	v_fmac_f32_e32 v112, v134, v134
	v_fmac_f32_e32 v112, v135, v135
	v_fmac_f32_e32 v112, v136, v136
	v_fmac_f32_e32 v112, v137, v137
	v_fmac_f32_e32 v112, v138, v138
	v_fmac_f32_e32 v112, v139, v139
	v_fmac_f32_e32 v112, v140, v140
	v_fmac_f32_e32 v112, v141, v141
	v_fmac_f32_e32 v112, v142, v142
	v_fmac_f32_e32 v112, v143, v143
	v_fmac_f32_e32 v112, v144, v144
	v_fmac_f32_e32 v112, v145, v145
	v_fmac_f32_e32 v112, v146, v146
	v_fmac_f32_e32 v112, v147, v147
	s_waitcnt vmcnt(24)
	v_mul_f32_e32 v113, v166, v166
	v_fmac_f32_e32 v113, v167, v167
	v_fmac_f32_e32 v113, v168, v168
	v_fmac_f32_e32 v113, v169, v169
	v_fmac_f32_e32 v113, v170, v170
	v_fmac_f32_e32 v113, v171, v171
	v_fmac_f32_e32 v113, v172, v172
	v_fmac_f32_e32 v113, v173, v173
	v_fmac_f32_e32 v113, v174, v174
	v_fmac_f32_e32 v113, v175, v175
	v_fmac_f32_e32 v113, v176, v176
	v_fmac_f32_e32 v113, v177, v177
	v_fmac_f32_e32 v113, v178, v178
	v_fmac_f32_e32 v113, v179, v179
	v_fmac_f32_e32 v113, v180, v180
	v_fmac_f32_e32 v113, v181, v181
	s_waitcnt vmcnt(20)
	v_mul_f32_e32 v114, v182, v182
	v_fmac_f32_e32 v114, v183, v183
	v_fmac_f32_e32 v114, v184, v184
	v_fmac_f32_e32 v114, v185, v185
	v_fmac_f32_e32 v114, v186, v186
	v_fmac_f32_e32 v114, v187, v187
	v_fmac_f32_e32 v114, v188, v188
	v_fmac_f32_e32 v114, v189, v189
	v_fmac_f32_e32 v114, v190, v190
	v_fmac_f32_e32 v114, v191, v191
	v_fmac_f32_e32 v114, v192, v192
	v_fmac_f32_e32 v114, v193, v193
	v_fmac_f32_e32 v114, v194, v194
	v_fmac_f32_e32 v114, v195, v195
	v_fmac_f32_e32 v114, v196, v196
	v_fmac_f32_e32 v114, v197, v197
	s_waitcnt vmcnt(16)
	v_mul_f32_e32 v115, v228, v228
	v_fmac_f32_e32 v115, v229, v229
	v_fmac_f32_e32 v115, v230, v230
	v_fmac_f32_e32 v115, v231, v231
	v_fmac_f32_e32 v115, v232, v232
	v_fmac_f32_e32 v115, v233, v233
	v_fmac_f32_e32 v115, v234, v234
	v_fmac_f32_e32 v115, v235, v235
	v_fmac_f32_e32 v115, v236, v236
	v_fmac_f32_e32 v115, v237, v237
	v_fmac_f32_e32 v115, v238, v238
	v_fmac_f32_e32 v115, v239, v239
	v_fmac_f32_e32 v115, v240, v240
	v_fmac_f32_e32 v115, v241, v241
	v_fmac_f32_e32 v115, v242, v242
	v_fmac_f32_e32 v115, v243, v243
	ds_bpermute_b32 v116, v122, v112
	ds_bpermute_b32 v117, v122, v113
	ds_bpermute_b32 v118, v122, v114
	ds_bpermute_b32 v119, v122, v115
	s_waitcnt lgkmcnt(0)
	v_add_f32_e32 v112, v112, v116
	v_add_f32_e32 v113, v113, v117
	v_add_f32_e32 v114, v114, v118
	v_add_f32_e32 v115, v115, v119
	ds_bpermute_b32 v116, v123, v112
	ds_bpermute_b32 v117, v123, v113
	ds_bpermute_b32 v118, v123, v114
	ds_bpermute_b32 v119, v123, v115
	s_waitcnt lgkmcnt(0)
	v_add_f32_e32 v112, v112, v116
	v_add_f32_e32 v113, v113, v117
	v_add_f32_e32 v114, v114, v118
	v_add_f32_e32 v115, v115, v119
	ds_bpermute_b32 v116, v124, v112
	ds_bpermute_b32 v117, v124, v113
	ds_bpermute_b32 v118, v124, v114
	ds_bpermute_b32 v119, v124, v115
	s_waitcnt lgkmcnt(0)
	v_add_f32_e32 v112, v112, v116
	v_add_f32_e32 v113, v113, v117
	v_add_f32_e32 v114, v114, v118
	v_add_f32_e32 v115, v115, v119
	ds_bpermute_b32 v116, v125, v112
	ds_bpermute_b32 v117, v125, v113
	ds_bpermute_b32 v118, v125, v114
	ds_bpermute_b32 v119, v125, v115
	s_waitcnt lgkmcnt(0)
	v_add_f32_e32 v112, v112, v116
	v_add_f32_e32 v113, v113, v117
	v_add_f32_e32 v114, v114, v118
	v_add_f32_e32 v115, v115, v119
	ds_bpermute_b32 v116, v126, v112
	ds_bpermute_b32 v117, v126, v113
	ds_bpermute_b32 v118, v126, v114
	ds_bpermute_b32 v119, v126, v115
	s_waitcnt lgkmcnt(0)
	v_add_f32_e32 v112, v112, v116
	v_add_f32_e32 v113, v113, v117
	v_add_f32_e32 v114, v114, v118
	v_add_f32_e32 v115, v115, v119
	ds_bpermute_b32 v116, v127, v112
	ds_bpermute_b32 v117, v127, v113
	ds_bpermute_b32 v118, v127, v114
	ds_bpermute_b32 v119, v127, v115
	s_waitcnt lgkmcnt(0)
	v_add_f32_e32 v112, v112, v116
	v_add_f32_e32 v113, v113, v117
	v_add_f32_e32 v114, v114, v118
	v_add_f32_e32 v115, v115, v119
	v_fmamk_f32 v112, v112, 0x3a800000, v208
	v_fmamk_f32 v113, v113, 0x3a800000, v208
	v_fmamk_f32 v114, v114, 0x3a800000, v208
	v_fmamk_f32 v115, v115, 0x3a800000, v208
	v_rsq_f32_e32 v112, v112
	v_rsq_f32_e32 v113, v113
	v_rsq_f32_e32 v114, v114
	v_rsq_f32_e32 v115, v115
	s_nop 1
	v_mul_f32_e32 v132, v132, v112
	v_mul_f32_e32 v133, v133, v112
	v_mul_f32_e32 v134, v134, v112
	v_mul_f32_e32 v135, v135, v112
	v_mul_f32_e32 v132, v0, v132
	v_mul_f32_e32 v133, v1, v133
	v_mul_f32_e32 v134, v2, v134
	v_mul_f32_e32 v135, v3, v135
	v_fma_f32 v132, v132, v16, v32
	v_fma_f32 v133, v133, v17, v33
	v_fma_f32 v134, v134, v18, v34
	v_fma_f32 v135, v135, v19, v35
	v_cvt_pk_bf16_f32 v128, v132, v133
	v_cvt_pk_bf16_f32 v129, v134, v135
	global_store_dwordx2 v121, v[128:129], s[8:9] offset:0
	v_mul_f32_e32 v136, v136, v112
	v_mul_f32_e32 v137, v137, v112
	v_mul_f32_e32 v138, v138, v112
	v_mul_f32_e32 v139, v139, v112
	v_mul_f32_e32 v136, v4, v136
	v_mul_f32_e32 v137, v5, v137
	v_mul_f32_e32 v138, v6, v138
	v_mul_f32_e32 v139, v7, v139
	v_fma_f32 v136, v136, v20, v36
	v_fma_f32 v137, v137, v21, v37
	v_fma_f32 v138, v138, v22, v38
	v_fma_f32 v139, v139, v23, v39
	v_cvt_pk_bf16_f32 v130, v136, v137
	v_cvt_pk_bf16_f32 v131, v138, v139
	global_store_dwordx2 v121, v[130:131], s[8:9] offset:512
	v_mul_f32_e32 v140, v140, v112
	v_mul_f32_e32 v141, v141, v112
	v_mul_f32_e32 v142, v142, v112
	v_mul_f32_e32 v143, v143, v112
	v_mul_f32_e32 v140, v8, v140
	v_mul_f32_e32 v141, v9, v141
	v_mul_f32_e32 v142, v10, v142
	v_mul_f32_e32 v143, v11, v143
	v_fma_f32 v140, v140, v24, v40
	v_fma_f32 v141, v141, v25, v41
	v_fma_f32 v142, v142, v26, v42
	v_fma_f32 v143, v143, v27, v43
	v_cvt_pk_bf16_f32 v128, v140, v141
	v_cvt_pk_bf16_f32 v129, v142, v143
	global_store_dwordx2 v121, v[128:129], s[8:9] offset:1024
	v_mul_f32_e32 v144, v144, v112
	v_mul_f32_e32 v145, v145, v112
	v_mul_f32_e32 v146, v146, v112
	v_mul_f32_e32 v147, v147, v112
	v_mul_f32_e32 v144, v12, v144
	v_mul_f32_e32 v145, v13, v145
	v_mul_f32_e32 v146, v14, v146
	v_mul_f32_e32 v147, v15, v147
	v_fma_f32 v144, v144, v28, v44
	v_fma_f32 v145, v145, v29, v45
	v_fma_f32 v146, v146, v30, v46
	v_fma_f32 v147, v147, v31, v47
	v_cvt_pk_bf16_f32 v130, v144, v145
	v_cvt_pk_bf16_f32 v131, v146, v147
	global_store_dwordx2 v121, v[130:131], s[8:9] offset:1536
	s_add_u32 s8, s8, 0x20000
	s_addc_u32 s9, s9, 0
	v_mul_f32_e32 v166, v166, v113
	v_mul_f32_e32 v167, v167, v113
	v_mul_f32_e32 v168, v168, v113
	v_mul_f32_e32 v169, v169, v113
	v_mul_f32_e32 v166, v0, v166
	v_mul_f32_e32 v167, v1, v167
	v_mul_f32_e32 v168, v2, v168
	v_mul_f32_e32 v169, v3, v169
	v_fma_f32 v166, v166, v16, v32
	v_fma_f32 v167, v167, v17, v33
	v_fma_f32 v168, v168, v18, v34
	v_fma_f32 v169, v169, v19, v35
	v_cvt_pk_bf16_f32 v128, v166, v167
	v_cvt_pk_bf16_f32 v129, v168, v169
	global_store_dwordx2 v121, v[128:129], s[8:9] offset:0
	v_mul_f32_e32 v170, v170, v113
	v_mul_f32_e32 v171, v171, v113
	v_mul_f32_e32 v172, v172, v113
	v_mul_f32_e32 v173, v173, v113
	v_mul_f32_e32 v170, v4, v170
	v_mul_f32_e32 v171, v5, v171
	v_mul_f32_e32 v172, v6, v172
	v_mul_f32_e32 v173, v7, v173
	v_fma_f32 v170, v170, v20, v36
	v_fma_f32 v171, v171, v21, v37
	v_fma_f32 v172, v172, v22, v38
	v_fma_f32 v173, v173, v23, v39
	v_cvt_pk_bf16_f32 v130, v170, v171
	v_cvt_pk_bf16_f32 v131, v172, v173
	global_store_dwordx2 v121, v[130:131], s[8:9] offset:512
	v_mul_f32_e32 v174, v174, v113
	v_mul_f32_e32 v175, v175, v113
	v_mul_f32_e32 v176, v176, v113
	v_mul_f32_e32 v177, v177, v113
	v_mul_f32_e32 v174, v8, v174
	v_mul_f32_e32 v175, v9, v175
	v_mul_f32_e32 v176, v10, v176
	v_mul_f32_e32 v177, v11, v177
	v_fma_f32 v174, v174, v24, v40
	v_fma_f32 v175, v175, v25, v41
	v_fma_f32 v176, v176, v26, v42
	v_fma_f32 v177, v177, v27, v43
	v_cvt_pk_bf16_f32 v128, v174, v175
	v_cvt_pk_bf16_f32 v129, v176, v177
	global_store_dwordx2 v121, v[128:129], s[8:9] offset:1024
	v_mul_f32_e32 v178, v178, v113
	v_mul_f32_e32 v179, v179, v113
	v_mul_f32_e32 v180, v180, v113
	v_mul_f32_e32 v181, v181, v113
	v_mul_f32_e32 v178, v12, v178
	v_mul_f32_e32 v179, v13, v179
	v_mul_f32_e32 v180, v14, v180
	v_mul_f32_e32 v181, v15, v181
	v_fma_f32 v178, v178, v28, v44
	v_fma_f32 v179, v179, v29, v45
	v_fma_f32 v180, v180, v30, v46
	v_fma_f32 v181, v181, v31, v47
	v_cvt_pk_bf16_f32 v130, v178, v179
	v_cvt_pk_bf16_f32 v131, v180, v181
	global_store_dwordx2 v121, v[130:131], s[8:9] offset:1536
	s_add_u32 s8, s8, 0x20000
	s_addc_u32 s9, s9, 0
	v_mul_f32_e32 v182, v182, v114
	v_mul_f32_e32 v183, v183, v114
	v_mul_f32_e32 v184, v184, v114
	v_mul_f32_e32 v185, v185, v114
	v_mul_f32_e32 v182, v0, v182
	v_mul_f32_e32 v183, v1, v183
	v_mul_f32_e32 v184, v2, v184
	v_mul_f32_e32 v185, v3, v185
	v_fma_f32 v182, v182, v16, v32
	v_fma_f32 v183, v183, v17, v33
	v_fma_f32 v184, v184, v18, v34
	v_fma_f32 v185, v185, v19, v35
	v_cvt_pk_bf16_f32 v128, v182, v183
	v_cvt_pk_bf16_f32 v129, v184, v185
	global_store_dwordx2 v121, v[128:129], s[8:9] offset:0
	v_mul_f32_e32 v186, v186, v114
	v_mul_f32_e32 v187, v187, v114
	v_mul_f32_e32 v188, v188, v114
	v_mul_f32_e32 v189, v189, v114
	v_mul_f32_e32 v186, v4, v186
	v_mul_f32_e32 v187, v5, v187
	v_mul_f32_e32 v188, v6, v188
	v_mul_f32_e32 v189, v7, v189
	v_fma_f32 v186, v186, v20, v36
	v_fma_f32 v187, v187, v21, v37
	v_fma_f32 v188, v188, v22, v38
	v_fma_f32 v189, v189, v23, v39
	v_cvt_pk_bf16_f32 v130, v186, v187
	v_cvt_pk_bf16_f32 v131, v188, v189
	global_store_dwordx2 v121, v[130:131], s[8:9] offset:512
	v_mul_f32_e32 v190, v190, v114
	v_mul_f32_e32 v191, v191, v114
	v_mul_f32_e32 v192, v192, v114
	v_mul_f32_e32 v193, v193, v114
	v_mul_f32_e32 v190, v8, v190
	v_mul_f32_e32 v191, v9, v191
	v_mul_f32_e32 v192, v10, v192
	v_mul_f32_e32 v193, v11, v193
	v_fma_f32 v190, v190, v24, v40
	v_fma_f32 v191, v191, v25, v41
	v_fma_f32 v192, v192, v26, v42
	v_fma_f32 v193, v193, v27, v43
	v_cvt_pk_bf16_f32 v128, v190, v191
	v_cvt_pk_bf16_f32 v129, v192, v193
	global_store_dwordx2 v121, v[128:129], s[8:9] offset:1024
	v_mul_f32_e32 v194, v194, v114
	v_mul_f32_e32 v195, v195, v114
	v_mul_f32_e32 v196, v196, v114
	v_mul_f32_e32 v197, v197, v114
	v_mul_f32_e32 v194, v12, v194
	v_mul_f32_e32 v195, v13, v195
	v_mul_f32_e32 v196, v14, v196
	v_mul_f32_e32 v197, v15, v197
	v_fma_f32 v194, v194, v28, v44
	v_fma_f32 v195, v195, v29, v45
	v_fma_f32 v196, v196, v30, v46
	v_fma_f32 v197, v197, v31, v47
	v_cvt_pk_bf16_f32 v130, v194, v195
	v_cvt_pk_bf16_f32 v131, v196, v197
	global_store_dwordx2 v121, v[130:131], s[8:9] offset:1536
	s_add_u32 s8, s8, 0x20000
	s_addc_u32 s9, s9, 0
	v_mul_f32_e32 v228, v228, v115
	v_mul_f32_e32 v229, v229, v115
	v_mul_f32_e32 v230, v230, v115
	v_mul_f32_e32 v231, v231, v115
	v_mul_f32_e32 v228, v0, v228
	v_mul_f32_e32 v229, v1, v229
	v_mul_f32_e32 v230, v2, v230
	v_mul_f32_e32 v231, v3, v231
	v_fma_f32 v228, v228, v16, v32
	v_fma_f32 v229, v229, v17, v33
	v_fma_f32 v230, v230, v18, v34
	v_fma_f32 v231, v231, v19, v35
	v_cvt_pk_bf16_f32 v128, v228, v229
	v_cvt_pk_bf16_f32 v129, v230, v231
	global_store_dwordx2 v121, v[128:129], s[8:9] offset:0
	v_mul_f32_e32 v232, v232, v115
	v_mul_f32_e32 v233, v233, v115
	v_mul_f32_e32 v234, v234, v115
	v_mul_f32_e32 v235, v235, v115
	v_mul_f32_e32 v232, v4, v232
	v_mul_f32_e32 v233, v5, v233
	v_mul_f32_e32 v234, v6, v234
	v_mul_f32_e32 v235, v7, v235
	v_fma_f32 v232, v232, v20, v36
	v_fma_f32 v233, v233, v21, v37
	v_fma_f32 v234, v234, v22, v38
	v_fma_f32 v235, v235, v23, v39
	v_cvt_pk_bf16_f32 v130, v232, v233
	v_cvt_pk_bf16_f32 v131, v234, v235
	global_store_dwordx2 v121, v[130:131], s[8:9] offset:512
	v_mul_f32_e32 v236, v236, v115
	v_mul_f32_e32 v237, v237, v115
	v_mul_f32_e32 v238, v238, v115
	v_mul_f32_e32 v239, v239, v115
	v_mul_f32_e32 v236, v8, v236
	v_mul_f32_e32 v237, v9, v237
	v_mul_f32_e32 v238, v10, v238
	v_mul_f32_e32 v239, v11, v239
	v_fma_f32 v236, v236, v24, v40
	v_fma_f32 v237, v237, v25, v41
	v_fma_f32 v238, v238, v26, v42
	v_fma_f32 v239, v239, v27, v43
	v_cvt_pk_bf16_f32 v128, v236, v237
	v_cvt_pk_bf16_f32 v129, v238, v239
	global_store_dwordx2 v121, v[128:129], s[8:9] offset:1024
	v_mul_f32_e32 v240, v240, v115
	v_mul_f32_e32 v241, v241, v115
	v_mul_f32_e32 v242, v242, v115
	v_mul_f32_e32 v243, v243, v115
	v_mul_f32_e32 v240, v12, v240
	v_mul_f32_e32 v241, v13, v241
	v_mul_f32_e32 v242, v14, v242
	v_mul_f32_e32 v243, v15, v243
	v_fma_f32 v240, v240, v28, v44
	v_fma_f32 v241, v241, v29, v45
	v_fma_f32 v242, v242, v30, v46
	v_fma_f32 v243, v243, v31, v47
	v_cvt_pk_bf16_f32 v130, v240, v241
	v_cvt_pk_bf16_f32 v131, v242, v243
	global_store_dwordx2 v121, v[130:131], s[8:9] offset:1536
	s_add_u32 s8, s8, 0x20000
	s_addc_u32 s9, s9, 0

.LBB0_562:
	s_and_b64 vcc, exec, s[0:1]
	s_cbranch_vccz .LBB0_569
	v_mov_b32_e32 v0, 16
	v_mov_b32_e32 v2, 0xe8
	v_add_u32_e32 v0, s91, v0
	ds_read_b64 v[0:1], v0
	v_readlane_b32 s0, v253, 11
	v_add_u32_e32 v2, s91, v2
	ds_read_b64 v[2:3], v2
	s_waitcnt lgkmcnt(0)
	v_readfirstlane_b32 s2, v1
	v_readfirstlane_b32 s6, v0
	v_mbcnt_lo_u32_b32 v0, -1, 0
	v_mbcnt_hi_u32_b32 v0, -1, v0
	v_readfirstlane_b32 s5, v3
	v_add_u32_e32 v1, s57, v0
	v_ashrrev_i32_e32 v1, 6, v1
	v_add_u32_e32 v52, s0, v1
	v_readfirstlane_b32 s4, v2
	v_cmp_gt_i32_e32 vcc, s3, v52
	s_and_saveexec_b64 s[0:1], vcc
	v_readlane_b32 s10, v252, 23
	s_cbranch_execz .LBB0_568
	v_readfirstlane_b32 s100, v52
	v_readlane_b32 s7, v252, 31
	s_nop 3
	s_lshl_b32 s8, s7, 12
	s_mov_b32 s7, s2
	s_add_u32 s6, s6, s8
	s_addc_u32 s7, s7, 0
	s_add_u32 s4, s4, 0x5200000
	s_addc_u32 s5, s5, 0
	v_readlane_b32 s8, v252, 25
	v_readlane_b32 s9, v252, 26
	s_nop 3
	v_lshlrev_b32_e32 v120, 4, v0
	v_lshlrev_b32_e32 v121, 3, v0
	v_lshlrev_b32_e32 v122, 2, v214
	v_lshlrev_b32_e32 v123, 2, v215
	v_lshlrev_b32_e32 v124, 2, v216
	v_lshlrev_b32_e32 v125, 2, v217
	v_lshlrev_b32_e32 v126, 2, v218
	v_lshlrev_b32_e32 v127, 2, v219
	s_lshr_b32 s2, s100, 6
	s_lshl_b32 s2, s2, 11
	s_and_b32 s101, s100, 63
	s_add_u32 s2, s2, s101
	s_lshl_b32 s101, s2, 12
	s_add_u32 s8, s8, s101
	s_addc_u32 s9, s9, 0
	s_lshl_b32 s101, s2, 11
	s_add_u32 s4, s4, s101
	s_addc_u32 s5, s5, 0
	global_load_dwordx4 v[0:3], v120, s[6:7] offset:0
	global_load_dwordx4 v[4:7], v120, s[6:7] offset:1024
	global_load_dwordx4 v[8:11], v120, s[6:7] offset:2048
	global_load_dwordx4 v[12:15], v120, s[6:7] offset:3072
	v_readlane_b32 s6, v252, 32
	v_readlane_b32 s7, v252, 33
	s_lshr_b32 s2, s100, 6
	s_mul_i32 s2, s2, 0x6000
	s_nop 3
	s_add_u32 s6, s6, s2
	s_addc_u32 s7, s7, 0
	s_add_u32 s6, s6, 0x1000
	s_addc_u32 s7, s7, 0
	global_load_dwordx4 v[16:19], v120, s[6:7] offset:0
	global_load_dwordx4 v[20:23], v120, s[6:7] offset:1024
	global_load_dwordx4 v[24:27], v120, s[6:7] offset:2048
	global_load_dwordx4 v[28:31], v120, s[6:7] offset:3072
	s_sub_u32 s6, s6, 0x1000
	s_subb_u32 s7, s7, 0
	global_load_dwordx4 v[32:35], v120, s[6:7] offset:0
	global_load_dwordx4 v[36:39], v120, s[6:7] offset:1024
	global_load_dwordx4 v[40:43], v120, s[6:7] offset:2048
	global_load_dwordx4 v[44:47], v120, s[6:7] offset:3072
	s_waitcnt vmcnt(0)
	v_add_f32_e32 v16, 1.0, v16
	v_add_f32_e32 v17, 1.0, v17
	v_add_f32_e32 v18, 1.0, v18
	v_add_f32_e32 v19, 1.0, v19
	v_add_f32_e32 v20, 1.0, v20
	v_add_f32_e32 v21, 1.0, v21
	v_add_f32_e32 v22, 1.0, v22
	v_add_f32_e32 v23, 1.0, v23
	v_add_f32_e32 v24, 1.0, v24
	v_add_f32_e32 v25, 1.0, v25
	v_add_f32_e32 v26, 1.0, v26
	v_add_f32_e32 v27, 1.0, v27
	v_add_f32_e32 v28, 1.0, v28
	v_add_f32_e32 v29, 1.0, v29
	v_add_f32_e32 v30, 1.0, v30
	v_add_f32_e32 v31, 1.0, v31
	s_movk_i32 s2, 3
	global_load_dwordx4 v[48:51], v120, s[8:9] offset:0 nt
	global_load_dwordx4 v[52:55], v120, s[8:9] offset:1024 nt
	global_load_dwordx4 v[56:59], v120, s[8:9] offset:2048 nt
	global_load_dwordx4 v[60:63], v120, s[8:9] offset:3072 nt
	s_add_u32 s8, s8, 0x40000
	s_addc_u32 s9, s9, 0
	global_load_dwordx4 v[64:67], v120, s[8:9] offset:0 nt
	global_load_dwordx4 v[68:71], v120, s[8:9] offset:1024 nt
	global_load_dwordx4 v[72:75], v120, s[8:9] offset:2048 nt
	global_load_dwordx4 v[76:79], v120, s[8:9] offset:3072 nt
	s_add_u32 s8, s8, 0x40000
	s_addc_u32 s9, s9, 0
	global_load_dwordx4 v[80:83], v120, s[8:9] offset:0 nt
	global_load_dwordx4 v[84:87], v120, s[8:9] offset:1024 nt
	global_load_dwordx4 v[88:91], v120, s[8:9] offset:2048 nt
	global_load_dwordx4 v[92:95], v120, s[8:9] offset:3072 nt
	s_add_u32 s8, s8, 0x40000
	s_addc_u32 s9, s9, 0
	global_load_dwordx4 v[96:99], v120, s[8:9] offset:0 nt
	global_load_dwordx4 v[100:103], v120, s[8:9] offset:1024 nt
	global_load_dwordx4 v[104:107], v120, s[8:9] offset:2048 nt
	global_load_dwordx4 v[108:111], v120, s[8:9] offset:3072 nt
	s_add_u32 s8, s8, 0x40000
	s_addc_u32 s9, s9, 0
	global_load_dwordx4 v[132:135], v120, s[8:9] offset:0 nt
	global_load_dwordx4 v[136:139], v120, s[8:9] offset:1024 nt
	global_load_dwordx4 v[140:143], v120, s[8:9] offset:2048 nt
	global_load_dwordx4 v[144:147], v120, s[8:9] offset:3072 nt
	s_add_u32 s8, s8, 0x40000
	s_addc_u32 s9, s9, 0
	global_load_dwordx4 v[166:169], v120, s[8:9] offset:0 nt
	global_load_dwordx4 v[170:173], v120, s[8:9] offset:1024 nt
	global_load_dwordx4 v[174:177], v120, s[8:9] offset:2048 nt
	global_load_dwordx4 v[178:181], v120, s[8:9] offset:3072 nt
	s_add_u32 s8, s8, 0x40000
	s_addc_u32 s9, s9, 0
	global_load_dwordx4 v[182:185], v120, s[8:9] offset:0 nt
	global_load_dwordx4 v[186:189], v120, s[8:9] offset:1024 nt
	global_load_dwordx4 v[190:193], v120, s[8:9] offset:2048 nt
	global_load_dwordx4 v[194:197], v120, s[8:9] offset:3072 nt
	s_add_u32 s8, s8, 0x40000
	s_addc_u32 s9, s9, 0
	global_load_dwordx4 v[228:231], v120, s[8:9] offset:0 nt
	global_load_dwordx4 v[232:235], v120, s[8:9] offset:1024 nt
	global_load_dwordx4 v[236:239], v120, s[8:9] offset:2048 nt
	global_load_dwordx4 v[240:243], v120, s[8:9] offset:3072 nt
	s_add_u32 s8, s8, 0x40000
	s_addc_u32 s9, s9, 0
	s_waitcnt vmcnt(28)
	v_mul_f32_e32 v112, v48, v48
	v_fmac_f32_e32 v112, v49, v49
	v_fmac_f32_e32 v112, v50, v50
	v_fmac_f32_e32 v112, v51, v51
	v_fmac_f32_e32 v112, v52, v52
	v_fmac_f32_e32 v112, v53, v53
	v_fmac_f32_e32 v112, v54, v54
	v_fmac_f32_e32 v112, v55, v55
	v_fmac_f32_e32 v112, v56, v56
	v_fmac_f32_e32 v112, v57, v57
	v_fmac_f32_e32 v112, v58, v58
	v_fmac_f32_e32 v112, v59, v59
	v_fmac_f32_e32 v112, v60, v60
	v_fmac_f32_e32 v112, v61, v61
	v_fmac_f32_e32 v112, v62, v62
	v_fmac_f32_e32 v112, v63, v63
	s_waitcnt vmcnt(24)
	v_mul_f32_e32 v113, v64, v64
	v_fmac_f32_e32 v113, v65, v65
	v_fmac_f32_e32 v113, v66, v66
	v_fmac_f32_e32 v113, v67, v67
	v_fmac_f32_e32 v113, v68, v68
	v_fmac_f32_e32 v113, v69, v69
	v_fmac_f32_e32 v113, v70, v70
	v_fmac_f32_e32 v113, v71, v71
	v_fmac_f32_e32 v113, v72, v72
	v_fmac_f32_e32 v113, v73, v73
	v_fmac_f32_e32 v113, v74, v74
	v_fmac_f32_e32 v113, v75, v75
	v_fmac_f32_e32 v113, v76, v76
	v_fmac_f32_e32 v113, v77, v77
	v_fmac_f32_e32 v113, v78, v78
	v_fmac_f32_e32 v113, v79, v79
	s_waitcnt vmcnt(20)
	v_mul_f32_e32 v114, v80, v80
	v_fmac_f32_e32 v114, v81, v81
	v_fmac_f32_e32 v114, v82, v82
	v_fmac_f32_e32 v114, v83, v83
	v_fmac_f32_e32 v114, v84, v84
	v_fmac_f32_e32 v114, v85, v85
	v_fmac_f32_e32 v114, v86, v86
	v_fmac_f32_e32 v114, v87, v87
	v_fmac_f32_e32 v114, v88, v88
	v_fmac_f32_e32 v114, v89, v89
	v_fmac_f32_e32 v114, v90, v90
	v_fmac_f32_e32 v114, v91, v91
	v_fmac_f32_e32 v114, v92, v92
	v_fmac_f32_e32 v114, v93, v93
	v_fmac_f32_e32 v114, v94, v94
	v_fmac_f32_e32 v114, v95, v95
	s_waitcnt vmcnt(16)
	v_mul_f32_e32 v115, v96, v96
	v_fmac_f32_e32 v115, v97, v97
	v_fmac_f32_e32 v115, v98, v98
	v_fmac_f32_e32 v115, v99, v99
	v_fmac_f32_e32 v115, v100, v100
	v_fmac_f32_e32 v115, v101, v101
	v_fmac_f32_e32 v115, v102, v102
	v_fmac_f32_e32 v115, v103, v103
	v_fmac_f32_e32 v115, v104, v104
	v_fmac_f32_e32 v115, v105, v105
	v_fmac_f32_e32 v115, v106, v106
	v_fmac_f32_e32 v115, v107, v107
	v_fmac_f32_e32 v115, v108, v108
	v_fmac_f32_e32 v115, v109, v109
	v_fmac_f32_e32 v115, v110, v110
	v_fmac_f32_e32 v115, v111, v111
	ds_bpermute_b32 v116, v122, v112
	ds_bpermute_b32 v117, v122, v113
	ds_bpermute_b32 v118, v122, v114
	ds_bpermute_b32 v119, v122, v115
	s_waitcnt lgkmcnt(0)
	v_add_f32_e32 v112, v112, v116
	v_add_f32_e32 v113, v113, v117
	v_add_f32_e32 v114, v114, v118
	v_add_f32_e32 v115, v115, v119
	ds_bpermute_b32 v116, v123, v112
	ds_bpermute_b32 v117, v123, v113
	ds_bpermute_b32 v118, v123, v114
	ds_bpermute_b32 v119, v123, v115
	s_waitcnt lgkmcnt(0)
	v_add_f32_e32 v112, v112, v116
	v_add_f32_e32 v113, v113, v117
	v_add_f32_e32 v114, v114, v118
	v_add_f32_e32 v115, v115, v119
	ds_bpermute_b32 v116, v124, v112
	ds_bpermute_b32 v117, v124, v113
	ds_bpermute_b32 v118, v124, v114
	ds_bpermute_b32 v119, v124, v115
	s_waitcnt lgkmcnt(0)
	v_add_f32_e32 v112, v112, v116
	v_add_f32_e32 v113, v113, v117
	v_add_f32_e32 v114, v114, v118
	v_add_f32_e32 v115, v115, v119
	ds_bpermute_b32 v116, v125, v112
	ds_bpermute_b32 v117, v125, v113
	ds_bpermute_b32 v118, v125, v114
	ds_bpermute_b32 v119, v125, v115
	s_waitcnt lgkmcnt(0)
	v_add_f32_e32 v112, v112, v116
	v_add_f32_e32 v113, v113, v117
	v_add_f32_e32 v114, v114, v118
	v_add_f32_e32 v115, v115, v119
	ds_bpermute_b32 v116, v126, v112
	ds_bpermute_b32 v117, v126, v113
	ds_bpermute_b32 v118, v126, v114
	ds_bpermute_b32 v119, v126, v115
	s_waitcnt lgkmcnt(0)
	v_add_f32_e32 v112, v112, v116
	v_add_f32_e32 v113, v113, v117
	v_add_f32_e32 v114, v114, v118
	v_add_f32_e32 v115, v115, v119
	ds_bpermute_b32 v116, v127, v112
	ds_bpermute_b32 v117, v127, v113
	ds_bpermute_b32 v118, v127, v114
	ds_bpermute_b32 v119, v127, v115
	s_waitcnt lgkmcnt(0)
	v_add_f32_e32 v112, v112, v116
	v_add_f32_e32 v113, v113, v117
	v_add_f32_e32 v114, v114, v118
	v_add_f32_e32 v115, v115, v119
	v_fmamk_f32 v112, v112, 0x3a800000, v208
	v_fmamk_f32 v113, v113, 0x3a800000, v208
	v_fmamk_f32 v114, v114, 0x3a800000, v208
	v_fmamk_f32 v115, v115, 0x3a800000, v208
	v_rsq_f32_e32 v112, v112
	v_rsq_f32_e32 v113, v113
	v_rsq_f32_e32 v114, v114
	v_rsq_f32_e32 v115, v115
	s_nop 1
	v_mul_f32_e32 v48, v48, v112
	v_mul_f32_e32 v49, v49, v112
	v_mul_f32_e32 v50, v50, v112
	v_mul_f32_e32 v51, v51, v112
	v_mul_f32_e32 v48, v0, v48
	v_mul_f32_e32 v49, v1, v49
	v_mul_f32_e32 v50, v2, v50
	v_mul_f32_e32 v51, v3, v51
	v_fma_f32 v48, v48, v16, v32
	v_fma_f32 v49, v49, v17, v33
	v_fma_f32 v50, v50, v18, v34
	v_fma_f32 v51, v51, v19, v35
	v_cvt_pk_bf16_f32 v128, v48, v49
	v_cvt_pk_bf16_f32 v129, v50, v51
	global_store_dwordx2 v121, v[128:129], s[4:5] offset:0
	v_mul_f32_e32 v52, v52, v112
	v_mul_f32_e32 v53, v53, v112
	v_mul_f32_e32 v54, v54, v112
	v_mul_f32_e32 v55, v55, v112
	v_mul_f32_e32 v52, v4, v52
	v_mul_f32_e32 v53, v5, v53
	v_mul_f32_e32 v54, v6, v54
	v_mul_f32_e32 v55, v7, v55
	v_fma_f32 v52, v52, v20, v36
	v_fma_f32 v53, v53, v21, v37
	v_fma_f32 v54, v54, v22, v38
	v_fma_f32 v55, v55, v23, v39
	v_cvt_pk_bf16_f32 v130, v52, v53
	v_cvt_pk_bf16_f32 v131, v54, v55
	global_store_dwordx2 v121, v[130:131], s[4:5] offset:512
	v_mul_f32_e32 v56, v56, v112
	v_mul_f32_e32 v57, v57, v112
	v_mul_f32_e32 v58, v58, v112
	v_mul_f32_e32 v59, v59, v112
	v_mul_f32_e32 v56, v8, v56
	v_mul_f32_e32 v57, v9, v57
	v_mul_f32_e32 v58, v10, v58
	v_mul_f32_e32 v59, v11, v59
	v_fma_f32 v56, v56, v24, v40
	v_fma_f32 v57, v57, v25, v41
	v_fma_f32 v58, v58, v26, v42
	v_fma_f32 v59, v59, v27, v43
	v_cvt_pk_bf16_f32 v128, v56, v57
	v_cvt_pk_bf16_f32 v129, v58, v59
	global_store_dwordx2 v121, v[128:129], s[4:5] offset:1024
	v_mul_f32_e32 v60, v60, v112
	v_mul_f32_e32 v61, v61, v112
	v_mul_f32_e32 v62, v62, v112
	v_mul_f32_e32 v63, v63, v112
	v_mul_f32_e32 v60, v12, v60
	v_mul_f32_e32 v61, v13, v61
	v_mul_f32_e32 v62, v14, v62
	v_mul_f32_e32 v63, v15, v63
	v_fma_f32 v60, v60, v28, v44
	v_fma_f32 v61, v61, v29, v45
	v_fma_f32 v62, v62, v30, v46
	v_fma_f32 v63, v63, v31, v47
	v_cvt_pk_bf16_f32 v130, v60, v61
	v_cvt_pk_bf16_f32 v131, v62, v63
	global_store_dwordx2 v121, v[130:131], s[4:5] offset:1536
	s_add_u32 s4, s4, 0x20000
	s_addc_u32 s5, s5, 0
	v_mul_f32_e32 v64, v64, v113
	v_mul_f32_e32 v65, v65, v113
	v_mul_f32_e32 v66, v66, v113
	v_mul_f32_e32 v67, v67, v113
	v_mul_f32_e32 v64, v0, v64
	v_mul_f32_e32 v65, v1, v65
	v_mul_f32_e32 v66, v2, v66
	v_mul_f32_e32 v67, v3, v67
	v_fma_f32 v64, v64, v16, v32
	v_fma_f32 v65, v65, v17, v33
	v_fma_f32 v66, v66, v18, v34
	v_fma_f32 v67, v67, v19, v35
	v_cvt_pk_bf16_f32 v128, v64, v65
	v_cvt_pk_bf16_f32 v129, v66, v67
	global_store_dwordx2 v121, v[128:129], s[4:5] offset:0
	v_mul_f32_e32 v68, v68, v113
	v_mul_f32_e32 v69, v69, v113
	v_mul_f32_e32 v70, v70, v113
	v_mul_f32_e32 v71, v71, v113
	v_mul_f32_e32 v68, v4, v68
	v_mul_f32_e32 v69, v5, v69
	v_mul_f32_e32 v70, v6, v70
	v_mul_f32_e32 v71, v7, v71
	v_fma_f32 v68, v68, v20, v36
	v_fma_f32 v69, v69, v21, v37
	v_fma_f32 v70, v70, v22, v38
	v_fma_f32 v71, v71, v23, v39
	v_cvt_pk_bf16_f32 v130, v68, v69
	v_cvt_pk_bf16_f32 v131, v70, v71
	global_store_dwordx2 v121, v[130:131], s[4:5] offset:512
	v_mul_f32_e32 v72, v72, v113
	v_mul_f32_e32 v73, v73, v113
	v_mul_f32_e32 v74, v74, v113
	v_mul_f32_e32 v75, v75, v113
	v_mul_f32_e32 v72, v8, v72
	v_mul_f32_e32 v73, v9, v73
	v_mul_f32_e32 v74, v10, v74
	v_mul_f32_e32 v75, v11, v75
	v_fma_f32 v72, v72, v24, v40
	v_fma_f32 v73, v73, v25, v41
	v_fma_f32 v74, v74, v26, v42
	v_fma_f32 v75, v75, v27, v43
	v_cvt_pk_bf16_f32 v128, v72, v73
	v_cvt_pk_bf16_f32 v129, v74, v75
	global_store_dwordx2 v121, v[128:129], s[4:5] offset:1024
	v_mul_f32_e32 v76, v76, v113
	v_mul_f32_e32 v77, v77, v113
	v_mul_f32_e32 v78, v78, v113
	v_mul_f32_e32 v79, v79, v113
	v_mul_f32_e32 v76, v12, v76
	v_mul_f32_e32 v77, v13, v77
	v_mul_f32_e32 v78, v14, v78
	v_mul_f32_e32 v79, v15, v79
	v_fma_f32 v76, v76, v28, v44
	v_fma_f32 v77, v77, v29, v45
	v_fma_f32 v78, v78, v30, v46
	v_fma_f32 v79, v79, v31, v47
	v_cvt_pk_bf16_f32 v130, v76, v77
	v_cvt_pk_bf16_f32 v131, v78, v79
	global_store_dwordx2 v121, v[130:131], s[4:5] offset:1536
	s_add_u32 s4, s4, 0x20000
	s_addc_u32 s5, s5, 0
	v_mul_f32_e32 v80, v80, v114
	v_mul_f32_e32 v81, v81, v114
	v_mul_f32_e32 v82, v82, v114
	v_mul_f32_e32 v83, v83, v114
	v_mul_f32_e32 v80, v0, v80
	v_mul_f32_e32 v81, v1, v81
	v_mul_f32_e32 v82, v2, v82
	v_mul_f32_e32 v83, v3, v83
	v_fma_f32 v80, v80, v16, v32
	v_fma_f32 v81, v81, v17, v33
	v_fma_f32 v82, v82, v18, v34
	v_fma_f32 v83, v83, v19, v35
	v_cvt_pk_bf16_f32 v128, v80, v81
	v_cvt_pk_bf16_f32 v129, v82, v83
	global_store_dwordx2 v121, v[128:129], s[4:5] offset:0
	v_mul_f32_e32 v84, v84, v114
	v_mul_f32_e32 v85, v85, v114
	v_mul_f32_e32 v86, v86, v114
	v_mul_f32_e32 v87, v87, v114
	v_mul_f32_e32 v84, v4, v84
	v_mul_f32_e32 v85, v5, v85
	v_mul_f32_e32 v86, v6, v86
	v_mul_f32_e32 v87, v7, v87
	v_fma_f32 v84, v84, v20, v36
	v_fma_f32 v85, v85, v21, v37
	v_fma_f32 v86, v86, v22, v38
	v_fma_f32 v87, v87, v23, v39
	v_cvt_pk_bf16_f32 v130, v84, v85
	v_cvt_pk_bf16_f32 v131, v86, v87
	global_store_dwordx2 v121, v[130:131], s[4:5] offset:512
	v_mul_f32_e32 v88, v88, v114
	v_mul_f32_e32 v89, v89, v114
	v_mul_f32_e32 v90, v90, v114
	v_mul_f32_e32 v91, v91, v114
	v_mul_f32_e32 v88, v8, v88
	v_mul_f32_e32 v89, v9, v89
	v_mul_f32_e32 v90, v10, v90
	v_mul_f32_e32 v91, v11, v91
	v_fma_f32 v88, v88, v24, v40
	v_fma_f32 v89, v89, v25, v41
	v_fma_f32 v90, v90, v26, v42
	v_fma_f32 v91, v91, v27, v43
	v_cvt_pk_bf16_f32 v128, v88, v89
	v_cvt_pk_bf16_f32 v129, v90, v91
	global_store_dwordx2 v121, v[128:129], s[4:5] offset:1024
	v_mul_f32_e32 v92, v92, v114
	v_mul_f32_e32 v93, v93, v114
	v_mul_f32_e32 v94, v94, v114
	v_mul_f32_e32 v95, v95, v114
	v_mul_f32_e32 v92, v12, v92
	v_mul_f32_e32 v93, v13, v93
	v_mul_f32_e32 v94, v14, v94
	v_mul_f32_e32 v95, v15, v95
	v_fma_f32 v92, v92, v28, v44
	v_fma_f32 v93, v93, v29, v45
	v_fma_f32 v94, v94, v30, v46
	v_fma_f32 v95, v95, v31, v47
	v_cvt_pk_bf16_f32 v130, v92, v93
	v_cvt_pk_bf16_f32 v131, v94, v95
	global_store_dwordx2 v121, v[130:131], s[4:5] offset:1536
	s_add_u32 s4, s4, 0x20000
	s_addc_u32 s5, s5, 0
	v_mul_f32_e32 v96, v96, v115
	v_mul_f32_e32 v97, v97, v115
	v_mul_f32_e32 v98, v98, v115
	v_mul_f32_e32 v99, v99, v115
	v_mul_f32_e32 v96, v0, v96
	v_mul_f32_e32 v97, v1, v97
	v_mul_f32_e32 v98, v2, v98
	v_mul_f32_e32 v99, v3, v99
	v_fma_f32 v96, v96, v16, v32
	v_fma_f32 v97, v97, v17, v33
	v_fma_f32 v98, v98, v18, v34
	v_fma_f32 v99, v99, v19, v35
	v_cvt_pk_bf16_f32 v128, v96, v97
	v_cvt_pk_bf16_f32 v129, v98, v99
	global_store_dwordx2 v121, v[128:129], s[4:5] offset:0
	v_mul_f32_e32 v100, v100, v115
	v_mul_f32_e32 v101, v101, v115
	v_mul_f32_e32 v102, v102, v115
	v_mul_f32_e32 v103, v103, v115
	v_mul_f32_e32 v100, v4, v100
	v_mul_f32_e32 v101, v5, v101
	v_mul_f32_e32 v102, v6, v102
	v_mul_f32_e32 v103, v7, v103
	v_fma_f32 v100, v100, v20, v36
	v_fma_f32 v101, v101, v21, v37
	v_fma_f32 v102, v102, v22, v38
	v_fma_f32 v103, v103, v23, v39
	v_cvt_pk_bf16_f32 v130, v100, v101
	v_cvt_pk_bf16_f32 v131, v102, v103
	global_store_dwordx2 v121, v[130:131], s[4:5] offset:512
	v_mul_f32_e32 v104, v104, v115
	v_mul_f32_e32 v105, v105, v115
	v_mul_f32_e32 v106, v106, v115
	v_mul_f32_e32 v107, v107, v115
	v_mul_f32_e32 v104, v8, v104
	v_mul_f32_e32 v105, v9, v105
	v_mul_f32_e32 v106, v10, v106
	v_mul_f32_e32 v107, v11, v107
	v_fma_f32 v104, v104, v24, v40
	v_fma_f32 v105, v105, v25, v41
	v_fma_f32 v106, v106, v26, v42
	v_fma_f32 v107, v107, v27, v43
	v_cvt_pk_bf16_f32 v128, v104, v105
	v_cvt_pk_bf16_f32 v129, v106, v107
	global_store_dwordx2 v121, v[128:129], s[4:5] offset:1024
	v_mul_f32_e32 v108, v108, v115
	v_mul_f32_e32 v109, v109, v115
	v_mul_f32_e32 v110, v110, v115
	v_mul_f32_e32 v111, v111, v115
	v_mul_f32_e32 v108, v12, v108
	v_mul_f32_e32 v109, v13, v109
	v_mul_f32_e32 v110, v14, v110
	v_mul_f32_e32 v111, v15, v111
	v_fma_f32 v108, v108, v28, v44
	v_fma_f32 v109, v109, v29, v45
	v_fma_f32 v110, v110, v30, v46
	v_fma_f32 v111, v111, v31, v47
	v_cvt_pk_bf16_f32 v130, v108, v109
	v_cvt_pk_bf16_f32 v131, v110, v111
	global_store_dwordx2 v121, v[130:131], s[4:5] offset:1536
	s_add_u32 s4, s4, 0x20000
	s_addc_u32 s5, s5, 0
.Lrms_sub0_loop:
	global_load_dwordx4 v[48:51], v120, s[8:9] offset:0 nt
	global_load_dwordx4 v[52:55], v120, s[8:9] offset:1024 nt
	global_load_dwordx4 v[56:59], v120, s[8:9] offset:2048 nt
	global_load_dwordx4 v[60:63], v120, s[8:9] offset:3072 nt
	s_add_u32 s8, s8, 0x40000
	s_addc_u32 s9, s9, 0
	global_load_dwordx4 v[64:67], v120, s[8:9] offset:0 nt
	global_load_dwordx4 v[68:71], v120, s[8:9] offset:1024 nt
	global_load_dwordx4 v[72:75], v120, s[8:9] offset:2048 nt
	global_load_dwordx4 v[76:79], v120, s[8:9] offset:3072 nt
	s_add_u32 s8, s8, 0x40000
	s_addc_u32 s9, s9, 0
	global_load_dwordx4 v[80:83], v120, s[8:9] offset:0 nt
	global_load_dwordx4 v[84:87], v120, s[8:9] offset:1024 nt
	global_load_dwordx4 v[88:91], v120, s[8:9] offset:2048 nt
	global_load_dwordx4 v[92:95], v120, s[8:9] offset:3072 nt
	s_add_u32 s8, s8, 0x40000
	s_addc_u32 s9, s9, 0
	global_load_dwordx4 v[96:99], v120, s[8:9] offset:0 nt
	global_load_dwordx4 v[100:103], v120, s[8:9] offset:1024 nt
	global_load_dwordx4 v[104:107], v120, s[8:9] offset:2048 nt
	global_load_dwordx4 v[108:111], v120, s[8:9] offset:3072 nt
	s_add_u32 s8, s8, 0x40000
	s_addc_u32 s9, s9, 0
	s_waitcnt vmcnt(44)
	v_mul_f32_e32 v112, v132, v132
	v_fmac_f32_e32 v112, v133, v133
	v_fmac_f32_e32 v112, v134, v134
	v_fmac_f32_e32 v112, v135, v135
	v_fmac_f32_e32 v112, v136, v136
	v_fmac_f32_e32 v112, v137, v137
	v_fmac_f32_e32 v112, v138, v138
	v_fmac_f32_e32 v112, v139, v139
	v_fmac_f32_e32 v112, v140, v140
	v_fmac_f32_e32 v112, v141, v141
	v_fmac_f32_e32 v112, v142, v142
	v_fmac_f32_e32 v112, v143, v143
	v_fmac_f32_e32 v112, v144, v144
	v_fmac_f32_e32 v112, v145, v145
	v_fmac_f32_e32 v112, v146, v146
	v_fmac_f32_e32 v112, v147, v147
	s_waitcnt vmcnt(40)
	v_mul_f32_e32 v113, v166, v166
	v_fmac_f32_e32 v113, v167, v167
	v_fmac_f32_e32 v113, v168, v168
	v_fmac_f32_e32 v113, v169, v169
	v_fmac_f32_e32 v113, v170, v170
	v_fmac_f32_e32 v113, v171, v171
	v_fmac_f32_e32 v113, v172, v172
	v_fmac_f32_e32 v113, v173, v173
	v_fmac_f32_e32 v113, v174, v174
	v_fmac_f32_e32 v113, v175, v175
	v_fmac_f32_e32 v113, v176, v176
	v_fmac_f32_e32 v113, v177, v177
	v_fmac_f32_e32 v113, v178, v178
	v_fmac_f32_e32 v113, v179, v179
	v_fmac_f32_e32 v113, v180, v180
	v_fmac_f32_e32 v113, v181, v181
	s_waitcnt vmcnt(36)
	v_mul_f32_e32 v114, v182, v182
	v_fmac_f32_e32 v114, v183, v183
	v_fmac_f32_e32 v114, v184, v184
	v_fmac_f32_e32 v114, v185, v185
	v_fmac_f32_e32 v114, v186, v186
	v_fmac_f32_e32 v114, v187, v187
	v_fmac_f32_e32 v114, v188, v188
	v_fmac_f32_e32 v114, v189, v189
	v_fmac_f32_e32 v114, v190, v190
	v_fmac_f32_e32 v114, v191, v191
	v_fmac_f32_e32 v114, v192, v192
	v_fmac_f32_e32 v114, v193, v193
	v_fmac_f32_e32 v114, v194, v194
	v_fmac_f32_e32 v114, v195, v195
	v_fmac_f32_e32 v114, v196, v196
	v_fmac_f32_e32 v114, v197, v197
	s_waitcnt vmcnt(32)
	v_mul_f32_e32 v115, v228, v228
	v_fmac_f32_e32 v115, v229, v229
	v_fmac_f32_e32 v115, v230, v230
	v_fmac_f32_e32 v115, v231, v231
	v_fmac_f32_e32 v115, v232, v232
	v_fmac_f32_e32 v115, v233, v233
	v_fmac_f32_e32 v115, v234, v234
	v_fmac_f32_e32 v115, v235, v235
	v_fmac_f32_e32 v115, v236, v236
	v_fmac_f32_e32 v115, v237, v237
	v_fmac_f32_e32 v115, v238, v238
	v_fmac_f32_e32 v115, v239, v239
	v_fmac_f32_e32 v115, v240, v240
	v_fmac_f32_e32 v115, v241, v241
	v_fmac_f32_e32 v115, v242, v242
	v_fmac_f32_e32 v115, v243, v243
	ds_bpermute_b32 v116, v122, v112
	ds_bpermute_b32 v117, v122, v113
	ds_bpermute_b32 v118, v122, v114
	ds_bpermute_b32 v119, v122, v115
	s_waitcnt lgkmcnt(0)
	v_add_f32_e32 v112, v112, v116
	v_add_f32_e32 v113, v113, v117
	v_add_f32_e32 v114, v114, v118
	v_add_f32_e32 v115, v115, v119
	ds_bpermute_b32 v116, v123, v112
	ds_bpermute_b32 v117, v123, v113
	ds_bpermute_b32 v118, v123, v114
	ds_bpermute_b32 v119, v123, v115
	s_waitcnt lgkmcnt(0)
	v_add_f32_e32 v112, v112, v116
	v_add_f32_e32 v113, v113, v117
	v_add_f32_e32 v114, v114, v118
	v_add_f32_e32 v115, v115, v119
	ds_bpermute_b32 v116, v124, v112
	ds_bpermute_b32 v117, v124, v113
	ds_bpermute_b32 v118, v124, v114
	ds_bpermute_b32 v119, v124, v115
	s_waitcnt lgkmcnt(0)
	v_add_f32_e32 v112, v112, v116
	v_add_f32_e32 v113, v113, v117
	v_add_f32_e32 v114, v114, v118
	v_add_f32_e32 v115, v115, v119
	ds_bpermute_b32 v116, v125, v112
	ds_bpermute_b32 v117, v125, v113
	ds_bpermute_b32 v118, v125, v114
	ds_bpermute_b32 v119, v125, v115
	s_waitcnt lgkmcnt(0)
	v_add_f32_e32 v112, v112, v116
	v_add_f32_e32 v113, v113, v117
	v_add_f32_e32 v114, v114, v118
	v_add_f32_e32 v115, v115, v119
	ds_bpermute_b32 v116, v126, v112
	ds_bpermute_b32 v117, v126, v113
	ds_bpermute_b32 v118, v126, v114
	ds_bpermute_b32 v119, v126, v115
	s_waitcnt lgkmcnt(0)
	v_add_f32_e32 v112, v112, v116
	v_add_f32_e32 v113, v113, v117
	v_add_f32_e32 v114, v114, v118
	v_add_f32_e32 v115, v115, v119
	ds_bpermute_b32 v116, v127, v112
	ds_bpermute_b32 v117, v127, v113
	ds_bpermute_b32 v118, v127, v114
	ds_bpermute_b32 v119, v127, v115
	s_waitcnt lgkmcnt(0)
	v_add_f32_e32 v112, v112, v116
	v_add_f32_e32 v113, v113, v117
	v_add_f32_e32 v114, v114, v118
	v_add_f32_e32 v115, v115, v119
	v_fmamk_f32 v112, v112, 0x3a800000, v208
	v_fmamk_f32 v113, v113, 0x3a800000, v208
	v_fmamk_f32 v114, v114, 0x3a800000, v208
	v_fmamk_f32 v115, v115, 0x3a800000, v208
	v_rsq_f32_e32 v112, v112
	v_rsq_f32_e32 v113, v113
	v_rsq_f32_e32 v114, v114
	v_rsq_f32_e32 v115, v115
	s_nop 1
	v_mul_f32_e32 v132, v132, v112
	v_mul_f32_e32 v133, v133, v112
	v_mul_f32_e32 v134, v134, v112
	v_mul_f32_e32 v135, v135, v112
	v_mul_f32_e32 v132, v0, v132
	v_mul_f32_e32 v133, v1, v133
	v_mul_f32_e32 v134, v2, v134
	v_mul_f32_e32 v135, v3, v135
	v_fma_f32 v132, v132, v16, v32
	v_fma_f32 v133, v133, v17, v33
	v_fma_f32 v134, v134, v18, v34
	v_fma_f32 v135, v135, v19, v35
	v_cvt_pk_bf16_f32 v128, v132, v133
	v_cvt_pk_bf16_f32 v129, v134, v135
	global_store_dwordx2 v121, v[128:129], s[4:5] offset:0
	v_mul_f32_e32 v136, v136, v112
	v_mul_f32_e32 v137, v137, v112
	v_mul_f32_e32 v138, v138, v112
	v_mul_f32_e32 v139, v139, v112
	v_mul_f32_e32 v136, v4, v136
	v_mul_f32_e32 v137, v5, v137
	v_mul_f32_e32 v138, v6, v138
	v_mul_f32_e32 v139, v7, v139
	v_fma_f32 v136, v136, v20, v36
	v_fma_f32 v137, v137, v21, v37
	v_fma_f32 v138, v138, v22, v38
	v_fma_f32 v139, v139, v23, v39
	v_cvt_pk_bf16_f32 v130, v136, v137
	v_cvt_pk_bf16_f32 v131, v138, v139
	global_store_dwordx2 v121, v[130:131], s[4:5] offset:512
	v_mul_f32_e32 v140, v140, v112
	v_mul_f32_e32 v141, v141, v112
	v_mul_f32_e32 v142, v142, v112
	v_mul_f32_e32 v143, v143, v112
	v_mul_f32_e32 v140, v8, v140
	v_mul_f32_e32 v141, v9, v141
	v_mul_f32_e32 v142, v10, v142
	v_mul_f32_e32 v143, v11, v143
	v_fma_f32 v140, v140, v24, v40
	v_fma_f32 v141, v141, v25, v41
	v_fma_f32 v142, v142, v26, v42
	v_fma_f32 v143, v143, v27, v43
	v_cvt_pk_bf16_f32 v128, v140, v141
	v_cvt_pk_bf16_f32 v129, v142, v143
	global_store_dwordx2 v121, v[128:129], s[4:5] offset:1024
	v_mul_f32_e32 v144, v144, v112
	v_mul_f32_e32 v145, v145, v112
	v_mul_f32_e32 v146, v146, v112
	v_mul_f32_e32 v147, v147, v112
	v_mul_f32_e32 v144, v12, v144
	v_mul_f32_e32 v145, v13, v145
	v_mul_f32_e32 v146, v14, v146
	v_mul_f32_e32 v147, v15, v147
	v_fma_f32 v144, v144, v28, v44
	v_fma_f32 v145, v145, v29, v45
	v_fma_f32 v146, v146, v30, v46
	v_fma_f32 v147, v147, v31, v47
	v_cvt_pk_bf16_f32 v130, v144, v145
	v_cvt_pk_bf16_f32 v131, v146, v147
	global_store_dwordx2 v121, v[130:131], s[4:5] offset:1536
	s_add_u32 s4, s4, 0x20000
	s_addc_u32 s5, s5, 0
	v_mul_f32_e32 v166, v166, v113
	v_mul_f32_e32 v167, v167, v113
	v_mul_f32_e32 v168, v168, v113
	v_mul_f32_e32 v169, v169, v113
	v_mul_f32_e32 v166, v0, v166
	v_mul_f32_e32 v167, v1, v167
	v_mul_f32_e32 v168, v2, v168
	v_mul_f32_e32 v169, v3, v169
	v_fma_f32 v166, v166, v16, v32
	v_fma_f32 v167, v167, v17, v33
	v_fma_f32 v168, v168, v18, v34
	v_fma_f32 v169, v169, v19, v35
	v_cvt_pk_bf16_f32 v128, v166, v167
	v_cvt_pk_bf16_f32 v129, v168, v169
	global_store_dwordx2 v121, v[128:129], s[4:5] offset:0
	v_mul_f32_e32 v170, v170, v113
	v_mul_f32_e32 v171, v171, v113
	v_mul_f32_e32 v172, v172, v113
	v_mul_f32_e32 v173, v173, v113
	v_mul_f32_e32 v170, v4, v170
	v_mul_f32_e32 v171, v5, v171
	v_mul_f32_e32 v172, v6, v172
	v_mul_f32_e32 v173, v7, v173
	v_fma_f32 v170, v170, v20, v36
	v_fma_f32 v171, v171, v21, v37
	v_fma_f32 v172, v172, v22, v38
	v_fma_f32 v173, v173, v23, v39
	v_cvt_pk_bf16_f32 v130, v170, v171
	v_cvt_pk_bf16_f32 v131, v172, v173
	global_store_dwordx2 v121, v[130:131], s[4:5] offset:512
	v_mul_f32_e32 v174, v174, v113
	v_mul_f32_e32 v175, v175, v113
	v_mul_f32_e32 v176, v176, v113
	v_mul_f32_e32 v177, v177, v113
	v_mul_f32_e32 v174, v8, v174
	v_mul_f32_e32 v175, v9, v175
	v_mul_f32_e32 v176, v10, v176
	v_mul_f32_e32 v177, v11, v177
	v_fma_f32 v174, v174, v24, v40
	v_fma_f32 v175, v175, v25, v41
	v_fma_f32 v176, v176, v26, v42
	v_fma_f32 v177, v177, v27, v43
	v_cvt_pk_bf16_f32 v128, v174, v175
	v_cvt_pk_bf16_f32 v129, v176, v177
	global_store_dwordx2 v121, v[128:129], s[4:5] offset:1024
	v_mul_f32_e32 v178, v178, v113
	v_mul_f32_e32 v179, v179, v113
	v_mul_f32_e32 v180, v180, v113
	v_mul_f32_e32 v181, v181, v113
	v_mul_f32_e32 v178, v12, v178
	v_mul_f32_e32 v179, v13, v179
	v_mul_f32_e32 v180, v14, v180
	v_mul_f32_e32 v181, v15, v181
	v_fma_f32 v178, v178, v28, v44
	v_fma_f32 v179, v179, v29, v45
	v_fma_f32 v180, v180, v30, v46
	v_fma_f32 v181, v181, v31, v47
	v_cvt_pk_bf16_f32 v130, v178, v179
	v_cvt_pk_bf16_f32 v131, v180, v181
	global_store_dwordx2 v121, v[130:131], s[4:5] offset:1536
	s_add_u32 s4, s4, 0x20000
	s_addc_u32 s5, s5, 0
	v_mul_f32_e32 v182, v182, v114
	v_mul_f32_e32 v183, v183, v114
	v_mul_f32_e32 v184, v184, v114
	v_mul_f32_e32 v185, v185, v114
	v_mul_f32_e32 v182, v0, v182
	v_mul_f32_e32 v183, v1, v183
	v_mul_f32_e32 v184, v2, v184
	v_mul_f32_e32 v185, v3, v185
	v_fma_f32 v182, v182, v16, v32
	v_fma_f32 v183, v183, v17, v33
	v_fma_f32 v184, v184, v18, v34
	v_fma_f32 v185, v185, v19, v35
	v_cvt_pk_bf16_f32 v128, v182, v183
	v_cvt_pk_bf16_f32 v129, v184, v185
	global_store_dwordx2 v121, v[128:129], s[4:5] offset:0
	v_mul_f32_e32 v186, v186, v114
	v_mul_f32_e32 v187, v187, v114
	v_mul_f32_e32 v188, v188, v114
	v_mul_f32_e32 v189, v189, v114
	v_mul_f32_e32 v186, v4, v186
	v_mul_f32_e32 v187, v5, v187
	v_mul_f32_e32 v188, v6, v188
	v_mul_f32_e32 v189, v7, v189
	v_fma_f32 v186, v186, v20, v36
	v_fma_f32 v187, v187, v21, v37
	v_fma_f32 v188, v188, v22, v38
	v_fma_f32 v189, v189, v23, v39
	v_cvt_pk_bf16_f32 v130, v186, v187
	v_cvt_pk_bf16_f32 v131, v188, v189
	global_store_dwordx2 v121, v[130:131], s[4:5] offset:512
	v_mul_f32_e32 v190, v190, v114
	v_mul_f32_e32 v191, v191, v114
	v_mul_f32_e32 v192, v192, v114
	v_mul_f32_e32 v193, v193, v114
	v_mul_f32_e32 v190, v8, v190
	v_mul_f32_e32 v191, v9, v191
	v_mul_f32_e32 v192, v10, v192
	v_mul_f32_e32 v193, v11, v193
	v_fma_f32 v190, v190, v24, v40
	v_fma_f32 v191, v191, v25, v41
	v_fma_f32 v192, v192, v26, v42
	v_fma_f32 v193, v193, v27, v43
	v_cvt_pk_bf16_f32 v128, v190, v191
	v_cvt_pk_bf16_f32 v129, v192, v193
	global_store_dwordx2 v121, v[128:129], s[4:5] offset:1024
	v_mul_f32_e32 v194, v194, v114
	v_mul_f32_e32 v195, v195, v114
	v_mul_f32_e32 v196, v196, v114
	v_mul_f32_e32 v197, v197, v114
	v_mul_f32_e32 v194, v12, v194
	v_mul_f32_e32 v195, v13, v195
	v_mul_f32_e32 v196, v14, v196
	v_mul_f32_e32 v197, v15, v197
	v_fma_f32 v194, v194, v28, v44
	v_fma_f32 v195, v195, v29, v45
	v_fma_f32 v196, v196, v30, v46
	v_fma_f32 v197, v197, v31, v47
	v_cvt_pk_bf16_f32 v130, v194, v195
	v_cvt_pk_bf16_f32 v131, v196, v197
	global_store_dwordx2 v121, v[130:131], s[4:5] offset:1536
	s_add_u32 s4, s4, 0x20000
	s_addc_u32 s5, s5, 0
	v_mul_f32_e32 v228, v228, v115
	v_mul_f32_e32 v229, v229, v115
	v_mul_f32_e32 v230, v230, v115
	v_mul_f32_e32 v231, v231, v115
	v_mul_f32_e32 v228, v0, v228
	v_mul_f32_e32 v229, v1, v229
	v_mul_f32_e32 v230, v2, v230
	v_mul_f32_e32 v231, v3, v231
	v_fma_f32 v228, v228, v16, v32
	v_fma_f32 v229, v229, v17, v33
	v_fma_f32 v230, v230, v18, v34
	v_fma_f32 v231, v231, v19, v35
	v_cvt_pk_bf16_f32 v128, v228, v229
	v_cvt_pk_bf16_f32 v129, v230, v231
	global_store_dwordx2 v121, v[128:129], s[4:5] offset:0
	v_mul_f32_e32 v232, v232, v115
	v_mul_f32_e32 v233, v233, v115
	v_mul_f32_e32 v234, v234, v115
	v_mul_f32_e32 v235, v235, v115
	v_mul_f32_e32 v232, v4, v232
	v_mul_f32_e32 v233, v5, v233
	v_mul_f32_e32 v234, v6, v234
	v_mul_f32_e32 v235, v7, v235
	v_fma_f32 v232, v232, v20, v36
	v_fma_f32 v233, v233, v21, v37
	v_fma_f32 v234, v234, v22, v38
	v_fma_f32 v235, v235, v23, v39
	v_cvt_pk_bf16_f32 v130, v232, v233
	v_cvt_pk_bf16_f32 v131, v234, v235
	global_store_dwordx2 v121, v[130:131], s[4:5] offset:512
	v_mul_f32_e32 v236, v236, v115
	v_mul_f32_e32 v237, v237, v115
	v_mul_f32_e32 v238, v238, v115
	v_mul_f32_e32 v239, v239, v115
	v_mul_f32_e32 v236, v8, v236
	v_mul_f32_e32 v237, v9, v237
	v_mul_f32_e32 v238, v10, v238
	v_mul_f32_e32 v239, v11, v239
	v_fma_f32 v236, v236, v24, v40
	v_fma_f32 v237, v237, v25, v41
	v_fma_f32 v238, v238, v26, v42
	v_fma_f32 v239, v239, v27, v43
	v_cvt_pk_bf16_f32 v128, v236, v237
	v_cvt_pk_bf16_f32 v129, v238, v239
	global_store_dwordx2 v121, v[128:129], s[4:5] offset:1024
	v_mul_f32_e32 v240, v240, v115
	v_mul_f32_e32 v241, v241, v115
	v_mul_f32_e32 v242, v242, v115
	v_mul_f32_e32 v243, v243, v115
	v_mul_f32_e32 v240, v12, v240
	v_mul_f32_e32 v241, v13, v241
	v_mul_f32_e32 v242, v14, v242
	v_mul_f32_e32 v243, v15, v243
	v_fma_f32 v240, v240, v28, v44
	v_fma_f32 v241, v241, v29, v45
	v_fma_f32 v242, v242, v30, v46
	v_fma_f32 v243, v243, v31, v47
	v_cvt_pk_bf16_f32 v130, v240, v241
	v_cvt_pk_bf16_f32 v131, v242, v243
	global_store_dwordx2 v121, v[130:131], s[4:5] offset:1536
	s_add_u32 s4, s4, 0x20000
	s_addc_u32 s5, s5, 0
	global_load_dwordx4 v[132:135], v120, s[8:9] offset:0 nt
	global_load_dwordx4 v[136:139], v120, s[8:9] offset:1024 nt
	global_load_dwordx4 v[140:143], v120, s[8:9] offset:2048 nt
	global_load_dwordx4 v[144:147], v120, s[8:9] offset:3072 nt
	s_add_u32 s8, s8, 0x40000
	s_addc_u32 s9, s9, 0
	global_load_dwordx4 v[166:169], v120, s[8:9] offset:0 nt
	global_load_dwordx4 v[170:173], v120, s[8:9] offset:1024 nt
	global_load_dwordx4 v[174:177], v120, s[8:9] offset:2048 nt
	global_load_dwordx4 v[178:181], v120, s[8:9] offset:3072 nt
	s_add_u32 s8, s8, 0x40000
	s_addc_u32 s9, s9, 0
	global_load_dwordx4 v[182:185], v120, s[8:9] offset:0 nt
	global_load_dwordx4 v[186:189], v120, s[8:9] offset:1024 nt
	global_load_dwordx4 v[190:193], v120, s[8:9] offset:2048 nt
	global_load_dwordx4 v[194:197], v120, s[8:9] offset:3072 nt
	s_add_u32 s8, s8, 0x40000
	s_addc_u32 s9, s9, 0
	global_load_dwordx4 v[228:231], v120, s[8:9] offset:0 nt
	global_load_dwordx4 v[232:235], v120, s[8:9] offset:1024 nt
	global_load_dwordx4 v[236:239], v120, s[8:9] offset:2048 nt
	global_load_dwordx4 v[240:243], v120, s[8:9] offset:3072 nt
	s_add_u32 s8, s8, 0x40000
	s_addc_u32 s9, s9, 0
	s_waitcnt vmcnt(44)
	v_mul_f32_e32 v112, v48, v48
	v_fmac_f32_e32 v112, v49, v49
	v_fmac_f32_e32 v112, v50, v50
	v_fmac_f32_e32 v112, v51, v51
	v_fmac_f32_e32 v112, v52, v52
	v_fmac_f32_e32 v112, v53, v53
	v_fmac_f32_e32 v112, v54, v54
	v_fmac_f32_e32 v112, v55, v55
	v_fmac_f32_e32 v112, v56, v56
	v_fmac_f32_e32 v112, v57, v57
	v_fmac_f32_e32 v112, v58, v58
	v_fmac_f32_e32 v112, v59, v59
	v_fmac_f32_e32 v112, v60, v60
	v_fmac_f32_e32 v112, v61, v61
	v_fmac_f32_e32 v112, v62, v62
	v_fmac_f32_e32 v112, v63, v63
	s_waitcnt vmcnt(40)
	v_mul_f32_e32 v113, v64, v64
	v_fmac_f32_e32 v113, v65, v65
	v_fmac_f32_e32 v113, v66, v66
	v_fmac_f32_e32 v113, v67, v67
	v_fmac_f32_e32 v113, v68, v68
	v_fmac_f32_e32 v113, v69, v69
	v_fmac_f32_e32 v113, v70, v70
	v_fmac_f32_e32 v113, v71, v71
	v_fmac_f32_e32 v113, v72, v72
	v_fmac_f32_e32 v113, v73, v73
	v_fmac_f32_e32 v113, v74, v74
	v_fmac_f32_e32 v113, v75, v75
	v_fmac_f32_e32 v113, v76, v76
	v_fmac_f32_e32 v113, v77, v77
	v_fmac_f32_e32 v113, v78, v78
	v_fmac_f32_e32 v113, v79, v79
	s_waitcnt vmcnt(36)
	v_mul_f32_e32 v114, v80, v80
	v_fmac_f32_e32 v114, v81, v81
	v_fmac_f32_e32 v114, v82, v82
	v_fmac_f32_e32 v114, v83, v83
	v_fmac_f32_e32 v114, v84, v84
	v_fmac_f32_e32 v114, v85, v85
	v_fmac_f32_e32 v114, v86, v86
	v_fmac_f32_e32 v114, v87, v87
	v_fmac_f32_e32 v114, v88, v88
	v_fmac_f32_e32 v114, v89, v89
	v_fmac_f32_e32 v114, v90, v90
	v_fmac_f32_e32 v114, v91, v91
	v_fmac_f32_e32 v114, v92, v92
	v_fmac_f32_e32 v114, v93, v93
	v_fmac_f32_e32 v114, v94, v94
	v_fmac_f32_e32 v114, v95, v95
	s_waitcnt vmcnt(32)
	v_mul_f32_e32 v115, v96, v96
	v_fmac_f32_e32 v115, v97, v97
	v_fmac_f32_e32 v115, v98, v98
	v_fmac_f32_e32 v115, v99, v99
	v_fmac_f32_e32 v115, v100, v100
	v_fmac_f32_e32 v115, v101, v101
	v_fmac_f32_e32 v115, v102, v102
	v_fmac_f32_e32 v115, v103, v103
	v_fmac_f32_e32 v115, v104, v104
	v_fmac_f32_e32 v115, v105, v105
	v_fmac_f32_e32 v115, v106, v106
	v_fmac_f32_e32 v115, v107, v107
	v_fmac_f32_e32 v115, v108, v108
	v_fmac_f32_e32 v115, v109, v109
	v_fmac_f32_e32 v115, v110, v110
	v_fmac_f32_e32 v115, v111, v111
	ds_bpermute_b32 v116, v122, v112
	ds_bpermute_b32 v117, v122, v113
	ds_bpermute_b32 v118, v122, v114
	ds_bpermute_b32 v119, v122, v115
	s_waitcnt lgkmcnt(0)
	v_add_f32_e32 v112, v112, v116
	v_add_f32_e32 v113, v113, v117
	v_add_f32_e32 v114, v114, v118
	v_add_f32_e32 v115, v115, v119
	ds_bpermute_b32 v116, v123, v112
	ds_bpermute_b32 v117, v123, v113
	ds_bpermute_b32 v118, v123, v114
	ds_bpermute_b32 v119, v123, v115
	s_waitcnt lgkmcnt(0)
	v_add_f32_e32 v112, v112, v116
	v_add_f32_e32 v113, v113, v117
	v_add_f32_e32 v114, v114, v118
	v_add_f32_e32 v115, v115, v119
	ds_bpermute_b32 v116, v124, v112
	ds_bpermute_b32 v117, v124, v113
	ds_bpermute_b32 v118, v124, v114
	ds_bpermute_b32 v119, v124, v115
	s_waitcnt lgkmcnt(0)
	v_add_f32_e32 v112, v112, v116
	v_add_f32_e32 v113, v113, v117
	v_add_f32_e32 v114, v114, v118
	v_add_f32_e32 v115, v115, v119
	ds_bpermute_b32 v116, v125, v112
	ds_bpermute_b32 v117, v125, v113
	ds_bpermute_b32 v118, v125, v114
	ds_bpermute_b32 v119, v125, v115
	s_waitcnt lgkmcnt(0)
	v_add_f32_e32 v112, v112, v116
	v_add_f32_e32 v113, v113, v117
	v_add_f32_e32 v114, v114, v118
	v_add_f32_e32 v115, v115, v119
	ds_bpermute_b32 v116, v126, v112
	ds_bpermute_b32 v117, v126, v113
	ds_bpermute_b32 v118, v126, v114
	ds_bpermute_b32 v119, v126, v115
	s_waitcnt lgkmcnt(0)
	v_add_f32_e32 v112, v112, v116
	v_add_f32_e32 v113, v113, v117
	v_add_f32_e32 v114, v114, v118
	v_add_f32_e32 v115, v115, v119
	ds_bpermute_b32 v116, v127, v112
	ds_bpermute_b32 v117, v127, v113
	ds_bpermute_b32 v118, v127, v114
	ds_bpermute_b32 v119, v127, v115
	s_waitcnt lgkmcnt(0)
	v_add_f32_e32 v112, v112, v116
	v_add_f32_e32 v113, v113, v117
	v_add_f32_e32 v114, v114, v118
	v_add_f32_e32 v115, v115, v119
	v_fmamk_f32 v112, v112, 0x3a800000, v208
	v_fmamk_f32 v113, v113, 0x3a800000, v208
	v_fmamk_f32 v114, v114, 0x3a800000, v208
	v_fmamk_f32 v115, v115, 0x3a800000, v208
	v_rsq_f32_e32 v112, v112
	v_rsq_f32_e32 v113, v113
	v_rsq_f32_e32 v114, v114
	v_rsq_f32_e32 v115, v115
	s_nop 1
	v_mul_f32_e32 v48, v48, v112
	v_mul_f32_e32 v49, v49, v112
	v_mul_f32_e32 v50, v50, v112
	v_mul_f32_e32 v51, v51, v112
	v_mul_f32_e32 v48, v0, v48
	v_mul_f32_e32 v49, v1, v49
	v_mul_f32_e32 v50, v2, v50
	v_mul_f32_e32 v51, v3, v51
	v_fma_f32 v48, v48, v16, v32
	v_fma_f32 v49, v49, v17, v33
	v_fma_f32 v50, v50, v18, v34
	v_fma_f32 v51, v51, v19, v35
	v_cvt_pk_bf16_f32 v128, v48, v49
	v_cvt_pk_bf16_f32 v129, v50, v51
	global_store_dwordx2 v121, v[128:129], s[4:5] offset:0
	v_mul_f32_e32 v52, v52, v112
	v_mul_f32_e32 v53, v53, v112
	v_mul_f32_e32 v54, v54, v112
	v_mul_f32_e32 v55, v55, v112
	v_mul_f32_e32 v52, v4, v52
	v_mul_f32_e32 v53, v5, v53
	v_mul_f32_e32 v54, v6, v54
	v_mul_f32_e32 v55, v7, v55
	v_fma_f32 v52, v52, v20, v36
	v_fma_f32 v53, v53, v21, v37
	v_fma_f32 v54, v54, v22, v38
	v_fma_f32 v55, v55, v23, v39
	v_cvt_pk_bf16_f32 v130, v52, v53
	v_cvt_pk_bf16_f32 v131, v54, v55
	global_store_dwordx2 v121, v[130:131], s[4:5] offset:512
	v_mul_f32_e32 v56, v56, v112
	v_mul_f32_e32 v57, v57, v112
	v_mul_f32_e32 v58, v58, v112
	v_mul_f32_e32 v59, v59, v112
	v_mul_f32_e32 v56, v8, v56
	v_mul_f32_e32 v57, v9, v57
	v_mul_f32_e32 v58, v10, v58
	v_mul_f32_e32 v59, v11, v59
	v_fma_f32 v56, v56, v24, v40
	v_fma_f32 v57, v57, v25, v41
	v_fma_f32 v58, v58, v26, v42
	v_fma_f32 v59, v59, v27, v43
	v_cvt_pk_bf16_f32 v128, v56, v57
	v_cvt_pk_bf16_f32 v129, v58, v59
	global_store_dwordx2 v121, v[128:129], s[4:5] offset:1024
	v_mul_f32_e32 v60, v60, v112
	v_mul_f32_e32 v61, v61, v112
	v_mul_f32_e32 v62, v62, v112
	v_mul_f32_e32 v63, v63, v112
	v_mul_f32_e32 v60, v12, v60
	v_mul_f32_e32 v61, v13, v61
	v_mul_f32_e32 v62, v14, v62
	v_mul_f32_e32 v63, v15, v63
	v_fma_f32 v60, v60, v28, v44
	v_fma_f32 v61, v61, v29, v45
	v_fma_f32 v62, v62, v30, v46
	v_fma_f32 v63, v63, v31, v47
	v_cvt_pk_bf16_f32 v130, v60, v61
	v_cvt_pk_bf16_f32 v131, v62, v63
	global_store_dwordx2 v121, v[130:131], s[4:5] offset:1536
	s_add_u32 s4, s4, 0x20000
	s_addc_u32 s5, s5, 0
	v_mul_f32_e32 v64, v64, v113
	v_mul_f32_e32 v65, v65, v113
	v_mul_f32_e32 v66, v66, v113
	v_mul_f32_e32 v67, v67, v113
	v_mul_f32_e32 v64, v0, v64
	v_mul_f32_e32 v65, v1, v65
	v_mul_f32_e32 v66, v2, v66
	v_mul_f32_e32 v67, v3, v67
	v_fma_f32 v64, v64, v16, v32
	v_fma_f32 v65, v65, v17, v33
	v_fma_f32 v66, v66, v18, v34
	v_fma_f32 v67, v67, v19, v35
	v_cvt_pk_bf16_f32 v128, v64, v65
	v_cvt_pk_bf16_f32 v129, v66, v67
	global_store_dwordx2 v121, v[128:129], s[4:5] offset:0
	v_mul_f32_e32 v68, v68, v113
	v_mul_f32_e32 v69, v69, v113
	v_mul_f32_e32 v70, v70, v113
	v_mul_f32_e32 v71, v71, v113
	v_mul_f32_e32 v68, v4, v68
	v_mul_f32_e32 v69, v5, v69
	v_mul_f32_e32 v70, v6, v70
	v_mul_f32_e32 v71, v7, v71
	v_fma_f32 v68, v68, v20, v36
	v_fma_f32 v69, v69, v21, v37
	v_fma_f32 v70, v70, v22, v38
	v_fma_f32 v71, v71, v23, v39
	v_cvt_pk_bf16_f32 v130, v68, v69
	v_cvt_pk_bf16_f32 v131, v70, v71
	global_store_dwordx2 v121, v[130:131], s[4:5] offset:512
	v_mul_f32_e32 v72, v72, v113
	v_mul_f32_e32 v73, v73, v113
	v_mul_f32_e32 v74, v74, v113
	v_mul_f32_e32 v75, v75, v113
	v_mul_f32_e32 v72, v8, v72
	v_mul_f32_e32 v73, v9, v73
	v_mul_f32_e32 v74, v10, v74
	v_mul_f32_e32 v75, v11, v75
	v_fma_f32 v72, v72, v24, v40
	v_fma_f32 v73, v73, v25, v41
	v_fma_f32 v74, v74, v26, v42
	v_fma_f32 v75, v75, v27, v43
	v_cvt_pk_bf16_f32 v128, v72, v73
	v_cvt_pk_bf16_f32 v129, v74, v75
	global_store_dwordx2 v121, v[128:129], s[4:5] offset:1024
	v_mul_f32_e32 v76, v76, v113
	v_mul_f32_e32 v77, v77, v113
	v_mul_f32_e32 v78, v78, v113
	v_mul_f32_e32 v79, v79, v113
	v_mul_f32_e32 v76, v12, v76
	v_mul_f32_e32 v77, v13, v77
	v_mul_f32_e32 v78, v14, v78
	v_mul_f32_e32 v79, v15, v79
	v_fma_f32 v76, v76, v28, v44
	v_fma_f32 v77, v77, v29, v45
	v_fma_f32 v78, v78, v30, v46
	v_fma_f32 v79, v79, v31, v47
	v_cvt_pk_bf16_f32 v130, v76, v77
	v_cvt_pk_bf16_f32 v131, v78, v79
	global_store_dwordx2 v121, v[130:131], s[4:5] offset:1536
	s_add_u32 s4, s4, 0x20000
	s_addc_u32 s5, s5, 0
	v_mul_f32_e32 v80, v80, v114
	v_mul_f32_e32 v81, v81, v114
	v_mul_f32_e32 v82, v82, v114
	v_mul_f32_e32 v83, v83, v114
	v_mul_f32_e32 v80, v0, v80
	v_mul_f32_e32 v81, v1, v81
	v_mul_f32_e32 v82, v2, v82
	v_mul_f32_e32 v83, v3, v83
	v_fma_f32 v80, v80, v16, v32
	v_fma_f32 v81, v81, v17, v33
	v_fma_f32 v82, v82, v18, v34
	v_fma_f32 v83, v83, v19, v35
	v_cvt_pk_bf16_f32 v128, v80, v81
	v_cvt_pk_bf16_f32 v129, v82, v83
	global_store_dwordx2 v121, v[128:129], s[4:5] offset:0
	v_mul_f32_e32 v84, v84, v114
	v_mul_f32_e32 v85, v85, v114
	v_mul_f32_e32 v86, v86, v114
	v_mul_f32_e32 v87, v87, v114
	v_mul_f32_e32 v84, v4, v84
	v_mul_f32_e32 v85, v5, v85
	v_mul_f32_e32 v86, v6, v86
	v_mul_f32_e32 v87, v7, v87
	v_fma_f32 v84, v84, v20, v36
	v_fma_f32 v85, v85, v21, v37
	v_fma_f32 v86, v86, v22, v38
	v_fma_f32 v87, v87, v23, v39
	v_cvt_pk_bf16_f32 v130, v84, v85
	v_cvt_pk_bf16_f32 v131, v86, v87
	global_store_dwordx2 v121, v[130:131], s[4:5] offset:512
	v_mul_f32_e32 v88, v88, v114
	v_mul_f32_e32 v89, v89, v114
	v_mul_f32_e32 v90, v90, v114
	v_mul_f32_e32 v91, v91, v114
	v_mul_f32_e32 v88, v8, v88
	v_mul_f32_e32 v89, v9, v89
	v_mul_f32_e32 v90, v10, v90
	v_mul_f32_e32 v91, v11, v91
	v_fma_f32 v88, v88, v24, v40
	v_fma_f32 v89, v89, v25, v41
	v_fma_f32 v90, v90, v26, v42
	v_fma_f32 v91, v91, v27, v43
	v_cvt_pk_bf16_f32 v128, v88, v89
	v_cvt_pk_bf16_f32 v129, v90, v91
	global_store_dwordx2 v121, v[128:129], s[4:5] offset:1024
	v_mul_f32_e32 v92, v92, v114
	v_mul_f32_e32 v93, v93, v114
	v_mul_f32_e32 v94, v94, v114
	v_mul_f32_e32 v95, v95, v114
	v_mul_f32_e32 v92, v12, v92
	v_mul_f32_e32 v93, v13, v93
	v_mul_f32_e32 v94, v14, v94
	v_mul_f32_e32 v95, v15, v95
	v_fma_f32 v92, v92, v28, v44
	v_fma_f32 v93, v93, v29, v45
	v_fma_f32 v94, v94, v30, v46
	v_fma_f32 v95, v95, v31, v47
	v_cvt_pk_bf16_f32 v130, v92, v93
	v_cvt_pk_bf16_f32 v131, v94, v95
	global_store_dwordx2 v121, v[130:131], s[4:5] offset:1536
	s_add_u32 s4, s4, 0x20000
	s_addc_u32 s5, s5, 0
	v_mul_f32_e32 v96, v96, v115
	v_mul_f32_e32 v97, v97, v115
	v_mul_f32_e32 v98, v98, v115
	v_mul_f32_e32 v99, v99, v115
	v_mul_f32_e32 v96, v0, v96
	v_mul_f32_e32 v97, v1, v97
	v_mul_f32_e32 v98, v2, v98
	v_mul_f32_e32 v99, v3, v99
	v_fma_f32 v96, v96, v16, v32
	v_fma_f32 v97, v97, v17, v33
	v_fma_f32 v98, v98, v18, v34
	v_fma_f32 v99, v99, v19, v35
	v_cvt_pk_bf16_f32 v128, v96, v97
	v_cvt_pk_bf16_f32 v129, v98, v99
	global_store_dwordx2 v121, v[128:129], s[4:5] offset:0
	v_mul_f32_e32 v100, v100, v115
	v_mul_f32_e32 v101, v101, v115
	v_mul_f32_e32 v102, v102, v115
	v_mul_f32_e32 v103, v103, v115
	v_mul_f32_e32 v100, v4, v100
	v_mul_f32_e32 v101, v5, v101
	v_mul_f32_e32 v102, v6, v102
	v_mul_f32_e32 v103, v7, v103
	v_fma_f32 v100, v100, v20, v36
	v_fma_f32 v101, v101, v21, v37
	v_fma_f32 v102, v102, v22, v38
	v_fma_f32 v103, v103, v23, v39
	v_cvt_pk_bf16_f32 v130, v100, v101
	v_cvt_pk_bf16_f32 v131, v102, v103
	global_store_dwordx2 v121, v[130:131], s[4:5] offset:512
	v_mul_f32_e32 v104, v104, v115
	v_mul_f32_e32 v105, v105, v115
	v_mul_f32_e32 v106, v106, v115
	v_mul_f32_e32 v107, v107, v115
	v_mul_f32_e32 v104, v8, v104
	v_mul_f32_e32 v105, v9, v105
	v_mul_f32_e32 v106, v10, v106
	v_mul_f32_e32 v107, v11, v107
	v_fma_f32 v104, v104, v24, v40
	v_fma_f32 v105, v105, v25, v41
	v_fma_f32 v106, v106, v26, v42
	v_fma_f32 v107, v107, v27, v43
	v_cvt_pk_bf16_f32 v128, v104, v105
	v_cvt_pk_bf16_f32 v129, v106, v107
	global_store_dwordx2 v121, v[128:129], s[4:5] offset:1024
	v_mul_f32_e32 v108, v108, v115
	v_mul_f32_e32 v109, v109, v115
	v_mul_f32_e32 v110, v110, v115
	v_mul_f32_e32 v111, v111, v115
	v_mul_f32_e32 v108, v12, v108
	v_mul_f32_e32 v109, v13, v109
	v_mul_f32_e32 v110, v14, v110
	v_mul_f32_e32 v111, v15, v111
	v_fma_f32 v108, v108, v28, v44
	v_fma_f32 v109, v109, v29, v45
	v_fma_f32 v110, v110, v30, v46
	v_fma_f32 v111, v111, v31, v47
	v_cvt_pk_bf16_f32 v130, v108, v109
	v_cvt_pk_bf16_f32 v131, v110, v111
	global_store_dwordx2 v121, v[130:131], s[4:5] offset:1536
	s_add_u32 s4, s4, 0x20000
	s_addc_u32 s5, s5, 0
	s_sub_u32 s2, s2, 1
	s_cmp_lg_u32 s2, 0
	s_cbranch_scc1 .Lrms_sub0_loop
	s_waitcnt vmcnt(28)
	v_mul_f32_e32 v112, v132, v132
	v_fmac_f32_e32 v112, v133, v133
	v_fmac_f32_e32 v112, v134, v134
	v_fmac_f32_e32 v112, v135, v135
	v_fmac_f32_e32 v112, v136, v136
	v_fmac_f32_e32 v112, v137, v137
	v_fmac_f32_e32 v112, v138, v138
	v_fmac_f32_e32 v112, v139, v139
	v_fmac_f32_e32 v112, v140, v140
	v_fmac_f32_e32 v112, v141, v141
	v_fmac_f32_e32 v112, v142, v142
	v_fmac_f32_e32 v112, v143, v143
	v_fmac_f32_e32 v112, v144, v144
	v_fmac_f32_e32 v112, v145, v145
	v_fmac_f32_e32 v112, v146, v146
	v_fmac_f32_e32 v112, v147, v147
	s_waitcnt vmcnt(24)
	v_mul_f32_e32 v113, v166, v166
	v_fmac_f32_e32 v113, v167, v167
	v_fmac_f32_e32 v113, v168, v168
	v_fmac_f32_e32 v113, v169, v169
	v_fmac_f32_e32 v113, v170, v170
	v_fmac_f32_e32 v113, v171, v171
	v_fmac_f32_e32 v113, v172, v172
	v_fmac_f32_e32 v113, v173, v173
	v_fmac_f32_e32 v113, v174, v174
	v_fmac_f32_e32 v113, v175, v175
	v_fmac_f32_e32 v113, v176, v176
	v_fmac_f32_e32 v113, v177, v177
	v_fmac_f32_e32 v113, v178, v178
	v_fmac_f32_e32 v113, v179, v179
	v_fmac_f32_e32 v113, v180, v180
	v_fmac_f32_e32 v113, v181, v181
	s_waitcnt vmcnt(20)
	v_mul_f32_e32 v114, v182, v182
	v_fmac_f32_e32 v114, v183, v183
	v_fmac_f32_e32 v114, v184, v184
	v_fmac_f32_e32 v114, v185, v185
	v_fmac_f32_e32 v114, v186, v186
	v_fmac_f32_e32 v114, v187, v187
	v_fmac_f32_e32 v114, v188, v188
	v_fmac_f32_e32 v114, v189, v189
	v_fmac_f32_e32 v114, v190, v190
	v_fmac_f32_e32 v114, v191, v191
	v_fmac_f32_e32 v114, v192, v192
	v_fmac_f32_e32 v114, v193, v193
	v_fmac_f32_e32 v114, v194, v194
	v_fmac_f32_e32 v114, v195, v195
	v_fmac_f32_e32 v114, v196, v196
	v_fmac_f32_e32 v114, v197, v197
	s_waitcnt vmcnt(16)
	v_mul_f32_e32 v115, v228, v228
	v_fmac_f32_e32 v115, v229, v229
	v_fmac_f32_e32 v115, v230, v230
	v_fmac_f32_e32 v115, v231, v231
	v_fmac_f32_e32 v115, v232, v232
	v_fmac_f32_e32 v115, v233, v233
	v_fmac_f32_e32 v115, v234, v234
	v_fmac_f32_e32 v115, v235, v235
	v_fmac_f32_e32 v115, v236, v236
	v_fmac_f32_e32 v115, v237, v237
	v_fmac_f32_e32 v115, v238, v238
	v_fmac_f32_e32 v115, v239, v239
	v_fmac_f32_e32 v115, v240, v240
	v_fmac_f32_e32 v115, v241, v241
	v_fmac_f32_e32 v115, v242, v242
	v_fmac_f32_e32 v115, v243, v243
	ds_bpermute_b32 v116, v122, v112
	ds_bpermute_b32 v117, v122, v113
	ds_bpermute_b32 v118, v122, v114
	ds_bpermute_b32 v119, v122, v115
	s_waitcnt lgkmcnt(0)
	v_add_f32_e32 v112, v112, v116
	v_add_f32_e32 v113, v113, v117
	v_add_f32_e32 v114, v114, v118
	v_add_f32_e32 v115, v115, v119
	ds_bpermute_b32 v116, v123, v112
	ds_bpermute_b32 v117, v123, v113
	ds_bpermute_b32 v118, v123, v114
	ds_bpermute_b32 v119, v123, v115
	s_waitcnt lgkmcnt(0)
	v_add_f32_e32 v112, v112, v116
	v_add_f32_e32 v113, v113, v117
	v_add_f32_e32 v114, v114, v118
	v_add_f32_e32 v115, v115, v119
	ds_bpermute_b32 v116, v124, v112
	ds_bpermute_b32 v117, v124, v113
	ds_bpermute_b32 v118, v124, v114
	ds_bpermute_b32 v119, v124, v115
	s_waitcnt lgkmcnt(0)
	v_add_f32_e32 v112, v112, v116
	v_add_f32_e32 v113, v113, v117
	v_add_f32_e32 v114, v114, v118
	v_add_f32_e32 v115, v115, v119
	ds_bpermute_b32 v116, v125, v112
	ds_bpermute_b32 v117, v125, v113
	ds_bpermute_b32 v118, v125, v114
	ds_bpermute_b32 v119, v125, v115
	s_waitcnt lgkmcnt(0)
	v_add_f32_e32 v112, v112, v116
	v_add_f32_e32 v113, v113, v117
	v_add_f32_e32 v114, v114, v118
	v_add_f32_e32 v115, v115, v119
	ds_bpermute_b32 v116, v126, v112
	ds_bpermute_b32 v117, v126, v113
	ds_bpermute_b32 v118, v126, v114
	ds_bpermute_b32 v119, v126, v115
	s_waitcnt lgkmcnt(0)
	v_add_f32_e32 v112, v112, v116
	v_add_f32_e32 v113, v113, v117
	v_add_f32_e32 v114, v114, v118
	v_add_f32_e32 v115, v115, v119
	ds_bpermute_b32 v116, v127, v112
	ds_bpermute_b32 v117, v127, v113
	ds_bpermute_b32 v118, v127, v114
	ds_bpermute_b32 v119, v127, v115
	s_waitcnt lgkmcnt(0)
	v_add_f32_e32 v112, v112, v116
	v_add_f32_e32 v113, v113, v117
	v_add_f32_e32 v114, v114, v118
	v_add_f32_e32 v115, v115, v119
	v_fmamk_f32 v112, v112, 0x3a800000, v208
	v_fmamk_f32 v113, v113, 0x3a800000, v208
	v_fmamk_f32 v114, v114, 0x3a800000, v208
	v_fmamk_f32 v115, v115, 0x3a800000, v208
	v_rsq_f32_e32 v112, v112
	v_rsq_f32_e32 v113, v113
	v_rsq_f32_e32 v114, v114
	v_rsq_f32_e32 v115, v115
	s_nop 1
	v_mul_f32_e32 v132, v132, v112
	v_mul_f32_e32 v133, v133, v112
	v_mul_f32_e32 v134, v134, v112
	v_mul_f32_e32 v135, v135, v112
	v_mul_f32_e32 v132, v0, v132
	v_mul_f32_e32 v133, v1, v133
	v_mul_f32_e32 v134, v2, v134
	v_mul_f32_e32 v135, v3, v135
	v_fma_f32 v132, v132, v16, v32
	v_fma_f32 v133, v133, v17, v33
	v_fma_f32 v134, v134, v18, v34
	v_fma_f32 v135, v135, v19, v35
	v_cvt_pk_bf16_f32 v128, v132, v133
	v_cvt_pk_bf16_f32 v129, v134, v135
	global_store_dwordx2 v121, v[128:129], s[4:5] offset:0
	v_mul_f32_e32 v136, v136, v112
	v_mul_f32_e32 v137, v137, v112
	v_mul_f32_e32 v138, v138, v112
	v_mul_f32_e32 v139, v139, v112
	v_mul_f32_e32 v136, v4, v136
	v_mul_f32_e32 v137, v5, v137
	v_mul_f32_e32 v138, v6, v138
	v_mul_f32_e32 v139, v7, v139
	v_fma_f32 v136, v136, v20, v36
	v_fma_f32 v137, v137, v21, v37
	v_fma_f32 v138, v138, v22, v38
	v_fma_f32 v139, v139, v23, v39
	v_cvt_pk_bf16_f32 v130, v136, v137
	v_cvt_pk_bf16_f32 v131, v138, v139
	global_store_dwordx2 v121, v[130:131], s[4:5] offset:512
	v_mul_f32_e32 v140, v140, v112
	v_mul_f32_e32 v141, v141, v112
	v_mul_f32_e32 v142, v142, v112
	v_mul_f32_e32 v143, v143, v112
	v_mul_f32_e32 v140, v8, v140
	v_mul_f32_e32 v141, v9, v141
	v_mul_f32_e32 v142, v10, v142
	v_mul_f32_e32 v143, v11, v143
	v_fma_f32 v140, v140, v24, v40
	v_fma_f32 v141, v141, v25, v41
	v_fma_f32 v142, v142, v26, v42
	v_fma_f32 v143, v143, v27, v43
	v_cvt_pk_bf16_f32 v128, v140, v141
	v_cvt_pk_bf16_f32 v129, v142, v143
	global_store_dwordx2 v121, v[128:129], s[4:5] offset:1024
	v_mul_f32_e32 v144, v144, v112
	v_mul_f32_e32 v145, v145, v112
	v_mul_f32_e32 v146, v146, v112
	v_mul_f32_e32 v147, v147, v112
	v_mul_f32_e32 v144, v12, v144
	v_mul_f32_e32 v145, v13, v145
	v_mul_f32_e32 v146, v14, v146
	v_mul_f32_e32 v147, v15, v147
	v_fma_f32 v144, v144, v28, v44
	v_fma_f32 v145, v145, v29, v45
	v_fma_f32 v146, v146, v30, v46
	v_fma_f32 v147, v147, v31, v47
	v_cvt_pk_bf16_f32 v130, v144, v145
	v_cvt_pk_bf16_f32 v131, v146, v147
	global_store_dwordx2 v121, v[130:131], s[4:5] offset:1536
	s_add_u32 s4, s4, 0x20000
	s_addc_u32 s5, s5, 0
	v_mul_f32_e32 v166, v166, v113
	v_mul_f32_e32 v167, v167, v113
	v_mul_f32_e32 v168, v168, v113
	v_mul_f32_e32 v169, v169, v113
	v_mul_f32_e32 v166, v0, v166
	v_mul_f32_e32 v167, v1, v167
	v_mul_f32_e32 v168, v2, v168
	v_mul_f32_e32 v169, v3, v169
	v_fma_f32 v166, v166, v16, v32
	v_fma_f32 v167, v167, v17, v33
	v_fma_f32 v168, v168, v18, v34
	v_fma_f32 v169, v169, v19, v35
	v_cvt_pk_bf16_f32 v128, v166, v167
	v_cvt_pk_bf16_f32 v129, v168, v169
	global_store_dwordx2 v121, v[128:129], s[4:5] offset:0
	v_mul_f32_e32 v170, v170, v113
	v_mul_f32_e32 v171, v171, v113
	v_mul_f32_e32 v172, v172, v113
	v_mul_f32_e32 v173, v173, v113
	v_mul_f32_e32 v170, v4, v170
	v_mul_f32_e32 v171, v5, v171
	v_mul_f32_e32 v172, v6, v172
	v_mul_f32_e32 v173, v7, v173
	v_fma_f32 v170, v170, v20, v36
	v_fma_f32 v171, v171, v21, v37
	v_fma_f32 v172, v172, v22, v38
	v_fma_f32 v173, v173, v23, v39
	v_cvt_pk_bf16_f32 v130, v170, v171
	v_cvt_pk_bf16_f32 v131, v172, v173
	global_store_dwordx2 v121, v[130:131], s[4:5] offset:512
	v_mul_f32_e32 v174, v174, v113
	v_mul_f32_e32 v175, v175, v113
	v_mul_f32_e32 v176, v176, v113
	v_mul_f32_e32 v177, v177, v113
	v_mul_f32_e32 v174, v8, v174
	v_mul_f32_e32 v175, v9, v175
	v_mul_f32_e32 v176, v10, v176
	v_mul_f32_e32 v177, v11, v177
	v_fma_f32 v174, v174, v24, v40
	v_fma_f32 v175, v175, v25, v41
	v_fma_f32 v176, v176, v26, v42
	v_fma_f32 v177, v177, v27, v43
	v_cvt_pk_bf16_f32 v128, v174, v175
	v_cvt_pk_bf16_f32 v129, v176, v177
	global_store_dwordx2 v121, v[128:129], s[4:5] offset:1024
	v_mul_f32_e32 v178, v178, v113
	v_mul_f32_e32 v179, v179, v113
	v_mul_f32_e32 v180, v180, v113
	v_mul_f32_e32 v181, v181, v113
	v_mul_f32_e32 v178, v12, v178
	v_mul_f32_e32 v179, v13, v179
	v_mul_f32_e32 v180, v14, v180
	v_mul_f32_e32 v181, v15, v181
	v_fma_f32 v178, v178, v28, v44
	v_fma_f32 v179, v179, v29, v45
	v_fma_f32 v180, v180, v30, v46
	v_fma_f32 v181, v181, v31, v47
	v_cvt_pk_bf16_f32 v130, v178, v179
	v_cvt_pk_bf16_f32 v131, v180, v181
	global_store_dwordx2 v121, v[130:131], s[4:5] offset:1536
	s_add_u32 s4, s4, 0x20000
	s_addc_u32 s5, s5, 0
	v_mul_f32_e32 v182, v182, v114
	v_mul_f32_e32 v183, v183, v114
	v_mul_f32_e32 v184, v184, v114
	v_mul_f32_e32 v185, v185, v114
	v_mul_f32_e32 v182, v0, v182
	v_mul_f32_e32 v183, v1, v183
	v_mul_f32_e32 v184, v2, v184
	v_mul_f32_e32 v185, v3, v185
	v_fma_f32 v182, v182, v16, v32
	v_fma_f32 v183, v183, v17, v33
	v_fma_f32 v184, v184, v18, v34
	v_fma_f32 v185, v185, v19, v35
	v_cvt_pk_bf16_f32 v128, v182, v183
	v_cvt_pk_bf16_f32 v129, v184, v185
	global_store_dwordx2 v121, v[128:129], s[4:5] offset:0
	v_mul_f32_e32 v186, v186, v114
	v_mul_f32_e32 v187, v187, v114
	v_mul_f32_e32 v188, v188, v114
	v_mul_f32_e32 v189, v189, v114
	v_mul_f32_e32 v186, v4, v186
	v_mul_f32_e32 v187, v5, v187
	v_mul_f32_e32 v188, v6, v188
	v_mul_f32_e32 v189, v7, v189
	v_fma_f32 v186, v186, v20, v36
	v_fma_f32 v187, v187, v21, v37
	v_fma_f32 v188, v188, v22, v38
	v_fma_f32 v189, v189, v23, v39
	v_cvt_pk_bf16_f32 v130, v186, v187
	v_cvt_pk_bf16_f32 v131, v188, v189
	global_store_dwordx2 v121, v[130:131], s[4:5] offset:512
	v_mul_f32_e32 v190, v190, v114
	v_mul_f32_e32 v191, v191, v114
	v_mul_f32_e32 v192, v192, v114
	v_mul_f32_e32 v193, v193, v114
	v_mul_f32_e32 v190, v8, v190
	v_mul_f32_e32 v191, v9, v191
	v_mul_f32_e32 v192, v10, v192
	v_mul_f32_e32 v193, v11, v193
	v_fma_f32 v190, v190, v24, v40
	v_fma_f32 v191, v191, v25, v41
	v_fma_f32 v192, v192, v26, v42
	v_fma_f32 v193, v193, v27, v43
	v_cvt_pk_bf16_f32 v128, v190, v191
	v_cvt_pk_bf16_f32 v129, v192, v193
	global_store_dwordx2 v121, v[128:129], s[4:5] offset:1024
	v_mul_f32_e32 v194, v194, v114
	v_mul_f32_e32 v195, v195, v114
	v_mul_f32_e32 v196, v196, v114
	v_mul_f32_e32 v197, v197, v114
	v_mul_f32_e32 v194, v12, v194
	v_mul_f32_e32 v195, v13, v195
	v_mul_f32_e32 v196, v14, v196
	v_mul_f32_e32 v197, v15, v197
	v_fma_f32 v194, v194, v28, v44
	v_fma_f32 v195, v195, v29, v45
	v_fma_f32 v196, v196, v30, v46
	v_fma_f32 v197, v197, v31, v47
	v_cvt_pk_bf16_f32 v130, v194, v195
	v_cvt_pk_bf16_f32 v131, v196, v197
	global_store_dwordx2 v121, v[130:131], s[4:5] offset:1536
	s_add_u32 s4, s4, 0x20000
	s_addc_u32 s5, s5, 0
	v_mul_f32_e32 v228, v228, v115
	v_mul_f32_e32 v229, v229, v115
	v_mul_f32_e32 v230, v230, v115
	v_mul_f32_e32 v231, v231, v115
	v_mul_f32_e32 v228, v0, v228
	v_mul_f32_e32 v229, v1, v229
	v_mul_f32_e32 v230, v2, v230
	v_mul_f32_e32 v231, v3, v231
	v_fma_f32 v228, v228, v16, v32
	v_fma_f32 v229, v229, v17, v33
	v_fma_f32 v230, v230, v18, v34
	v_fma_f32 v231, v231, v19, v35
	v_cvt_pk_bf16_f32 v128, v228, v229
	v_cvt_pk_bf16_f32 v129, v230, v231
	global_store_dwordx2 v121, v[128:129], s[4:5] offset:0
	v_mul_f32_e32 v232, v232, v115
	v_mul_f32_e32 v233, v233, v115
	v_mul_f32_e32 v234, v234, v115
	v_mul_f32_e32 v235, v235, v115
	v_mul_f32_e32 v232, v4, v232
	v_mul_f32_e32 v233, v5, v233
	v_mul_f32_e32 v234, v6, v234
	v_mul_f32_e32 v235, v7, v235
	v_fma_f32 v232, v232, v20, v36
	v_fma_f32 v233, v233, v21, v37
	v_fma_f32 v234, v234, v22, v38
	v_fma_f32 v235, v235, v23, v39
	v_cvt_pk_bf16_f32 v130, v232, v233
	v_cvt_pk_bf16_f32 v131, v234, v235
	global_store_dwordx2 v121, v[130:131], s[4:5] offset:512
	v_mul_f32_e32 v236, v236, v115
	v_mul_f32_e32 v237, v237, v115
	v_mul_f32_e32 v238, v238, v115
	v_mul_f32_e32 v239, v239, v115
	v_mul_f32_e32 v236, v8, v236
	v_mul_f32_e32 v237, v9, v237
	v_mul_f32_e32 v238, v10, v238
	v_mul_f32_e32 v239, v11, v239
	v_fma_f32 v236, v236, v24, v40
	v_fma_f32 v237, v237, v25, v41
	v_fma_f32 v238, v238, v26, v42
	v_fma_f32 v239, v239, v27, v43
	v_cvt_pk_bf16_f32 v128, v236, v237
	v_cvt_pk_bf16_f32 v129, v238, v239
	global_store_dwordx2 v121, v[128:129], s[4:5] offset:1024
	v_mul_f32_e32 v240, v240, v115
	v_mul_f32_e32 v241, v241, v115
	v_mul_f32_e32 v242, v242, v115
	v_mul_f32_e32 v243, v243, v115
	v_mul_f32_e32 v240, v12, v240
	v_mul_f32_e32 v241, v13, v241
	v_mul_f32_e32 v242, v14, v242
	v_mul_f32_e32 v243, v15, v243
	v_fma_f32 v240, v240, v28, v44
	v_fma_f32 v241, v241, v29, v45
	v_fma_f32 v242, v242, v30, v46
	v_fma_f32 v243, v243, v31, v47
	v_cvt_pk_bf16_f32 v130, v240, v241
	v_cvt_pk_bf16_f32 v131, v242, v243
	global_store_dwordx2 v121, v[130:131], s[4:5] offset:1536
	s_add_u32 s4, s4, 0x20000
	s_addc_u32 s5, s5, 0
